# GEMM K loops: LDS-DMA pieces issued in scalar-base form (vOff, s[base]); the per-piece v_lshl_add_u64 address builds removed (188 of 256)
# speedup vs baseline: 1.0072x; 1.0072x over previous
.LBB0_289:
	ds_read_b128 v[170:173], v167
	ds_read_b128 v[174:177], v167 offset:1024
	ds_read_b128 v[178:181], v167 offset:2048
	ds_read_b128 v[182:185], v167 offset:3072
	ds_read_b128 v[186:189], v168
	ds_read_b128 v[190:193], v168 offset:1024
	ds_read_b128 v[194:197], v168 offset:2048
	ds_read_b128 v[198:201], v168 offset:3072
	s_add_u32 s26, s24, 0xfffc0080
	s_addc_u32 s27, s25, -1
	s_cmp_eq_u32 s54, 12
	s_cselect_b32 s29, s13, s27
	s_cselect_b32 s28, s50, s26
	s_cselect_b32 s27, s15, s53
	s_cselect_b32 s26, s51, s52
	s_add_i32 m0, s21, 0xc000
	ds_read_b128 v[210:213], v169
	ds_read_b128 v[214:217], v169 offset:1024
	ds_read_b128 v[218:221], v169 offset:2048
	ds_read_b128 v[222:225], v169 offset:3072
	ds_read_b128 v[226:229], v169 offset:4096
	ds_read_b128 v[230:233], v169 offset:5120
	ds_read_b128 v[234:237], v169 offset:6144
	ds_read_b128 v[238:241], v169 offset:7168
	global_load_lds_dwordx4 v158, s[24:25]
	s_add_i32 m0, s21, 0xe000
	s_nop 0
	global_load_lds_dwordx4 v156, s[24:25]
	s_waitcnt vmcnt(8)
	s_waitcnt lgkmcnt(0)
	s_barrier
	s_setprio 1
	s_waitcnt lgkmcnt(0)
	v_mfma_f32_16x16x32_bf16 v[124:127], v[170:173], v[210:213], v[124:127]
	v_mfma_f32_16x16x32_bf16 v[116:119], v[178:181], v[210:213], v[116:119]
	v_mfma_f32_16x16x32_bf16 v[108:111], v[170:173], v[218:221], v[108:111]
	v_mfma_f32_16x16x32_bf16 v[100:103], v[178:181], v[218:221], v[100:103]
	v_mfma_f32_16x16x32_bf16 v[92:95], v[170:173], v[226:229], v[92:95]
	v_mfma_f32_16x16x32_bf16 v[84:87], v[178:181], v[226:229], v[84:87]
	v_mfma_f32_16x16x32_bf16 v[76:79], v[170:173], v[234:237], v[76:79]
	v_mfma_f32_16x16x32_bf16 v[68:71], v[178:181], v[234:237], v[68:71]
	v_mfma_f32_16x16x32_bf16 v[124:127], v[174:177], v[214:217], v[124:127]
	v_mfma_f32_16x16x32_bf16 v[116:119], v[182:185], v[214:217], v[116:119]
	v_mfma_f32_16x16x32_bf16 v[108:111], v[174:177], v[222:225], v[108:111]
	v_mfma_f32_16x16x32_bf16 v[100:103], v[182:185], v[222:225], v[100:103]
	v_mfma_f32_16x16x32_bf16 v[92:95], v[174:177], v[230:233], v[92:95]
	v_mfma_f32_16x16x32_bf16 v[84:87], v[182:185], v[230:233], v[84:87]
	v_mfma_f32_16x16x32_bf16 v[76:79], v[174:177], v[238:241], v[76:79]
	v_mfma_f32_16x16x32_bf16 v[68:71], v[182:185], v[238:241], v[68:71]
	s_setprio 0
	s_setprio 1
	v_mfma_f32_16x16x32_bf16 v[120:123], v[186:189], v[210:213], v[120:123]
	v_mfma_f32_16x16x32_bf16 v[112:115], v[194:197], v[210:213], v[112:115]
	v_mfma_f32_16x16x32_bf16 v[104:107], v[186:189], v[218:221], v[104:107]
	v_mfma_f32_16x16x32_bf16 v[96:99], v[194:197], v[218:221], v[96:99]
	v_mfma_f32_16x16x32_bf16 v[88:91], v[186:189], v[226:229], v[88:91]
	v_mfma_f32_16x16x32_bf16 v[80:83], v[194:197], v[226:229], v[80:83]
	v_mfma_f32_16x16x32_bf16 v[72:75], v[186:189], v[234:237], v[72:75]
	v_mfma_f32_16x16x32_bf16 v[64:67], v[194:197], v[234:237], v[64:67]
	v_mfma_f32_16x16x32_bf16 v[120:123], v[190:193], v[214:217], v[120:123]
	v_mfma_f32_16x16x32_bf16 v[112:115], v[198:201], v[214:217], v[112:115]
	v_mfma_f32_16x16x32_bf16 v[104:107], v[190:193], v[222:225], v[104:107]
	v_mfma_f32_16x16x32_bf16 v[96:99], v[198:201], v[222:225], v[96:99]
	v_mfma_f32_16x16x32_bf16 v[88:91], v[190:193], v[230:233], v[88:91]
	v_mfma_f32_16x16x32_bf16 v[80:83], v[198:201], v[230:233], v[80:83]
	v_mfma_f32_16x16x32_bf16 v[72:75], v[190:193], v[238:241], v[72:75]
	v_mfma_f32_16x16x32_bf16 v[64:67], v[198:201], v[238:241], v[64:67]
	s_setprio 0
	s_barrier
	s_add_i32 s55, s48, s38
	s_mov_b32 m0, s55
	ds_read_b128 v[210:213], v169 offset:16384
	ds_read_b128 v[214:217], v169 offset:17408
	ds_read_b128 v[218:221], v169 offset:18432
	ds_read_b128 v[222:225], v169 offset:19456
	ds_read_b128 v[226:229], v169 offset:20480
	ds_read_b128 v[230:233], v169 offset:21504
	ds_read_b128 v[234:237], v169 offset:22528
	ds_read_b128 v[238:241], v169 offset:23552
	global_load_lds_dwordx4 v134, s[26:27]
	s_add_i32 m0, s55, 0x2000
	s_add_u32 s56, s26, 0x4000
	s_addc_u32 s57, s27, 0
	s_add_i32 s55, s49, s38
	global_load_lds_dwordx4 v130, s[26:27]
	s_mov_b32 m0, s55
	v_lshl_add_u64 v[242:243], s[28:29], 0, v[132:133]
	global_load_lds_dwordx4 v134, s[56:57]
	s_add_i32 m0, s55, 0x2000
	s_nop 0
	global_load_lds_dwordx4 v130, s[56:57]
	v_lshl_add_u64 v[164:165], s[28:29], 0, v[136:137]
	s_mov_b32 m0, s21
	s_nop 0
	global_load_lds_dwordx4 v[164:165], off
	s_mov_b32 m0, s23
	s_nop 0
	global_load_lds_dwordx4 v[242:243], off
	s_waitcnt vmcnt(8)
	s_waitcnt lgkmcnt(0)
	s_barrier
	s_setprio 1
	s_waitcnt lgkmcnt(0)
	v_mfma_f32_16x16x32_bf16 v[60:63], v[170:173], v[210:213], v[60:63]
	v_mfma_f32_16x16x32_bf16 v[52:55], v[178:181], v[210:213], v[52:55]
	v_mfma_f32_16x16x32_bf16 v[44:47], v[170:173], v[218:221], v[44:47]
	v_mfma_f32_16x16x32_bf16 v[36:39], v[178:181], v[218:221], v[36:39]
	v_mfma_f32_16x16x32_bf16 v[28:31], v[170:173], v[226:229], v[28:31]
	v_mfma_f32_16x16x32_bf16 v[20:23], v[178:181], v[226:229], v[20:23]
	v_mfma_f32_16x16x32_bf16 v[12:15], v[170:173], v[234:237], v[12:15]
	v_mfma_f32_16x16x32_bf16 v[4:7], v[178:181], v[234:237], v[4:7]
	v_mfma_f32_16x16x32_bf16 v[60:63], v[174:177], v[214:217], v[60:63]
	v_mfma_f32_16x16x32_bf16 v[52:55], v[182:185], v[214:217], v[52:55]
	v_mfma_f32_16x16x32_bf16 v[44:47], v[174:177], v[222:225], v[44:47]
	v_mfma_f32_16x16x32_bf16 v[36:39], v[182:185], v[222:225], v[36:39]
	v_mfma_f32_16x16x32_bf16 v[28:31], v[174:177], v[230:233], v[28:31]
	v_mfma_f32_16x16x32_bf16 v[20:23], v[182:185], v[230:233], v[20:23]
	v_mfma_f32_16x16x32_bf16 v[12:15], v[174:177], v[238:241], v[12:15]
	v_mfma_f32_16x16x32_bf16 v[4:7], v[182:185], v[238:241], v[4:7]
	s_setprio 0
	s_setprio 1
	v_mfma_f32_16x16x32_bf16 v[56:59], v[186:189], v[210:213], v[56:59]
	v_mfma_f32_16x16x32_bf16 v[48:51], v[194:197], v[210:213], v[48:51]
	v_mfma_f32_16x16x32_bf16 v[40:43], v[186:189], v[218:221], v[40:43]
	v_mfma_f32_16x16x32_bf16 v[32:35], v[194:197], v[218:221], v[32:35]
	v_mfma_f32_16x16x32_bf16 v[24:27], v[186:189], v[226:229], v[24:27]
	v_mfma_f32_16x16x32_bf16 v[16:19], v[194:197], v[226:229], v[16:19]
	v_mfma_f32_16x16x32_bf16 v[8:11], v[186:189], v[234:237], v[8:11]
	v_mfma_f32_16x16x32_bf16 v[0:3], v[194:197], v[234:237], v[0:3]
	v_mfma_f32_16x16x32_bf16 v[56:59], v[190:193], v[214:217], v[56:59]
	v_mfma_f32_16x16x32_bf16 v[48:51], v[198:201], v[214:217], v[48:51]
	v_mfma_f32_16x16x32_bf16 v[40:43], v[190:193], v[222:225], v[40:43]
	v_mfma_f32_16x16x32_bf16 v[32:35], v[198:201], v[222:225], v[32:35]
	v_mfma_f32_16x16x32_bf16 v[24:27], v[190:193], v[230:233], v[24:27]
	v_mfma_f32_16x16x32_bf16 v[16:19], v[198:201], v[230:233], v[16:19]
	v_mfma_f32_16x16x32_bf16 v[8:11], v[190:193], v[238:241], v[8:11]
	v_mfma_f32_16x16x32_bf16 v[0:3], v[198:201], v[238:241], v[0:3]
	s_setprio 0
	s_barrier
	s_add_i32 s55, 0, 0x18000
	s_add_i32 s56, 0, 0x1c000
	v_add_u32_e32 v182, s55, v129
	v_add_u32_e32 v198, s56, v129
	ds_read_b128 v[170:173], v182
	ds_read_b128 v[174:177], v182 offset:1024
	ds_read_b128 v[178:181], v182 offset:2048
	ds_read_b128 v[182:185], v182 offset:3072
	ds_read_b128 v[186:189], v198
	ds_read_b128 v[190:193], v198 offset:1024
	ds_read_b128 v[194:197], v198 offset:2048
	ds_read_b128 v[198:201], v198 offset:3072
	s_add_u32 s28, s28, 0x40000
	s_addc_u32 s29, s29, 0
	s_mov_b32 m0, s41
	ds_read_b128 v[210:213], v169 offset:32768
	ds_read_b128 v[214:217], v169 offset:33792
	ds_read_b128 v[218:221], v169 offset:34816
	ds_read_b128 v[222:225], v169 offset:35840
	ds_read_b128 v[226:229], v169 offset:36864
	ds_read_b128 v[230:233], v169 offset:37888
	ds_read_b128 v[234:237], v169 offset:38912
	ds_read_b128 v[238:241], v169 offset:39936
	global_load_lds_dwordx4 v136, s[28:29]
	s_mov_b32 m0, s42
	s_nop 0
	global_load_lds_dwordx4 v132, s[28:29]
	s_waitcnt vmcnt(8)
	s_waitcnt lgkmcnt(0)
	s_barrier
	s_setprio 1
	s_waitcnt lgkmcnt(0)
	v_mfma_f32_16x16x32_bf16 v[124:127], v[170:173], v[210:213], v[124:127]
	v_mfma_f32_16x16x32_bf16 v[116:119], v[178:181], v[210:213], v[116:119]
	v_mfma_f32_16x16x32_bf16 v[108:111], v[170:173], v[218:221], v[108:111]
	v_mfma_f32_16x16x32_bf16 v[100:103], v[178:181], v[218:221], v[100:103]
	v_mfma_f32_16x16x32_bf16 v[92:95], v[170:173], v[226:229], v[92:95]
	v_mfma_f32_16x16x32_bf16 v[84:87], v[178:181], v[226:229], v[84:87]
	v_mfma_f32_16x16x32_bf16 v[76:79], v[170:173], v[234:237], v[76:79]
	v_mfma_f32_16x16x32_bf16 v[68:71], v[178:181], v[234:237], v[68:71]
	v_mfma_f32_16x16x32_bf16 v[124:127], v[174:177], v[214:217], v[124:127]
	v_mfma_f32_16x16x32_bf16 v[116:119], v[182:185], v[214:217], v[116:119]
	v_mfma_f32_16x16x32_bf16 v[108:111], v[174:177], v[222:225], v[108:111]
	v_mfma_f32_16x16x32_bf16 v[100:103], v[182:185], v[222:225], v[100:103]
	v_mfma_f32_16x16x32_bf16 v[92:95], v[174:177], v[230:233], v[92:95]
	v_mfma_f32_16x16x32_bf16 v[84:87], v[182:185], v[230:233], v[84:87]
	v_mfma_f32_16x16x32_bf16 v[76:79], v[174:177], v[238:241], v[76:79]
	v_mfma_f32_16x16x32_bf16 v[68:71], v[182:185], v[238:241], v[68:71]
	s_setprio 0
	s_setprio 1
	v_mfma_f32_16x16x32_bf16 v[120:123], v[186:189], v[210:213], v[120:123]
	v_mfma_f32_16x16x32_bf16 v[112:115], v[194:197], v[210:213], v[112:115]
	v_mfma_f32_16x16x32_bf16 v[104:107], v[186:189], v[218:221], v[104:107]
	v_mfma_f32_16x16x32_bf16 v[96:99], v[194:197], v[218:221], v[96:99]
	v_mfma_f32_16x16x32_bf16 v[88:91], v[186:189], v[226:229], v[88:91]
	v_mfma_f32_16x16x32_bf16 v[80:83], v[194:197], v[226:229], v[80:83]
	v_mfma_f32_16x16x32_bf16 v[72:75], v[186:189], v[234:237], v[72:75]
	v_mfma_f32_16x16x32_bf16 v[64:67], v[194:197], v[234:237], v[64:67]
	v_mfma_f32_16x16x32_bf16 v[120:123], v[190:193], v[214:217], v[120:123]
	v_mfma_f32_16x16x32_bf16 v[112:115], v[198:201], v[214:217], v[112:115]
	v_mfma_f32_16x16x32_bf16 v[104:107], v[190:193], v[222:225], v[104:107]
	v_mfma_f32_16x16x32_bf16 v[96:99], v[198:201], v[222:225], v[96:99]
	v_mfma_f32_16x16x32_bf16 v[88:91], v[190:193], v[230:233], v[88:91]
	v_mfma_f32_16x16x32_bf16 v[80:83], v[198:201], v[230:233], v[80:83]
	v_mfma_f32_16x16x32_bf16 v[72:75], v[190:193], v[238:241], v[72:75]
	v_mfma_f32_16x16x32_bf16 v[64:67], v[198:201], v[238:241], v[64:67]
	s_setprio 0
	s_barrier
	s_add_u32 s28, s26, 0x8000
	s_addc_u32 s29, s27, 0
	s_add_i32 s55, s55, s38
	s_mov_b32 m0, s55
	ds_read_b128 v[210:213], v169 offset:49152
	ds_read_b128 v[214:217], v169 offset:50176
	ds_read_b128 v[218:221], v169 offset:51200
	ds_read_b128 v[222:225], v169 offset:52224
	ds_read_b128 v[226:229], v169 offset:53248
	ds_read_b128 v[230:233], v169 offset:54272
	ds_read_b128 v[234:237], v169 offset:55296
	ds_read_b128 v[238:241], v169 offset:56320
	global_load_lds_dwordx4 v134, s[28:29]
	s_add_i32 m0, s55, 0x2000
	s_add_u32 s26, s26, 0xc000
	v_lshl_add_u64 v[244:245], s[28:29], 0, v[130:131]
	s_addc_u32 s27, s27, 0
	s_add_i32 s28, s56, s38
	global_load_lds_dwordx4 v[244:245], off
	s_mov_b32 m0, s28
	v_lshl_add_u64 v[164:165], v[164:165], 0, s[8:9]
	global_load_lds_dwordx4 v134, s[26:27]
	s_add_i32 m0, s28, 0x2000
	s_nop 0
	global_load_lds_dwordx4 v130, s[26:27]
	s_mov_b32 m0, s45
	s_nop 0
	global_load_lds_dwordx4 v[164:165], off
	v_lshl_add_u64 v[164:165], v[242:243], 0, s[8:9]
	s_mov_b32 m0, s46
	s_nop 0
	global_load_lds_dwordx4 v[164:165], off
	s_waitcnt vmcnt(8)
	s_waitcnt lgkmcnt(0)
	s_barrier
	s_setprio 1
	s_waitcnt lgkmcnt(0)
	v_mfma_f32_16x16x32_bf16 v[60:63], v[170:173], v[210:213], v[60:63]
	v_mfma_f32_16x16x32_bf16 v[52:55], v[178:181], v[210:213], v[52:55]
	v_mfma_f32_16x16x32_bf16 v[44:47], v[170:173], v[218:221], v[44:47]
	v_mfma_f32_16x16x32_bf16 v[36:39], v[178:181], v[218:221], v[36:39]
	v_mfma_f32_16x16x32_bf16 v[28:31], v[170:173], v[226:229], v[28:31]
	v_mfma_f32_16x16x32_bf16 v[20:23], v[178:181], v[226:229], v[20:23]
	v_mfma_f32_16x16x32_bf16 v[12:15], v[170:173], v[234:237], v[12:15]
	v_mfma_f32_16x16x32_bf16 v[4:7], v[178:181], v[234:237], v[4:7]
	v_mfma_f32_16x16x32_bf16 v[60:63], v[174:177], v[214:217], v[60:63]
	v_mfma_f32_16x16x32_bf16 v[52:55], v[182:185], v[214:217], v[52:55]
	v_mfma_f32_16x16x32_bf16 v[44:47], v[174:177], v[222:225], v[44:47]
	v_mfma_f32_16x16x32_bf16 v[36:39], v[182:185], v[222:225], v[36:39]
	v_mfma_f32_16x16x32_bf16 v[28:31], v[174:177], v[230:233], v[28:31]
	v_mfma_f32_16x16x32_bf16 v[20:23], v[182:185], v[230:233], v[20:23]
	v_mfma_f32_16x16x32_bf16 v[12:15], v[174:177], v[238:241], v[12:15]
	v_mfma_f32_16x16x32_bf16 v[4:7], v[182:185], v[238:241], v[4:7]
	s_setprio 0
	s_setprio 1
	v_mfma_f32_16x16x32_bf16 v[56:59], v[186:189], v[210:213], v[56:59]
	v_mfma_f32_16x16x32_bf16 v[48:51], v[194:197], v[210:213], v[48:51]
	v_mfma_f32_16x16x32_bf16 v[40:43], v[186:189], v[218:221], v[40:43]
	v_mfma_f32_16x16x32_bf16 v[32:35], v[194:197], v[218:221], v[32:35]
	v_mfma_f32_16x16x32_bf16 v[24:27], v[186:189], v[226:229], v[24:27]
	v_mfma_f32_16x16x32_bf16 v[16:19], v[194:197], v[226:229], v[16:19]
	v_mfma_f32_16x16x32_bf16 v[8:11], v[186:189], v[234:237], v[8:11]
	v_mfma_f32_16x16x32_bf16 v[0:3], v[194:197], v[234:237], v[0:3]
	v_mfma_f32_16x16x32_bf16 v[56:59], v[190:193], v[214:217], v[56:59]
	v_mfma_f32_16x16x32_bf16 v[48:51], v[198:201], v[214:217], v[48:51]
	v_mfma_f32_16x16x32_bf16 v[40:43], v[190:193], v[222:225], v[40:43]
	v_mfma_f32_16x16x32_bf16 v[32:35], v[198:201], v[222:225], v[32:35]
	v_mfma_f32_16x16x32_bf16 v[24:27], v[190:193], v[230:233], v[24:27]
	v_mfma_f32_16x16x32_bf16 v[16:19], v[198:201], v[230:233], v[16:19]
	v_mfma_f32_16x16x32_bf16 v[8:11], v[190:193], v[238:241], v[8:11]
	v_mfma_f32_16x16x32_bf16 v[0:3], v[198:201], v[238:241], v[0:3]
	s_setprio 0
	s_barrier
	s_add_i32 s54, s54, 2
	s_add_u32 s52, s52, 0x10000
	s_addc_u32 s53, s53, 0
	s_add_u32 s24, s24, 0x100
	s_addc_u32 s25, s25, 0
	s_cmp_gt_u32 s54, 13
	s_cbranch_scc0 .LBB0_289
	s_and_b64 vcc, exec, s[10:11]
	s_cbranch_vccz .LBB0_292
	s_barrier

.LBB0_408:
	v_add_u32_e32 v168, s71, v182
	v_add_u32_e32 v204, s72, v182
	ds_read_b128 v[156:159], v168
	ds_read_b128 v[160:163], v168 offset:1024
	ds_read_b128 v[164:167], v168 offset:2048
	ds_read_b128 v[168:171], v168 offset:3072
	ds_read_b128 v[172:175], v204
	ds_read_b128 v[176:179], v204 offset:1024
	ds_read_b128 v[212:215], v204 offset:2048
	ds_read_b128 v[216:219], v204 offset:3072
	s_add_u32 s40, s38, 0x4000
	s_addc_u32 s41, s39, 0
	s_cmp_eq_u32 s49, 40
	s_cselect_b32 s44, s0, s40
	s_cselect_b32 s45, s1, s41
	s_cselect_b32 s42, s36, s47
	s_cselect_b32 s43, s37, s48
	s_add_u32 s40, s44, 0x8000
	s_addc_u32 s41, s45, 0
	s_add_i32 m0, s58, 0xc000
	ds_read_b128 v[220:223], v199
	ds_read_b128 v[224:227], v199 offset:1024
	ds_read_b128 v[228:231], v199 offset:2048
	ds_read_b128 v[232:235], v199 offset:3072
	ds_read_b128 v[236:239], v199 offset:4096
	ds_read_b128 v[240:243], v199 offset:5120
	ds_read_b128 v[244:247], v199 offset:6144
	ds_read_b128 v[248:251], v199 offset:7168
	global_load_lds_dwordx4 v150, s[38:39]
	s_add_i32 m0, s58, 0xe000
	s_nop 0
	global_load_lds_dwordx4 v148, s[38:39]
	s_waitcnt vmcnt(8)
	s_waitcnt lgkmcnt(0)
	s_barrier
	s_setprio 1
	s_waitcnt lgkmcnt(0)
	v_mfma_f32_16x16x32_bf16 v[124:127], v[156:159], v[220:223], v[124:127]
	v_mfma_f32_16x16x32_bf16 v[120:123], v[164:167], v[220:223], v[120:123]
	v_mfma_f32_16x16x32_bf16 v[116:119], v[156:159], v[228:231], v[116:119]
	v_mfma_f32_16x16x32_bf16 v[108:111], v[164:167], v[228:231], v[108:111]
	v_mfma_f32_16x16x32_bf16 v[92:95], v[156:159], v[236:239], v[92:95]
	v_mfma_f32_16x16x32_bf16 v[88:91], v[164:167], v[236:239], v[88:91]
	v_mfma_f32_16x16x32_bf16 v[84:87], v[156:159], v[244:247], v[84:87]
	v_mfma_f32_16x16x32_bf16 v[76:79], v[164:167], v[244:247], v[76:79]
	v_mfma_f32_16x16x32_bf16 v[124:127], v[160:163], v[224:227], v[124:127]
	v_mfma_f32_16x16x32_bf16 v[120:123], v[168:171], v[224:227], v[120:123]
	v_mfma_f32_16x16x32_bf16 v[116:119], v[160:163], v[232:235], v[116:119]
	v_mfma_f32_16x16x32_bf16 v[108:111], v[168:171], v[232:235], v[108:111]
	v_mfma_f32_16x16x32_bf16 v[92:95], v[160:163], v[240:243], v[92:95]
	v_mfma_f32_16x16x32_bf16 v[88:91], v[168:171], v[240:243], v[88:91]
	v_mfma_f32_16x16x32_bf16 v[84:87], v[160:163], v[248:251], v[84:87]
	v_mfma_f32_16x16x32_bf16 v[76:79], v[168:171], v[248:251], v[76:79]
	s_setprio 0
	s_setprio 1
	v_mfma_f32_16x16x32_bf16 v[112:115], v[172:175], v[220:223], v[112:115]
	v_mfma_f32_16x16x32_bf16 v[104:107], v[212:215], v[220:223], v[104:107]
	v_mfma_f32_16x16x32_bf16 v[100:103], v[172:175], v[228:231], v[100:103]
	v_mfma_f32_16x16x32_bf16 v[96:99], v[212:215], v[228:231], v[96:99]
	v_mfma_f32_16x16x32_bf16 v[80:83], v[172:175], v[236:239], v[80:83]
	v_mfma_f32_16x16x32_bf16 v[72:75], v[212:215], v[236:239], v[72:75]
	v_mfma_f32_16x16x32_bf16 v[68:71], v[172:175], v[244:247], v[68:71]
	v_mfma_f32_16x16x32_bf16 v[64:67], v[212:215], v[244:247], v[64:67]
	v_mfma_f32_16x16x32_bf16 v[112:115], v[176:179], v[224:227], v[112:115]
	v_mfma_f32_16x16x32_bf16 v[104:107], v[216:219], v[224:227], v[104:107]
	v_mfma_f32_16x16x32_bf16 v[100:103], v[176:179], v[232:235], v[100:103]
	v_mfma_f32_16x16x32_bf16 v[96:99], v[216:219], v[232:235], v[96:99]
	v_mfma_f32_16x16x32_bf16 v[80:83], v[176:179], v[240:243], v[80:83]
	v_mfma_f32_16x16x32_bf16 v[72:75], v[216:219], v[240:243], v[72:75]
	v_mfma_f32_16x16x32_bf16 v[68:71], v[176:179], v[248:251], v[68:71]
	v_mfma_f32_16x16x32_bf16 v[64:67], v[216:219], v[248:251], v[64:67]
	s_setprio 0
	s_barrier
	s_add_i32 s50, s71, s57
	s_mov_b32 m0, s50
	ds_read_b128 v[220:223], v199 offset:16384
	ds_read_b128 v[224:227], v199 offset:17408
	ds_read_b128 v[228:231], v199 offset:18432
	ds_read_b128 v[232:235], v199 offset:19456
	ds_read_b128 v[236:239], v199 offset:20480
	ds_read_b128 v[240:243], v199 offset:21504
	ds_read_b128 v[244:247], v199 offset:22528
	ds_read_b128 v[248:251], v199 offset:23552
	global_load_lds_dwordx4 v128, s[42:43]
	s_add_i32 m0, s50, 0x2000
	s_add_u32 s50, s42, 0x4000
	s_addc_u32 s51, s43, 0
	s_add_i32 s52, s72, s57
	global_load_lds_dwordx4 v130, s[42:43]
	s_mov_b32 m0, s52
	s_nop 0
	global_load_lds_dwordx4 v128, s[50:51]
	s_add_i32 m0, s52, 0x2000
	s_nop 0
	global_load_lds_dwordx4 v130, s[50:51]
	s_mov_b32 m0, s58
	s_nop 0
	global_load_lds_dwordx4 v128, s[44:45]
	s_mov_b32 m0, s59
	s_nop 0
	global_load_lds_dwordx4 v130, s[44:45]
	s_waitcnt vmcnt(8)
	s_waitcnt lgkmcnt(0)
	s_barrier
	s_setprio 1
	s_waitcnt lgkmcnt(0)
	v_mfma_f32_16x16x32_bf16 v[60:63], v[156:159], v[220:223], v[60:63]
	v_mfma_f32_16x16x32_bf16 v[56:59], v[164:167], v[220:223], v[56:59]
	v_mfma_f32_16x16x32_bf16 v[52:55], v[156:159], v[228:231], v[52:55]
	v_mfma_f32_16x16x32_bf16 v[44:47], v[164:167], v[228:231], v[44:47]
	v_mfma_f32_16x16x32_bf16 v[32:35], v[156:159], v[236:239], v[32:35]
	v_mfma_f32_16x16x32_bf16 v[24:27], v[164:167], v[236:239], v[24:27]
	v_mfma_f32_16x16x32_bf16 v[20:23], v[156:159], v[244:247], v[20:23]
	v_mfma_f32_16x16x32_bf16 v[12:15], v[164:167], v[244:247], v[12:15]
	v_mfma_f32_16x16x32_bf16 v[60:63], v[160:163], v[224:227], v[60:63]
	v_mfma_f32_16x16x32_bf16 v[56:59], v[168:171], v[224:227], v[56:59]
	v_mfma_f32_16x16x32_bf16 v[52:55], v[160:163], v[232:235], v[52:55]
	v_mfma_f32_16x16x32_bf16 v[44:47], v[168:171], v[232:235], v[44:47]
	v_mfma_f32_16x16x32_bf16 v[32:35], v[160:163], v[240:243], v[32:35]
	v_mfma_f32_16x16x32_bf16 v[24:27], v[168:171], v[240:243], v[24:27]
	v_mfma_f32_16x16x32_bf16 v[20:23], v[160:163], v[248:251], v[20:23]
	v_mfma_f32_16x16x32_bf16 v[12:15], v[168:171], v[248:251], v[12:15]
	s_setprio 0
	s_setprio 1
	v_mfma_f32_16x16x32_bf16 v[48:51], v[172:175], v[220:223], v[48:51]
	v_mfma_f32_16x16x32_bf16 v[40:43], v[212:215], v[220:223], v[40:43]
	v_mfma_f32_16x16x32_bf16 v[36:39], v[172:175], v[228:231], v[36:39]
	v_mfma_f32_16x16x32_bf16 v[28:31], v[212:215], v[228:231], v[28:31]
	v_mfma_f32_16x16x32_bf16 v[16:19], v[172:175], v[236:239], v[16:19]
	v_mfma_f32_16x16x32_bf16 v[8:11], v[212:215], v[236:239], v[8:11]
	v_mfma_f32_16x16x32_bf16 v[4:7], v[172:175], v[244:247], v[4:7]
	v_mfma_f32_16x16x32_bf16 v[0:3], v[212:215], v[244:247], v[0:3]
	v_mfma_f32_16x16x32_bf16 v[48:51], v[176:179], v[224:227], v[48:51]
	v_mfma_f32_16x16x32_bf16 v[40:43], v[216:219], v[224:227], v[40:43]
	v_mfma_f32_16x16x32_bf16 v[36:39], v[176:179], v[232:235], v[36:39]
	v_mfma_f32_16x16x32_bf16 v[28:31], v[216:219], v[232:235], v[28:31]
	v_mfma_f32_16x16x32_bf16 v[16:19], v[176:179], v[240:243], v[16:19]
	v_mfma_f32_16x16x32_bf16 v[8:11], v[216:219], v[240:243], v[8:11]
	v_mfma_f32_16x16x32_bf16 v[4:7], v[176:179], v[248:251], v[4:7]
	v_mfma_f32_16x16x32_bf16 v[0:3], v[216:219], v[248:251], v[0:3]
	s_setprio 0
	s_barrier
	s_add_i32 s50, 0, 0x18000
	s_add_i32 s51, 0, 0x1c000
	v_add_u32_e32 v168, s50, v182
	v_add_u32_e32 v204, s51, v182
	ds_read_b128 v[156:159], v168
	ds_read_b128 v[160:163], v168 offset:1024
	ds_read_b128 v[164:167], v168 offset:2048
	ds_read_b128 v[168:171], v168 offset:3072
	ds_read_b128 v[172:175], v204
	ds_read_b128 v[176:179], v204 offset:1024
	ds_read_b128 v[212:215], v204 offset:2048
	ds_read_b128 v[216:219], v204 offset:3072
	s_add_u32 s44, s44, 0x4000
	s_addc_u32 s45, s45, 0
	s_mov_b32 m0, s60
	ds_read_b128 v[220:223], v199 offset:32768
	ds_read_b128 v[224:227], v199 offset:33792
	ds_read_b128 v[228:231], v199 offset:34816
	ds_read_b128 v[232:235], v199 offset:35840
	ds_read_b128 v[236:239], v199 offset:36864
	ds_read_b128 v[240:243], v199 offset:37888
	ds_read_b128 v[244:247], v199 offset:38912
	ds_read_b128 v[248:251], v199 offset:39936
	global_load_lds_dwordx4 v128, s[44:45]
	s_mov_b32 m0, s61
	s_nop 0
	global_load_lds_dwordx4 v130, s[44:45]
	s_waitcnt vmcnt(8)
	s_waitcnt lgkmcnt(0)
	s_barrier
	s_setprio 1
	s_waitcnt lgkmcnt(0)
	v_mfma_f32_16x16x32_bf16 v[124:127], v[156:159], v[220:223], v[124:127]
	v_mfma_f32_16x16x32_bf16 v[120:123], v[164:167], v[220:223], v[120:123]
	v_mfma_f32_16x16x32_bf16 v[116:119], v[156:159], v[228:231], v[116:119]
	v_mfma_f32_16x16x32_bf16 v[108:111], v[164:167], v[228:231], v[108:111]
	v_mfma_f32_16x16x32_bf16 v[92:95], v[156:159], v[236:239], v[92:95]
	v_mfma_f32_16x16x32_bf16 v[88:91], v[164:167], v[236:239], v[88:91]
	v_mfma_f32_16x16x32_bf16 v[84:87], v[156:159], v[244:247], v[84:87]
	v_mfma_f32_16x16x32_bf16 v[76:79], v[164:167], v[244:247], v[76:79]
	v_mfma_f32_16x16x32_bf16 v[124:127], v[160:163], v[224:227], v[124:127]
	v_mfma_f32_16x16x32_bf16 v[120:123], v[168:171], v[224:227], v[120:123]
	v_mfma_f32_16x16x32_bf16 v[116:119], v[160:163], v[232:235], v[116:119]
	v_mfma_f32_16x16x32_bf16 v[108:111], v[168:171], v[232:235], v[108:111]
	v_mfma_f32_16x16x32_bf16 v[92:95], v[160:163], v[240:243], v[92:95]
	v_mfma_f32_16x16x32_bf16 v[88:91], v[168:171], v[240:243], v[88:91]
	v_mfma_f32_16x16x32_bf16 v[84:87], v[160:163], v[248:251], v[84:87]
	v_mfma_f32_16x16x32_bf16 v[76:79], v[168:171], v[248:251], v[76:79]
	s_setprio 0
	s_setprio 1
	v_mfma_f32_16x16x32_bf16 v[112:115], v[172:175], v[220:223], v[112:115]
	v_mfma_f32_16x16x32_bf16 v[104:107], v[212:215], v[220:223], v[104:107]
	v_mfma_f32_16x16x32_bf16 v[100:103], v[172:175], v[228:231], v[100:103]
	v_mfma_f32_16x16x32_bf16 v[96:99], v[212:215], v[228:231], v[96:99]
	v_mfma_f32_16x16x32_bf16 v[80:83], v[172:175], v[236:239], v[80:83]
	v_mfma_f32_16x16x32_bf16 v[72:75], v[212:215], v[236:239], v[72:75]
	v_mfma_f32_16x16x32_bf16 v[68:71], v[172:175], v[244:247], v[68:71]
	v_mfma_f32_16x16x32_bf16 v[64:67], v[212:215], v[244:247], v[64:67]
	v_mfma_f32_16x16x32_bf16 v[112:115], v[176:179], v[224:227], v[112:115]
	v_mfma_f32_16x16x32_bf16 v[104:107], v[216:219], v[224:227], v[104:107]
	v_mfma_f32_16x16x32_bf16 v[100:103], v[176:179], v[232:235], v[100:103]
	v_mfma_f32_16x16x32_bf16 v[96:99], v[216:219], v[232:235], v[96:99]
	v_mfma_f32_16x16x32_bf16 v[80:83], v[176:179], v[240:243], v[80:83]
	v_mfma_f32_16x16x32_bf16 v[72:75], v[216:219], v[240:243], v[72:75]
	v_mfma_f32_16x16x32_bf16 v[68:71], v[176:179], v[248:251], v[68:71]
	v_mfma_f32_16x16x32_bf16 v[64:67], v[216:219], v[248:251], v[64:67]
	s_setprio 0
	s_barrier
	s_add_u32 s44, s42, 0x8000
	s_addc_u32 s45, s43, 0
	s_add_i32 s50, s50, s57
	s_mov_b32 m0, s50
	ds_read_b128 v[220:223], v199 offset:49152
	ds_read_b128 v[224:227], v199 offset:50176
	ds_read_b128 v[228:231], v199 offset:51200
	ds_read_b128 v[232:235], v199 offset:52224
	ds_read_b128 v[236:239], v199 offset:53248
	ds_read_b128 v[240:243], v199 offset:54272
	ds_read_b128 v[244:247], v199 offset:55296
	ds_read_b128 v[248:251], v199 offset:56320
	global_load_lds_dwordx4 v128, s[44:45]
	s_add_i32 m0, s50, 0x2000
	s_add_u32 s42, s42, 0xc000
	v_lshl_add_u64 v[252:253], s[44:45], 0, v[130:131]
	s_addc_u32 s43, s43, 0
	s_add_i32 s44, s51, s57
	global_load_lds_dwordx4 v[252:253], off
	s_mov_b32 m0, s44
	s_nop 0
	global_load_lds_dwordx4 v128, s[42:43]
	s_add_i32 m0, s44, 0x2000
	s_nop 0
	global_load_lds_dwordx4 v130, s[42:43]
	s_mov_b32 m0, s67
	s_nop 0
	global_load_lds_dwordx4 v128, s[40:41]
	s_mov_b32 m0, s68
	s_nop 0
	global_load_lds_dwordx4 v130, s[40:41]
	s_waitcnt vmcnt(8)
	s_waitcnt lgkmcnt(0)
	s_barrier
	s_setprio 1
	s_waitcnt lgkmcnt(0)
	v_mfma_f32_16x16x32_bf16 v[60:63], v[156:159], v[220:223], v[60:63]
	v_mfma_f32_16x16x32_bf16 v[56:59], v[164:167], v[220:223], v[56:59]
	v_mfma_f32_16x16x32_bf16 v[52:55], v[156:159], v[228:231], v[52:55]
	v_mfma_f32_16x16x32_bf16 v[44:47], v[164:167], v[228:231], v[44:47]
	v_mfma_f32_16x16x32_bf16 v[32:35], v[156:159], v[236:239], v[32:35]
	v_mfma_f32_16x16x32_bf16 v[24:27], v[164:167], v[236:239], v[24:27]
	v_mfma_f32_16x16x32_bf16 v[20:23], v[156:159], v[244:247], v[20:23]
	v_mfma_f32_16x16x32_bf16 v[12:15], v[164:167], v[244:247], v[12:15]
	v_mfma_f32_16x16x32_bf16 v[60:63], v[160:163], v[224:227], v[60:63]
	v_mfma_f32_16x16x32_bf16 v[56:59], v[168:171], v[224:227], v[56:59]
	v_mfma_f32_16x16x32_bf16 v[52:55], v[160:163], v[232:235], v[52:55]
	v_mfma_f32_16x16x32_bf16 v[44:47], v[168:171], v[232:235], v[44:47]
	v_mfma_f32_16x16x32_bf16 v[32:35], v[160:163], v[240:243], v[32:35]
	v_mfma_f32_16x16x32_bf16 v[24:27], v[168:171], v[240:243], v[24:27]
	v_mfma_f32_16x16x32_bf16 v[20:23], v[160:163], v[248:251], v[20:23]
	v_mfma_f32_16x16x32_bf16 v[12:15], v[168:171], v[248:251], v[12:15]
	s_setprio 0
	s_setprio 1
	v_mfma_f32_16x16x32_bf16 v[48:51], v[172:175], v[220:223], v[48:51]
	v_mfma_f32_16x16x32_bf16 v[40:43], v[212:215], v[220:223], v[40:43]
	v_mfma_f32_16x16x32_bf16 v[36:39], v[172:175], v[228:231], v[36:39]
	v_mfma_f32_16x16x32_bf16 v[28:31], v[212:215], v[228:231], v[28:31]
	v_mfma_f32_16x16x32_bf16 v[16:19], v[172:175], v[236:239], v[16:19]
	v_mfma_f32_16x16x32_bf16 v[8:11], v[212:215], v[236:239], v[8:11]
	v_mfma_f32_16x16x32_bf16 v[4:7], v[172:175], v[244:247], v[4:7]
	v_mfma_f32_16x16x32_bf16 v[0:3], v[212:215], v[244:247], v[0:3]
	v_mfma_f32_16x16x32_bf16 v[48:51], v[176:179], v[224:227], v[48:51]
	v_mfma_f32_16x16x32_bf16 v[40:43], v[216:219], v[224:227], v[40:43]
	v_mfma_f32_16x16x32_bf16 v[36:39], v[176:179], v[232:235], v[36:39]
	v_mfma_f32_16x16x32_bf16 v[28:31], v[216:219], v[232:235], v[28:31]
	v_mfma_f32_16x16x32_bf16 v[16:19], v[176:179], v[240:243], v[16:19]
	v_mfma_f32_16x16x32_bf16 v[8:11], v[216:219], v[240:243], v[8:11]
	v_mfma_f32_16x16x32_bf16 v[4:7], v[176:179], v[248:251], v[4:7]
	v_mfma_f32_16x16x32_bf16 v[0:3], v[216:219], v[248:251], v[0:3]
	s_setprio 0
	s_barrier
	s_add_i32 s49, s49, 2
	s_add_u32 s47, s47, 0x10000
	s_addc_u32 s48, s48, 0
	s_add_u32 s38, s38, 0x10000
	s_addc_u32 s39, s39, 0
	s_cmp_gt_u32 s49, 41
	s_cbranch_scc0 .LBB0_408
	s_and_b64 vcc, exec, s[14:15]
	s_cbranch_vccz .LBB0_411
	s_barrier

.LBB0_492:
	ds_read_b128 v[128:131], v212
	ds_read_b128 v[132:135], v212 offset:1024
	ds_read_b128 v[136:139], v212 offset:2048
	ds_read_b128 v[140:143], v212 offset:3072
	ds_read_b128 v[144:147], v213
	ds_read_b128 v[148:151], v213 offset:1024
	ds_read_b128 v[152:155], v213 offset:2048
	ds_read_b128 v[156:159], v213 offset:3072
	s_add_u32 s34, s30, 0xfffc0080
	s_addc_u32 s35, s31, -1
	s_cmp_eq_u32 s39, 12
	s_cselect_b32 s37, s1, s35
	s_cselect_b32 s36, s7, s34
	s_cselect_b32 s35, s10, s38
	s_cselect_b32 s34, s23, s25
	s_add_i32 m0, s47, 0xc000
	ds_read_b128 v[160:163], v214
	ds_read_b128 v[164:167], v214 offset:1024
	ds_read_b128 v[196:199], v214 offset:2048
	ds_read_b128 v[216:219], v214 offset:3072
	ds_read_b128 v[220:223], v214 offset:4096
	ds_read_b128 v[224:227], v214 offset:5120
	ds_read_b128 v[228:231], v214 offset:6144
	ds_read_b128 v[232:235], v214 offset:7168
	global_load_lds_dwordx4 v190, s[30:31]
	s_add_i32 m0, s47, 0xe000
	s_nop 0
	global_load_lds_dwordx4 v188, s[30:31]
	s_waitcnt vmcnt(8)
	s_waitcnt lgkmcnt(0)
	s_barrier
	s_setprio 1
	s_waitcnt lgkmcnt(0)
	v_mfma_f32_16x16x32_bf16 v[124:127], v[128:131], v[160:163], v[124:127]
	v_mfma_f32_16x16x32_bf16 v[120:123], v[136:139], v[160:163], v[120:123]
	v_mfma_f32_16x16x32_bf16 v[116:119], v[128:131], v[196:199], v[116:119]
	v_mfma_f32_16x16x32_bf16 v[112:115], v[136:139], v[196:199], v[112:115]
	v_mfma_f32_16x16x32_bf16 v[108:111], v[128:131], v[220:223], v[108:111]
	v_mfma_f32_16x16x32_bf16 v[104:107], v[136:139], v[220:223], v[104:107]
	v_mfma_f32_16x16x32_bf16 v[100:103], v[128:131], v[228:231], v[100:103]
	v_mfma_f32_16x16x32_bf16 v[96:99], v[136:139], v[228:231], v[96:99]
	v_mfma_f32_16x16x32_bf16 v[124:127], v[132:135], v[164:167], v[124:127]
	v_mfma_f32_16x16x32_bf16 v[120:123], v[140:143], v[164:167], v[120:123]
	v_mfma_f32_16x16x32_bf16 v[116:119], v[132:135], v[216:219], v[116:119]
	v_mfma_f32_16x16x32_bf16 v[112:115], v[140:143], v[216:219], v[112:115]
	v_mfma_f32_16x16x32_bf16 v[108:111], v[132:135], v[224:227], v[108:111]
	v_mfma_f32_16x16x32_bf16 v[104:107], v[140:143], v[224:227], v[104:107]
	v_mfma_f32_16x16x32_bf16 v[100:103], v[132:135], v[232:235], v[100:103]
	v_mfma_f32_16x16x32_bf16 v[96:99], v[140:143], v[232:235], v[96:99]
	s_setprio 0
	s_setprio 1
	v_mfma_f32_16x16x32_bf16 v[60:63], v[144:147], v[160:163], v[60:63]
	v_mfma_f32_16x16x32_bf16 v[56:59], v[152:155], v[160:163], v[56:59]
	v_mfma_f32_16x16x32_bf16 v[52:55], v[144:147], v[196:199], v[52:55]
	v_mfma_f32_16x16x32_bf16 v[48:51], v[152:155], v[196:199], v[48:51]
	v_mfma_f32_16x16x32_bf16 v[44:47], v[144:147], v[220:223], v[44:47]
	v_mfma_f32_16x16x32_bf16 v[40:43], v[152:155], v[220:223], v[40:43]
	v_mfma_f32_16x16x32_bf16 v[36:39], v[144:147], v[228:231], v[36:39]
	v_mfma_f32_16x16x32_bf16 v[32:35], v[152:155], v[228:231], v[32:35]
	v_mfma_f32_16x16x32_bf16 v[60:63], v[148:151], v[164:167], v[60:63]
	v_mfma_f32_16x16x32_bf16 v[56:59], v[156:159], v[164:167], v[56:59]
	v_mfma_f32_16x16x32_bf16 v[52:55], v[148:151], v[216:219], v[52:55]
	v_mfma_f32_16x16x32_bf16 v[48:51], v[156:159], v[216:219], v[48:51]
	v_mfma_f32_16x16x32_bf16 v[44:47], v[148:151], v[224:227], v[44:47]
	v_mfma_f32_16x16x32_bf16 v[40:43], v[156:159], v[224:227], v[40:43]
	v_mfma_f32_16x16x32_bf16 v[36:39], v[148:151], v[232:235], v[36:39]
	v_mfma_f32_16x16x32_bf16 v[32:35], v[156:159], v[232:235], v[32:35]
	s_setprio 0
	s_barrier
	s_add_i32 s66, s61, s46
	s_mov_b32 m0, s66
	ds_read_b128 v[160:163], v214 offset:16384
	ds_read_b128 v[164:167], v214 offset:17408
	ds_read_b128 v[196:199], v214 offset:18432
	ds_read_b128 v[216:219], v214 offset:19456
	ds_read_b128 v[220:223], v214 offset:20480
	ds_read_b128 v[224:227], v214 offset:21504
	ds_read_b128 v[228:231], v214 offset:22528
	ds_read_b128 v[232:235], v214 offset:23552
	global_load_lds_dwordx4 v172, s[34:35]
	s_add_i32 m0, s66, 0x2000
	s_add_u32 s66, s34, 0x4000
	s_addc_u32 s67, s35, 0
	s_add_i32 s68, s62, s46
	global_load_lds_dwordx4 v176, s[34:35]
	s_mov_b32 m0, s68
	v_lshl_add_u64 v[236:237], s[36:37], 0, v[174:175]
	global_load_lds_dwordx4 v172, s[66:67]
	s_add_i32 m0, s68, 0x2000
	s_nop 0
	global_load_lds_dwordx4 v176, s[66:67]
	v_lshl_add_u64 v[200:201], s[36:37], 0, v[170:171]
	s_mov_b32 m0, s47
	s_nop 0
	global_load_lds_dwordx4 v[200:201], off
	s_mov_b32 m0, s48
	s_nop 0
	global_load_lds_dwordx4 v[236:237], off
	s_waitcnt vmcnt(8)
	s_waitcnt lgkmcnt(0)
	s_barrier
	s_setprio 1
	s_waitcnt lgkmcnt(0)
	v_mfma_f32_16x16x32_bf16 v[92:95], v[128:131], v[160:163], v[92:95]
	v_mfma_f32_16x16x32_bf16 v[88:91], v[136:139], v[160:163], v[88:91]
	v_mfma_f32_16x16x32_bf16 v[84:87], v[128:131], v[196:199], v[84:87]
	v_mfma_f32_16x16x32_bf16 v[80:83], v[136:139], v[196:199], v[80:83]
	v_mfma_f32_16x16x32_bf16 v[76:79], v[128:131], v[220:223], v[76:79]
	v_mfma_f32_16x16x32_bf16 v[72:75], v[136:139], v[220:223], v[72:75]
	v_mfma_f32_16x16x32_bf16 v[68:71], v[128:131], v[228:231], v[68:71]
	v_mfma_f32_16x16x32_bf16 v[64:67], v[136:139], v[228:231], v[64:67]
	v_mfma_f32_16x16x32_bf16 v[92:95], v[132:135], v[164:167], v[92:95]
	v_mfma_f32_16x16x32_bf16 v[88:91], v[140:143], v[164:167], v[88:91]
	v_mfma_f32_16x16x32_bf16 v[84:87], v[132:135], v[216:219], v[84:87]
	v_mfma_f32_16x16x32_bf16 v[80:83], v[140:143], v[216:219], v[80:83]
	v_mfma_f32_16x16x32_bf16 v[76:79], v[132:135], v[224:227], v[76:79]
	v_mfma_f32_16x16x32_bf16 v[72:75], v[140:143], v[224:227], v[72:75]
	v_mfma_f32_16x16x32_bf16 v[68:71], v[132:135], v[232:235], v[68:71]
	v_mfma_f32_16x16x32_bf16 v[64:67], v[140:143], v[232:235], v[64:67]
	s_setprio 0
	s_setprio 1
	v_mfma_f32_16x16x32_bf16 v[28:31], v[144:147], v[160:163], v[28:31]
	v_mfma_f32_16x16x32_bf16 v[24:27], v[152:155], v[160:163], v[24:27]
	v_mfma_f32_16x16x32_bf16 v[20:23], v[144:147], v[196:199], v[20:23]
	v_mfma_f32_16x16x32_bf16 v[16:19], v[152:155], v[196:199], v[16:19]
	v_mfma_f32_16x16x32_bf16 v[12:15], v[144:147], v[220:223], v[12:15]
	v_mfma_f32_16x16x32_bf16 v[8:11], v[152:155], v[220:223], v[8:11]
	v_mfma_f32_16x16x32_bf16 v[4:7], v[144:147], v[228:231], v[4:7]
	v_mfma_f32_16x16x32_bf16 v[0:3], v[152:155], v[228:231], v[0:3]
	v_mfma_f32_16x16x32_bf16 v[28:31], v[148:151], v[164:167], v[28:31]
	v_mfma_f32_16x16x32_bf16 v[24:27], v[156:159], v[164:167], v[24:27]
	v_mfma_f32_16x16x32_bf16 v[20:23], v[148:151], v[216:219], v[20:23]
	v_mfma_f32_16x16x32_bf16 v[16:19], v[156:159], v[216:219], v[16:19]
	v_mfma_f32_16x16x32_bf16 v[12:15], v[148:151], v[224:227], v[12:15]
	v_mfma_f32_16x16x32_bf16 v[8:11], v[156:159], v[224:227], v[8:11]
	v_mfma_f32_16x16x32_bf16 v[4:7], v[148:151], v[232:235], v[4:7]
	v_mfma_f32_16x16x32_bf16 v[0:3], v[156:159], v[232:235], v[0:3]
	s_setprio 0
	s_barrier
	s_add_i32 s66, 0, 0x18000
	s_add_i32 s67, 0, 0x1c000
	v_add_u32_e32 v140, s66, v210
	v_add_u32_e32 v156, s67, v210
	ds_read_b128 v[128:131], v140
	ds_read_b128 v[132:135], v140 offset:1024
	ds_read_b128 v[136:139], v140 offset:2048
	ds_read_b128 v[140:143], v140 offset:3072
	ds_read_b128 v[144:147], v156
	ds_read_b128 v[148:151], v156 offset:1024
	ds_read_b128 v[152:155], v156 offset:2048
	ds_read_b128 v[156:159], v156 offset:3072
	s_add_u32 s36, s36, 0x40000
	s_addc_u32 s37, s37, 0
	s_mov_b32 m0, s49
	ds_read_b128 v[160:163], v214 offset:32768
	ds_read_b128 v[164:167], v214 offset:33792
	ds_read_b128 v[196:199], v214 offset:34816
	ds_read_b128 v[216:219], v214 offset:35840
	ds_read_b128 v[220:223], v214 offset:36864
	ds_read_b128 v[224:227], v214 offset:37888
	ds_read_b128 v[228:231], v214 offset:38912
	ds_read_b128 v[232:235], v214 offset:39936
	global_load_lds_dwordx4 v170, s[36:37]
	s_mov_b32 m0, s50
	s_nop 0
	global_load_lds_dwordx4 v174, s[36:37]
	s_waitcnt vmcnt(8)
	s_waitcnt lgkmcnt(0)
	s_barrier
	s_setprio 1
	s_waitcnt lgkmcnt(0)
	v_mfma_f32_16x16x32_bf16 v[124:127], v[128:131], v[160:163], v[124:127]
	v_mfma_f32_16x16x32_bf16 v[120:123], v[136:139], v[160:163], v[120:123]
	v_mfma_f32_16x16x32_bf16 v[116:119], v[128:131], v[196:199], v[116:119]
	v_mfma_f32_16x16x32_bf16 v[112:115], v[136:139], v[196:199], v[112:115]
	v_mfma_f32_16x16x32_bf16 v[108:111], v[128:131], v[220:223], v[108:111]
	v_mfma_f32_16x16x32_bf16 v[104:107], v[136:139], v[220:223], v[104:107]
	v_mfma_f32_16x16x32_bf16 v[100:103], v[128:131], v[228:231], v[100:103]
	v_mfma_f32_16x16x32_bf16 v[96:99], v[136:139], v[228:231], v[96:99]
	v_mfma_f32_16x16x32_bf16 v[124:127], v[132:135], v[164:167], v[124:127]
	v_mfma_f32_16x16x32_bf16 v[120:123], v[140:143], v[164:167], v[120:123]
	v_mfma_f32_16x16x32_bf16 v[116:119], v[132:135], v[216:219], v[116:119]
	v_mfma_f32_16x16x32_bf16 v[112:115], v[140:143], v[216:219], v[112:115]
	v_mfma_f32_16x16x32_bf16 v[108:111], v[132:135], v[224:227], v[108:111]
	v_mfma_f32_16x16x32_bf16 v[104:107], v[140:143], v[224:227], v[104:107]
	v_mfma_f32_16x16x32_bf16 v[100:103], v[132:135], v[232:235], v[100:103]
	v_mfma_f32_16x16x32_bf16 v[96:99], v[140:143], v[232:235], v[96:99]
	s_setprio 0
	s_setprio 1
	v_mfma_f32_16x16x32_bf16 v[60:63], v[144:147], v[160:163], v[60:63]
	v_mfma_f32_16x16x32_bf16 v[56:59], v[152:155], v[160:163], v[56:59]
	v_mfma_f32_16x16x32_bf16 v[52:55], v[144:147], v[196:199], v[52:55]
	v_mfma_f32_16x16x32_bf16 v[48:51], v[152:155], v[196:199], v[48:51]
	v_mfma_f32_16x16x32_bf16 v[44:47], v[144:147], v[220:223], v[44:47]
	v_mfma_f32_16x16x32_bf16 v[40:43], v[152:155], v[220:223], v[40:43]
	v_mfma_f32_16x16x32_bf16 v[36:39], v[144:147], v[228:231], v[36:39]
	v_mfma_f32_16x16x32_bf16 v[32:35], v[152:155], v[228:231], v[32:35]
	v_mfma_f32_16x16x32_bf16 v[60:63], v[148:151], v[164:167], v[60:63]
	v_mfma_f32_16x16x32_bf16 v[56:59], v[156:159], v[164:167], v[56:59]
	v_mfma_f32_16x16x32_bf16 v[52:55], v[148:151], v[216:219], v[52:55]
	v_mfma_f32_16x16x32_bf16 v[48:51], v[156:159], v[216:219], v[48:51]
	v_mfma_f32_16x16x32_bf16 v[44:47], v[148:151], v[224:227], v[44:47]
	v_mfma_f32_16x16x32_bf16 v[40:43], v[156:159], v[224:227], v[40:43]
	v_mfma_f32_16x16x32_bf16 v[36:39], v[148:151], v[232:235], v[36:39]
	v_mfma_f32_16x16x32_bf16 v[32:35], v[156:159], v[232:235], v[32:35]
	s_setprio 0
	s_barrier
	s_add_u32 s36, s34, 0x8000
	s_addc_u32 s37, s35, 0
	s_add_i32 s66, s66, s46
	s_mov_b32 m0, s66
	ds_read_b128 v[160:163], v214 offset:49152
	ds_read_b128 v[164:167], v214 offset:50176
	ds_read_b128 v[196:199], v214 offset:51200
	ds_read_b128 v[216:219], v214 offset:52224
	ds_read_b128 v[220:223], v214 offset:53248
	ds_read_b128 v[224:227], v214 offset:54272
	ds_read_b128 v[228:231], v214 offset:55296
	ds_read_b128 v[232:235], v214 offset:56320
	global_load_lds_dwordx4 v172, s[36:37]
	s_add_i32 m0, s66, 0x2000
	s_add_u32 s34, s34, 0xc000
	v_lshl_add_u64 v[238:239], s[36:37], 0, v[176:177]
	s_addc_u32 s35, s35, 0
	s_add_i32 s36, s67, s46
	global_load_lds_dwordx4 v[238:239], off
	s_mov_b32 m0, s36
	v_lshl_add_u64 v[200:201], v[200:201], 0, s[16:17]
	global_load_lds_dwordx4 v172, s[34:35]
	s_add_i32 m0, s36, 0x2000
	s_nop 0
	global_load_lds_dwordx4 v176, s[34:35]
	s_mov_b32 m0, s55
	s_nop 0
	global_load_lds_dwordx4 v[200:201], off
	v_lshl_add_u64 v[200:201], v[236:237], 0, s[16:17]
	s_mov_b32 m0, s56
	s_nop 0
	global_load_lds_dwordx4 v[200:201], off
	s_waitcnt vmcnt(8)
	s_waitcnt lgkmcnt(0)
	s_barrier
	s_setprio 1
	s_waitcnt lgkmcnt(0)
	v_mfma_f32_16x16x32_bf16 v[92:95], v[128:131], v[160:163], v[92:95]
	v_mfma_f32_16x16x32_bf16 v[88:91], v[136:139], v[160:163], v[88:91]
	v_mfma_f32_16x16x32_bf16 v[84:87], v[128:131], v[196:199], v[84:87]
	v_mfma_f32_16x16x32_bf16 v[80:83], v[136:139], v[196:199], v[80:83]
	v_mfma_f32_16x16x32_bf16 v[76:79], v[128:131], v[220:223], v[76:79]
	v_mfma_f32_16x16x32_bf16 v[72:75], v[136:139], v[220:223], v[72:75]
	v_mfma_f32_16x16x32_bf16 v[68:71], v[128:131], v[228:231], v[68:71]
	v_mfma_f32_16x16x32_bf16 v[64:67], v[136:139], v[228:231], v[64:67]
	v_mfma_f32_16x16x32_bf16 v[92:95], v[132:135], v[164:167], v[92:95]
	v_mfma_f32_16x16x32_bf16 v[88:91], v[140:143], v[164:167], v[88:91]
	v_mfma_f32_16x16x32_bf16 v[84:87], v[132:135], v[216:219], v[84:87]
	v_mfma_f32_16x16x32_bf16 v[80:83], v[140:143], v[216:219], v[80:83]
	v_mfma_f32_16x16x32_bf16 v[76:79], v[132:135], v[224:227], v[76:79]
	v_mfma_f32_16x16x32_bf16 v[72:75], v[140:143], v[224:227], v[72:75]
	v_mfma_f32_16x16x32_bf16 v[68:71], v[132:135], v[232:235], v[68:71]
	v_mfma_f32_16x16x32_bf16 v[64:67], v[140:143], v[232:235], v[64:67]
	s_setprio 0
	s_setprio 1
	v_mfma_f32_16x16x32_bf16 v[28:31], v[144:147], v[160:163], v[28:31]
	v_mfma_f32_16x16x32_bf16 v[24:27], v[152:155], v[160:163], v[24:27]
	v_mfma_f32_16x16x32_bf16 v[20:23], v[144:147], v[196:199], v[20:23]
	v_mfma_f32_16x16x32_bf16 v[16:19], v[152:155], v[196:199], v[16:19]
	v_mfma_f32_16x16x32_bf16 v[12:15], v[144:147], v[220:223], v[12:15]
	v_mfma_f32_16x16x32_bf16 v[8:11], v[152:155], v[220:223], v[8:11]
	v_mfma_f32_16x16x32_bf16 v[4:7], v[144:147], v[228:231], v[4:7]
	v_mfma_f32_16x16x32_bf16 v[0:3], v[152:155], v[228:231], v[0:3]
	v_mfma_f32_16x16x32_bf16 v[28:31], v[148:151], v[164:167], v[28:31]
	v_mfma_f32_16x16x32_bf16 v[24:27], v[156:159], v[164:167], v[24:27]
	v_mfma_f32_16x16x32_bf16 v[20:23], v[148:151], v[216:219], v[20:23]
	v_mfma_f32_16x16x32_bf16 v[16:19], v[156:159], v[216:219], v[16:19]
	v_mfma_f32_16x16x32_bf16 v[12:15], v[148:151], v[224:227], v[12:15]
	v_mfma_f32_16x16x32_bf16 v[8:11], v[156:159], v[224:227], v[8:11]
	v_mfma_f32_16x16x32_bf16 v[4:7], v[148:151], v[232:235], v[4:7]
	v_mfma_f32_16x16x32_bf16 v[0:3], v[156:159], v[232:235], v[0:3]
	s_setprio 0
	s_barrier
	s_add_i32 s39, s39, 2
	s_add_u32 s25, s25, 0x10000
	s_addc_u32 s38, s38, 0
	s_add_u32 s30, s30, 0x100
	s_addc_u32 s31, s31, 0
	s_cmp_gt_u32 s39, 13
	s_cbranch_scc0 .LBB0_492
	s_and_b64 vcc, exec, s[18:19]
	s_cbranch_vccz .LBB0_503
	s_barrier
	v_lshl_add_u32 v216, s0, 8, v169
	s_cmp_gt_i32 s6, 4
	s_mov_b64 s[0:1], -1
	s_cbranch_scc1 .LBB0_504

.LBB0_1071:
	ds_read_b128 v[128:131], v170
	ds_read_b128 v[148:151], v170 offset:1024
	ds_read_b128 v[152:155], v170 offset:2048
	ds_read_b128 v[174:177], v170 offset:3072
	ds_read_b128 v[178:181], v171
	ds_read_b128 v[182:185], v171 offset:1024
	ds_read_b128 v[186:189], v171 offset:2048
	ds_read_b128 v[190:193], v171 offset:3072
	s_add_u32 s30, s28, 0xfffe0080
	s_addc_u32 s31, s29, -1
	s_cmp_eq_u32 s56, 4
	s_cselect_b32 s35, s17, s31
	s_cselect_b32 s34, s52, s30
	s_cselect_b32 s31, s19, s55
	s_cselect_b32 s30, s53, s54
	s_add_i32 m0, s25, 0xc000
	ds_read_b128 v[194:197], v172
	ds_read_b128 v[198:201], v172 offset:1024
	ds_read_b128 v[210:213], v172 offset:2048
	ds_read_b128 v[214:217], v172 offset:3072
	ds_read_b128 v[218:221], v172 offset:4096
	ds_read_b128 v[222:225], v172 offset:5120
	ds_read_b128 v[226:229], v172 offset:6144
	ds_read_b128 v[230:233], v172 offset:7168
	global_load_lds_dwordx4 v142, s[28:29]
	s_add_i32 m0, s25, 0xe000
	s_nop 0
	global_load_lds_dwordx4 v140, s[28:29]
	s_waitcnt vmcnt(8)
	s_waitcnt lgkmcnt(0)
	s_barrier
	s_setprio 1
	s_waitcnt lgkmcnt(0)
	v_mfma_f32_16x16x32_bf16 v[124:127], v[128:131], v[194:197], v[124:127]
	v_mfma_f32_16x16x32_bf16 v[120:123], v[152:155], v[194:197], v[120:123]
	v_mfma_f32_16x16x32_bf16 v[116:119], v[128:131], v[210:213], v[116:119]
	v_mfma_f32_16x16x32_bf16 v[112:115], v[152:155], v[210:213], v[112:115]
	v_mfma_f32_16x16x32_bf16 v[92:95], v[128:131], v[218:221], v[92:95]
	v_mfma_f32_16x16x32_bf16 v[88:91], v[152:155], v[218:221], v[88:91]
	v_mfma_f32_16x16x32_bf16 v[84:87], v[128:131], v[226:229], v[84:87]
	v_mfma_f32_16x16x32_bf16 v[72:75], v[152:155], v[226:229], v[72:75]
	v_mfma_f32_16x16x32_bf16 v[124:127], v[148:151], v[198:201], v[124:127]
	v_mfma_f32_16x16x32_bf16 v[120:123], v[174:177], v[198:201], v[120:123]
	v_mfma_f32_16x16x32_bf16 v[116:119], v[148:151], v[214:217], v[116:119]
	v_mfma_f32_16x16x32_bf16 v[112:115], v[174:177], v[214:217], v[112:115]
	v_mfma_f32_16x16x32_bf16 v[92:95], v[148:151], v[222:225], v[92:95]
	v_mfma_f32_16x16x32_bf16 v[88:91], v[174:177], v[222:225], v[88:91]
	v_mfma_f32_16x16x32_bf16 v[84:87], v[148:151], v[230:233], v[84:87]
	v_mfma_f32_16x16x32_bf16 v[72:75], v[174:177], v[230:233], v[72:75]
	s_setprio 0
	s_setprio 1
	v_mfma_f32_16x16x32_bf16 v[108:111], v[178:181], v[194:197], v[108:111]
	v_mfma_f32_16x16x32_bf16 v[104:107], v[186:189], v[194:197], v[104:107]
	v_mfma_f32_16x16x32_bf16 v[100:103], v[178:181], v[210:213], v[100:103]
	v_mfma_f32_16x16x32_bf16 v[96:99], v[186:189], v[210:213], v[96:99]
	v_mfma_f32_16x16x32_bf16 v[80:83], v[178:181], v[218:221], v[80:83]
	v_mfma_f32_16x16x32_bf16 v[76:79], v[186:189], v[218:221], v[76:79]
	v_mfma_f32_16x16x32_bf16 v[68:71], v[178:181], v[226:229], v[68:71]
	v_mfma_f32_16x16x32_bf16 v[64:67], v[186:189], v[226:229], v[64:67]
	v_mfma_f32_16x16x32_bf16 v[108:111], v[182:185], v[198:201], v[108:111]
	v_mfma_f32_16x16x32_bf16 v[104:107], v[190:193], v[198:201], v[104:107]
	v_mfma_f32_16x16x32_bf16 v[100:103], v[182:185], v[214:217], v[100:103]
	v_mfma_f32_16x16x32_bf16 v[96:99], v[190:193], v[214:217], v[96:99]
	v_mfma_f32_16x16x32_bf16 v[80:83], v[182:185], v[222:225], v[80:83]
	v_mfma_f32_16x16x32_bf16 v[76:79], v[190:193], v[222:225], v[76:79]
	v_mfma_f32_16x16x32_bf16 v[68:71], v[182:185], v[230:233], v[68:71]
	v_mfma_f32_16x16x32_bf16 v[64:67], v[190:193], v[230:233], v[64:67]
	s_setprio 0
	s_barrier
	s_add_i32 s57, s49, s42
	s_mov_b32 m0, s57
	ds_read_b128 v[194:197], v172 offset:16384
	ds_read_b128 v[198:201], v172 offset:17408
	ds_read_b128 v[210:213], v172 offset:18432
	ds_read_b128 v[214:217], v172 offset:19456
	ds_read_b128 v[218:221], v172 offset:20480
	ds_read_b128 v[222:225], v172 offset:21504
	ds_read_b128 v[226:229], v172 offset:22528
	ds_read_b128 v[230:233], v172 offset:23552
	global_load_lds_dwordx4 v134, s[30:31]
	s_add_i32 m0, s57, 0x2000
	s_add_u32 s58, s30, 0x4000
	s_addc_u32 s59, s31, 0
	s_add_i32 s57, s50, s42
	global_load_lds_dwordx4 v138, s[30:31]
	s_mov_b32 m0, s57
	v_lshl_add_u64 v[236:237], s[34:35], 0, v[136:137]
	global_load_lds_dwordx4 v134, s[58:59]
	s_add_i32 m0, s57, 0x2000
	s_nop 0
	global_load_lds_dwordx4 v138, s[58:59]
	v_lshl_add_u64 v[234:235], s[34:35], 0, v[132:133]
	s_mov_b32 m0, s25
	s_nop 0
	global_load_lds_dwordx4 v[234:235], off
	s_mov_b32 m0, s27
	s_nop 0
	global_load_lds_dwordx4 v[236:237], off
	s_waitcnt vmcnt(8)
	s_waitcnt lgkmcnt(0)
	s_barrier
	s_setprio 1
	s_waitcnt lgkmcnt(0)
	v_mfma_f32_16x16x32_bf16 v[60:63], v[128:131], v[194:197], v[60:63]
	v_mfma_f32_16x16x32_bf16 v[56:59], v[152:155], v[194:197], v[56:59]
	v_mfma_f32_16x16x32_bf16 v[48:51], v[128:131], v[210:213], v[48:51]
	v_mfma_f32_16x16x32_bf16 v[40:43], v[152:155], v[210:213], v[40:43]
	v_mfma_f32_16x16x32_bf16 v[32:35], v[128:131], v[218:221], v[32:35]
	v_mfma_f32_16x16x32_bf16 v[24:27], v[152:155], v[218:221], v[24:27]
	v_mfma_f32_16x16x32_bf16 v[16:19], v[128:131], v[226:229], v[16:19]
	v_mfma_f32_16x16x32_bf16 v[8:11], v[152:155], v[226:229], v[8:11]
	v_mfma_f32_16x16x32_bf16 v[60:63], v[148:151], v[198:201], v[60:63]
	v_mfma_f32_16x16x32_bf16 v[56:59], v[174:177], v[198:201], v[56:59]
	v_mfma_f32_16x16x32_bf16 v[48:51], v[148:151], v[214:217], v[48:51]
	v_mfma_f32_16x16x32_bf16 v[40:43], v[174:177], v[214:217], v[40:43]
	v_mfma_f32_16x16x32_bf16 v[32:35], v[148:151], v[222:225], v[32:35]
	v_mfma_f32_16x16x32_bf16 v[24:27], v[174:177], v[222:225], v[24:27]
	v_mfma_f32_16x16x32_bf16 v[16:19], v[148:151], v[230:233], v[16:19]
	v_mfma_f32_16x16x32_bf16 v[8:11], v[174:177], v[230:233], v[8:11]
	s_setprio 0
	s_setprio 1
	v_mfma_f32_16x16x32_bf16 v[52:55], v[178:181], v[194:197], v[52:55]
	v_mfma_f32_16x16x32_bf16 v[44:47], v[186:189], v[194:197], v[44:47]
	v_mfma_f32_16x16x32_bf16 v[36:39], v[178:181], v[210:213], v[36:39]
	v_mfma_f32_16x16x32_bf16 v[28:31], v[186:189], v[210:213], v[28:31]
	v_mfma_f32_16x16x32_bf16 v[20:23], v[178:181], v[218:221], v[20:23]
	v_mfma_f32_16x16x32_bf16 v[12:15], v[186:189], v[218:221], v[12:15]
	v_mfma_f32_16x16x32_bf16 v[4:7], v[178:181], v[226:229], v[4:7]
	v_mfma_f32_16x16x32_bf16 v[0:3], v[186:189], v[226:229], v[0:3]
	v_mfma_f32_16x16x32_bf16 v[52:55], v[182:185], v[198:201], v[52:55]
	v_mfma_f32_16x16x32_bf16 v[44:47], v[190:193], v[198:201], v[44:47]
	v_mfma_f32_16x16x32_bf16 v[36:39], v[182:185], v[214:217], v[36:39]
	v_mfma_f32_16x16x32_bf16 v[28:31], v[190:193], v[214:217], v[28:31]
	v_mfma_f32_16x16x32_bf16 v[20:23], v[182:185], v[222:225], v[20:23]
	v_mfma_f32_16x16x32_bf16 v[12:15], v[190:193], v[222:225], v[12:15]
	v_mfma_f32_16x16x32_bf16 v[4:7], v[182:185], v[230:233], v[4:7]
	v_mfma_f32_16x16x32_bf16 v[0:3], v[190:193], v[230:233], v[0:3]
	s_setprio 0
	s_barrier
	s_add_i32 s57, 0, 0x18000
	v_add_u32_e32 v173, s57, v168
	s_add_i32 s58, 0, 0x1c000
	ds_read_b128 v[128:131], v173
	ds_read_b128 v[148:151], v173 offset:1024
	ds_read_b128 v[152:155], v173 offset:2048
	ds_read_b128 v[174:177], v173 offset:3072
	v_add_u32_e32 v173, s58, v168
	ds_read_b128 v[178:181], v173
	ds_read_b128 v[182:185], v173 offset:1024
	ds_read_b128 v[186:189], v173 offset:2048
	ds_read_b128 v[190:193], v173 offset:3072
	s_add_u32 s34, s34, 0x20000
	s_addc_u32 s35, s35, 0
	s_mov_b32 m0, s43
	ds_read_b128 v[194:197], v172 offset:32768
	ds_read_b128 v[198:201], v172 offset:33792
	ds_read_b128 v[210:213], v172 offset:34816
	ds_read_b128 v[214:217], v172 offset:35840
	ds_read_b128 v[218:221], v172 offset:36864
	ds_read_b128 v[222:225], v172 offset:37888
	ds_read_b128 v[226:229], v172 offset:38912
	ds_read_b128 v[230:233], v172 offset:39936
	global_load_lds_dwordx4 v132, s[34:35]
	s_mov_b32 m0, s44
	s_nop 0
	global_load_lds_dwordx4 v136, s[34:35]
	s_waitcnt vmcnt(8)
	s_waitcnt lgkmcnt(0)
	s_barrier
	s_setprio 1
	s_waitcnt lgkmcnt(0)
	v_mfma_f32_16x16x32_bf16 v[124:127], v[128:131], v[194:197], v[124:127]
	v_mfma_f32_16x16x32_bf16 v[120:123], v[152:155], v[194:197], v[120:123]
	v_mfma_f32_16x16x32_bf16 v[116:119], v[128:131], v[210:213], v[116:119]
	v_mfma_f32_16x16x32_bf16 v[112:115], v[152:155], v[210:213], v[112:115]
	v_mfma_f32_16x16x32_bf16 v[92:95], v[128:131], v[218:221], v[92:95]
	v_mfma_f32_16x16x32_bf16 v[88:91], v[152:155], v[218:221], v[88:91]
	v_mfma_f32_16x16x32_bf16 v[84:87], v[128:131], v[226:229], v[84:87]
	v_mfma_f32_16x16x32_bf16 v[72:75], v[152:155], v[226:229], v[72:75]
	v_mfma_f32_16x16x32_bf16 v[124:127], v[148:151], v[198:201], v[124:127]
	v_mfma_f32_16x16x32_bf16 v[120:123], v[174:177], v[198:201], v[120:123]
	v_mfma_f32_16x16x32_bf16 v[116:119], v[148:151], v[214:217], v[116:119]
	v_mfma_f32_16x16x32_bf16 v[112:115], v[174:177], v[214:217], v[112:115]
	v_mfma_f32_16x16x32_bf16 v[92:95], v[148:151], v[222:225], v[92:95]
	v_mfma_f32_16x16x32_bf16 v[88:91], v[174:177], v[222:225], v[88:91]
	v_mfma_f32_16x16x32_bf16 v[84:87], v[148:151], v[230:233], v[84:87]
	v_mfma_f32_16x16x32_bf16 v[72:75], v[174:177], v[230:233], v[72:75]
	s_setprio 0
	s_setprio 1
	v_mfma_f32_16x16x32_bf16 v[108:111], v[178:181], v[194:197], v[108:111]
	v_mfma_f32_16x16x32_bf16 v[104:107], v[186:189], v[194:197], v[104:107]
	v_mfma_f32_16x16x32_bf16 v[100:103], v[178:181], v[210:213], v[100:103]
	v_mfma_f32_16x16x32_bf16 v[96:99], v[186:189], v[210:213], v[96:99]
	v_mfma_f32_16x16x32_bf16 v[80:83], v[178:181], v[218:221], v[80:83]
	v_mfma_f32_16x16x32_bf16 v[76:79], v[186:189], v[218:221], v[76:79]
	v_mfma_f32_16x16x32_bf16 v[68:71], v[178:181], v[226:229], v[68:71]
	v_mfma_f32_16x16x32_bf16 v[64:67], v[186:189], v[226:229], v[64:67]
	v_mfma_f32_16x16x32_bf16 v[108:111], v[182:185], v[198:201], v[108:111]
	v_mfma_f32_16x16x32_bf16 v[104:107], v[190:193], v[198:201], v[104:107]
	v_mfma_f32_16x16x32_bf16 v[100:103], v[182:185], v[214:217], v[100:103]
	v_mfma_f32_16x16x32_bf16 v[96:99], v[190:193], v[214:217], v[96:99]
	v_mfma_f32_16x16x32_bf16 v[80:83], v[182:185], v[222:225], v[80:83]
	v_mfma_f32_16x16x32_bf16 v[76:79], v[190:193], v[222:225], v[76:79]
	v_mfma_f32_16x16x32_bf16 v[68:71], v[182:185], v[230:233], v[68:71]
	v_mfma_f32_16x16x32_bf16 v[64:67], v[190:193], v[230:233], v[64:67]
	s_setprio 0
	s_barrier
	s_add_u32 s34, s30, 0x8000
	s_addc_u32 s35, s31, 0
	s_add_i32 s57, s57, s42
	s_mov_b32 m0, s57
	ds_read_b128 v[194:197], v172 offset:49152
	ds_read_b128 v[198:201], v172 offset:50176
	ds_read_b128 v[210:213], v172 offset:51200
	ds_read_b128 v[214:217], v172 offset:52224
	ds_read_b128 v[218:221], v172 offset:53248
	ds_read_b128 v[222:225], v172 offset:54272
	ds_read_b128 v[226:229], v172 offset:55296
	ds_read_b128 v[230:233], v172 offset:56320
	global_load_lds_dwordx4 v134, s[34:35]
	s_add_i32 m0, s57, 0x2000
	s_add_u32 s30, s30, 0xc000
	v_lshl_add_u64 v[238:239], s[34:35], 0, v[138:139]
	s_addc_u32 s31, s31, 0
	s_add_i32 s34, s58, s42
	global_load_lds_dwordx4 v[238:239], off
	s_mov_b32 m0, s34
	v_lshl_add_u64 v[234:235], v[234:235], 0, s[12:13]
	global_load_lds_dwordx4 v134, s[30:31]
	s_add_i32 m0, s34, 0x2000
	s_nop 0
	global_load_lds_dwordx4 v138, s[30:31]
	s_mov_b32 m0, s46
	s_nop 0
	global_load_lds_dwordx4 v[234:235], off
	v_lshl_add_u64 v[234:235], v[236:237], 0, s[12:13]
	s_mov_b32 m0, s47
	s_nop 0
	global_load_lds_dwordx4 v[234:235], off
	s_waitcnt vmcnt(8)
	s_waitcnt lgkmcnt(0)
	s_barrier
	s_setprio 1
	s_waitcnt lgkmcnt(0)
	v_mfma_f32_16x16x32_bf16 v[60:63], v[128:131], v[194:197], v[60:63]
	v_mfma_f32_16x16x32_bf16 v[56:59], v[152:155], v[194:197], v[56:59]
	v_mfma_f32_16x16x32_bf16 v[48:51], v[128:131], v[210:213], v[48:51]
	v_mfma_f32_16x16x32_bf16 v[40:43], v[152:155], v[210:213], v[40:43]
	v_mfma_f32_16x16x32_bf16 v[32:35], v[128:131], v[218:221], v[32:35]
	v_mfma_f32_16x16x32_bf16 v[24:27], v[152:155], v[218:221], v[24:27]
	v_mfma_f32_16x16x32_bf16 v[16:19], v[128:131], v[226:229], v[16:19]
	v_mfma_f32_16x16x32_bf16 v[8:11], v[152:155], v[226:229], v[8:11]
	v_mfma_f32_16x16x32_bf16 v[60:63], v[148:151], v[198:201], v[60:63]
	v_mfma_f32_16x16x32_bf16 v[56:59], v[174:177], v[198:201], v[56:59]
	v_mfma_f32_16x16x32_bf16 v[48:51], v[148:151], v[214:217], v[48:51]
	v_mfma_f32_16x16x32_bf16 v[40:43], v[174:177], v[214:217], v[40:43]
	v_mfma_f32_16x16x32_bf16 v[32:35], v[148:151], v[222:225], v[32:35]
	v_mfma_f32_16x16x32_bf16 v[24:27], v[174:177], v[222:225], v[24:27]
	v_mfma_f32_16x16x32_bf16 v[16:19], v[148:151], v[230:233], v[16:19]
	v_mfma_f32_16x16x32_bf16 v[8:11], v[174:177], v[230:233], v[8:11]
	s_setprio 0
	s_setprio 1
	v_mfma_f32_16x16x32_bf16 v[52:55], v[178:181], v[194:197], v[52:55]
	v_mfma_f32_16x16x32_bf16 v[44:47], v[186:189], v[194:197], v[44:47]
	v_mfma_f32_16x16x32_bf16 v[36:39], v[178:181], v[210:213], v[36:39]
	v_mfma_f32_16x16x32_bf16 v[28:31], v[186:189], v[210:213], v[28:31]
	v_mfma_f32_16x16x32_bf16 v[20:23], v[178:181], v[218:221], v[20:23]
	v_mfma_f32_16x16x32_bf16 v[12:15], v[186:189], v[218:221], v[12:15]
	v_mfma_f32_16x16x32_bf16 v[4:7], v[178:181], v[226:229], v[4:7]
	v_mfma_f32_16x16x32_bf16 v[0:3], v[186:189], v[226:229], v[0:3]
	v_mfma_f32_16x16x32_bf16 v[52:55], v[182:185], v[198:201], v[52:55]
	v_mfma_f32_16x16x32_bf16 v[44:47], v[190:193], v[198:201], v[44:47]
	v_mfma_f32_16x16x32_bf16 v[36:39], v[182:185], v[214:217], v[36:39]
	v_mfma_f32_16x16x32_bf16 v[28:31], v[190:193], v[214:217], v[28:31]
	v_mfma_f32_16x16x32_bf16 v[20:23], v[182:185], v[222:225], v[20:23]
	v_mfma_f32_16x16x32_bf16 v[12:15], v[190:193], v[222:225], v[12:15]
	v_mfma_f32_16x16x32_bf16 v[4:7], v[182:185], v[230:233], v[4:7]
	v_mfma_f32_16x16x32_bf16 v[0:3], v[190:193], v[230:233], v[0:3]
	s_setprio 0
	s_barrier
	s_add_i32 s56, s56, 2
	s_add_u32 s54, s54, 0x10000
	s_addc_u32 s55, s55, 0
	s_add_u32 s28, s28, 0x100
	s_addc_u32 s29, s29, 0
	s_cmp_gt_u32 s56, 5
	s_cbranch_scc0 .LBB0_1071
	s_and_b64 vcc, exec, s[14:15]
	s_cbranch_vccz .LBB0_1074
	s_barrier

.LBB0_1095:
	ds_read_b128 v[144:147], v155
	ds_read_b128 v[148:151], v155 offset:1024
	ds_read_b128 v[158:161], v155 offset:2048
	ds_read_b128 v[162:165], v155 offset:3072
	ds_read_b128 v[166:169], v156
	ds_read_b128 v[170:173], v156 offset:1024
	ds_read_b128 v[174:177], v156 offset:2048
	ds_read_b128 v[178:181], v156 offset:3072
	s_add_u32 s28, s26, 0xfffe0080
	s_addc_u32 s29, s27, -1
	s_cmp_eq_u32 s54, 4
	s_cselect_b32 s31, s15, s29
	s_cselect_b32 s30, s50, s28
	s_cselect_b32 s29, s17, s53
	s_cselect_b32 s28, s51, s52
	s_add_i32 m0, s23, 0xc000
	ds_read_b128 v[182:185], v157
	ds_read_b128 v[186:189], v157 offset:1024
	ds_read_b128 v[190:193], v157 offset:2048
	ds_read_b128 v[194:197], v157 offset:3072
	ds_read_b128 v[198:201], v157 offset:4096
	ds_read_b128 v[210:213], v157 offset:5120
	ds_read_b128 v[214:217], v157 offset:6144
	ds_read_b128 v[218:221], v157 offset:7168
	global_load_lds_dwordx4 v130, s[26:27]
	s_add_i32 m0, s23, 0xe000
	s_nop 0
	global_load_lds_dwordx4 v128, s[26:27]
	s_waitcnt vmcnt(8)
	s_waitcnt lgkmcnt(0)
	s_barrier
	s_setprio 1
	s_waitcnt lgkmcnt(0)
	v_mfma_f32_16x16x32_bf16 v[124:127], v[144:147], v[182:185], v[124:127]
	v_mfma_f32_16x16x32_bf16 v[120:123], v[158:161], v[182:185], v[120:123]
	v_mfma_f32_16x16x32_bf16 v[112:115], v[144:147], v[190:193], v[112:115]
	v_mfma_f32_16x16x32_bf16 v[104:107], v[158:161], v[190:193], v[104:107]
	v_mfma_f32_16x16x32_bf16 v[92:95], v[144:147], v[198:201], v[92:95]
	v_mfma_f32_16x16x32_bf16 v[88:91], v[158:161], v[198:201], v[88:91]
	v_mfma_f32_16x16x32_bf16 v[80:83], v[144:147], v[214:217], v[80:83]
	v_mfma_f32_16x16x32_bf16 v[72:75], v[158:161], v[214:217], v[72:75]
	v_mfma_f32_16x16x32_bf16 v[124:127], v[148:151], v[186:189], v[124:127]
	v_mfma_f32_16x16x32_bf16 v[120:123], v[162:165], v[186:189], v[120:123]
	v_mfma_f32_16x16x32_bf16 v[112:115], v[148:151], v[194:197], v[112:115]
	v_mfma_f32_16x16x32_bf16 v[104:107], v[162:165], v[194:197], v[104:107]
	v_mfma_f32_16x16x32_bf16 v[92:95], v[148:151], v[210:213], v[92:95]
	v_mfma_f32_16x16x32_bf16 v[88:91], v[162:165], v[210:213], v[88:91]
	v_mfma_f32_16x16x32_bf16 v[80:83], v[148:151], v[218:221], v[80:83]
	v_mfma_f32_16x16x32_bf16 v[72:75], v[162:165], v[218:221], v[72:75]
	s_setprio 0
	s_setprio 1
	v_mfma_f32_16x16x32_bf16 v[116:119], v[166:169], v[182:185], v[116:119]
	v_mfma_f32_16x16x32_bf16 v[108:111], v[174:177], v[182:185], v[108:111]
	v_mfma_f32_16x16x32_bf16 v[100:103], v[166:169], v[190:193], v[100:103]
	v_mfma_f32_16x16x32_bf16 v[96:99], v[174:177], v[190:193], v[96:99]
	v_mfma_f32_16x16x32_bf16 v[84:87], v[166:169], v[198:201], v[84:87]
	v_mfma_f32_16x16x32_bf16 v[76:79], v[174:177], v[198:201], v[76:79]
	v_mfma_f32_16x16x32_bf16 v[68:71], v[166:169], v[214:217], v[68:71]
	v_mfma_f32_16x16x32_bf16 v[64:67], v[174:177], v[214:217], v[64:67]
	v_mfma_f32_16x16x32_bf16 v[116:119], v[170:173], v[186:189], v[116:119]
	v_mfma_f32_16x16x32_bf16 v[108:111], v[178:181], v[186:189], v[108:111]
	v_mfma_f32_16x16x32_bf16 v[100:103], v[170:173], v[194:197], v[100:103]
	v_mfma_f32_16x16x32_bf16 v[96:99], v[178:181], v[194:197], v[96:99]
	v_mfma_f32_16x16x32_bf16 v[84:87], v[170:173], v[210:213], v[84:87]
	v_mfma_f32_16x16x32_bf16 v[76:79], v[178:181], v[210:213], v[76:79]
	v_mfma_f32_16x16x32_bf16 v[68:71], v[170:173], v[218:221], v[68:71]
	v_mfma_f32_16x16x32_bf16 v[64:67], v[178:181], v[218:221], v[64:67]
	s_setprio 0
	s_barrier
	s_add_i32 s55, s47, s40
	s_mov_b32 m0, s55
	ds_read_b128 v[182:185], v157 offset:16384
	ds_read_b128 v[186:189], v157 offset:17408
	ds_read_b128 v[190:193], v157 offset:18432
	ds_read_b128 v[194:197], v157 offset:19456
	ds_read_b128 v[198:201], v157 offset:20480
	ds_read_b128 v[210:213], v157 offset:21504
	ds_read_b128 v[214:217], v157 offset:22528
	ds_read_b128 v[218:221], v157 offset:23552
	global_load_lds_dwordx4 v134, s[28:29]
	s_add_i32 m0, s55, 0x2000
	s_add_u32 s56, s28, 0x4000
	s_addc_u32 s57, s29, 0
	s_add_i32 s55, s48, s40
	global_load_lds_dwordx4 v138, s[28:29]
	s_mov_b32 m0, s55
	v_lshl_add_u64 v[224:225], s[30:31], 0, v[136:137]
	global_load_lds_dwordx4 v134, s[56:57]
	s_add_i32 m0, s55, 0x2000
	s_nop 0
	global_load_lds_dwordx4 v138, s[56:57]
	v_lshl_add_u64 v[222:223], s[30:31], 0, v[132:133]
	s_mov_b32 m0, s23
	s_nop 0
	global_load_lds_dwordx4 v[222:223], off
	s_mov_b32 m0, s25
	s_nop 0
	global_load_lds_dwordx4 v[224:225], off
	s_waitcnt vmcnt(8)
	s_waitcnt lgkmcnt(0)
	s_barrier
	s_setprio 1
	s_waitcnt lgkmcnt(0)
	v_mfma_f32_16x16x32_bf16 v[60:63], v[144:147], v[182:185], v[60:63]
	v_mfma_f32_16x16x32_bf16 v[56:59], v[158:161], v[182:185], v[56:59]
	v_mfma_f32_16x16x32_bf16 v[48:51], v[144:147], v[190:193], v[48:51]
	v_mfma_f32_16x16x32_bf16 v[40:43], v[158:161], v[190:193], v[40:43]
	v_mfma_f32_16x16x32_bf16 v[28:31], v[144:147], v[198:201], v[28:31]
	v_mfma_f32_16x16x32_bf16 v[24:27], v[158:161], v[198:201], v[24:27]
	v_mfma_f32_16x16x32_bf16 v[16:19], v[144:147], v[214:217], v[16:19]
	v_mfma_f32_16x16x32_bf16 v[8:11], v[158:161], v[214:217], v[8:11]
	v_mfma_f32_16x16x32_bf16 v[60:63], v[148:151], v[186:189], v[60:63]
	v_mfma_f32_16x16x32_bf16 v[56:59], v[162:165], v[186:189], v[56:59]
	v_mfma_f32_16x16x32_bf16 v[48:51], v[148:151], v[194:197], v[48:51]
	v_mfma_f32_16x16x32_bf16 v[40:43], v[162:165], v[194:197], v[40:43]
	v_mfma_f32_16x16x32_bf16 v[28:31], v[148:151], v[210:213], v[28:31]
	v_mfma_f32_16x16x32_bf16 v[24:27], v[162:165], v[210:213], v[24:27]
	v_mfma_f32_16x16x32_bf16 v[16:19], v[148:151], v[218:221], v[16:19]
	v_mfma_f32_16x16x32_bf16 v[8:11], v[162:165], v[218:221], v[8:11]
	s_setprio 0
	s_setprio 1
	v_mfma_f32_16x16x32_bf16 v[52:55], v[166:169], v[182:185], v[52:55]
	v_mfma_f32_16x16x32_bf16 v[44:47], v[174:177], v[182:185], v[44:47]
	v_mfma_f32_16x16x32_bf16 v[36:39], v[166:169], v[190:193], v[36:39]
	v_mfma_f32_16x16x32_bf16 v[32:35], v[174:177], v[190:193], v[32:35]
	v_mfma_f32_16x16x32_bf16 v[20:23], v[166:169], v[198:201], v[20:23]
	v_mfma_f32_16x16x32_bf16 v[12:15], v[174:177], v[198:201], v[12:15]
	v_mfma_f32_16x16x32_bf16 v[4:7], v[166:169], v[214:217], v[4:7]
	v_mfma_f32_16x16x32_bf16 v[0:3], v[174:177], v[214:217], v[0:3]
	v_mfma_f32_16x16x32_bf16 v[52:55], v[170:173], v[186:189], v[52:55]
	v_mfma_f32_16x16x32_bf16 v[44:47], v[178:181], v[186:189], v[44:47]
	v_mfma_f32_16x16x32_bf16 v[36:39], v[170:173], v[194:197], v[36:39]
	v_mfma_f32_16x16x32_bf16 v[32:35], v[178:181], v[194:197], v[32:35]
	v_mfma_f32_16x16x32_bf16 v[20:23], v[170:173], v[210:213], v[20:23]
	v_mfma_f32_16x16x32_bf16 v[12:15], v[178:181], v[210:213], v[12:15]
	v_mfma_f32_16x16x32_bf16 v[4:7], v[170:173], v[218:221], v[4:7]
	v_mfma_f32_16x16x32_bf16 v[0:3], v[178:181], v[218:221], v[0:3]
	s_setprio 0
	s_barrier
	s_add_i32 s55, 0, 0x18000
	s_add_i32 s56, 0, 0x1c000
	v_add_u32_e32 v162, s55, v153
	v_add_u32_e32 v178, s56, v153
	ds_read_b128 v[144:147], v162
	ds_read_b128 v[148:151], v162 offset:1024
	ds_read_b128 v[158:161], v162 offset:2048
	ds_read_b128 v[162:165], v162 offset:3072
	ds_read_b128 v[166:169], v178
	ds_read_b128 v[170:173], v178 offset:1024
	ds_read_b128 v[174:177], v178 offset:2048
	ds_read_b128 v[178:181], v178 offset:3072
	s_add_u32 s30, s30, 0x20000
	s_addc_u32 s31, s31, 0
	s_mov_b32 m0, s41
	ds_read_b128 v[182:185], v157 offset:32768
	ds_read_b128 v[186:189], v157 offset:33792
	ds_read_b128 v[190:193], v157 offset:34816
	ds_read_b128 v[194:197], v157 offset:35840
	ds_read_b128 v[198:201], v157 offset:36864
	ds_read_b128 v[210:213], v157 offset:37888
	ds_read_b128 v[214:217], v157 offset:38912
	ds_read_b128 v[218:221], v157 offset:39936
	global_load_lds_dwordx4 v132, s[30:31]
	s_mov_b32 m0, s42
	s_nop 0
	global_load_lds_dwordx4 v136, s[30:31]
	s_waitcnt vmcnt(8)
	s_waitcnt lgkmcnt(0)
	s_barrier
	s_setprio 1
	s_waitcnt lgkmcnt(0)
	v_mfma_f32_16x16x32_bf16 v[124:127], v[144:147], v[182:185], v[124:127]
	v_mfma_f32_16x16x32_bf16 v[120:123], v[158:161], v[182:185], v[120:123]
	v_mfma_f32_16x16x32_bf16 v[112:115], v[144:147], v[190:193], v[112:115]
	v_mfma_f32_16x16x32_bf16 v[104:107], v[158:161], v[190:193], v[104:107]
	v_mfma_f32_16x16x32_bf16 v[92:95], v[144:147], v[198:201], v[92:95]
	v_mfma_f32_16x16x32_bf16 v[88:91], v[158:161], v[198:201], v[88:91]
	v_mfma_f32_16x16x32_bf16 v[80:83], v[144:147], v[214:217], v[80:83]
	v_mfma_f32_16x16x32_bf16 v[72:75], v[158:161], v[214:217], v[72:75]
	v_mfma_f32_16x16x32_bf16 v[124:127], v[148:151], v[186:189], v[124:127]
	v_mfma_f32_16x16x32_bf16 v[120:123], v[162:165], v[186:189], v[120:123]
	v_mfma_f32_16x16x32_bf16 v[112:115], v[148:151], v[194:197], v[112:115]
	v_mfma_f32_16x16x32_bf16 v[104:107], v[162:165], v[194:197], v[104:107]
	v_mfma_f32_16x16x32_bf16 v[92:95], v[148:151], v[210:213], v[92:95]
	v_mfma_f32_16x16x32_bf16 v[88:91], v[162:165], v[210:213], v[88:91]
	v_mfma_f32_16x16x32_bf16 v[80:83], v[148:151], v[218:221], v[80:83]
	v_mfma_f32_16x16x32_bf16 v[72:75], v[162:165], v[218:221], v[72:75]
	s_setprio 0
	s_setprio 1
	v_mfma_f32_16x16x32_bf16 v[116:119], v[166:169], v[182:185], v[116:119]
	v_mfma_f32_16x16x32_bf16 v[108:111], v[174:177], v[182:185], v[108:111]
	v_mfma_f32_16x16x32_bf16 v[100:103], v[166:169], v[190:193], v[100:103]
	v_mfma_f32_16x16x32_bf16 v[96:99], v[174:177], v[190:193], v[96:99]
	v_mfma_f32_16x16x32_bf16 v[84:87], v[166:169], v[198:201], v[84:87]
	v_mfma_f32_16x16x32_bf16 v[76:79], v[174:177], v[198:201], v[76:79]
	v_mfma_f32_16x16x32_bf16 v[68:71], v[166:169], v[214:217], v[68:71]
	v_mfma_f32_16x16x32_bf16 v[64:67], v[174:177], v[214:217], v[64:67]
	v_mfma_f32_16x16x32_bf16 v[116:119], v[170:173], v[186:189], v[116:119]
	v_mfma_f32_16x16x32_bf16 v[108:111], v[178:181], v[186:189], v[108:111]
	v_mfma_f32_16x16x32_bf16 v[100:103], v[170:173], v[194:197], v[100:103]
	v_mfma_f32_16x16x32_bf16 v[96:99], v[178:181], v[194:197], v[96:99]
	v_mfma_f32_16x16x32_bf16 v[84:87], v[170:173], v[210:213], v[84:87]
	v_mfma_f32_16x16x32_bf16 v[76:79], v[178:181], v[210:213], v[76:79]
	v_mfma_f32_16x16x32_bf16 v[68:71], v[170:173], v[218:221], v[68:71]
	v_mfma_f32_16x16x32_bf16 v[64:67], v[178:181], v[218:221], v[64:67]
	s_setprio 0
	s_barrier
	s_add_u32 s30, s28, 0x8000
	s_addc_u32 s31, s29, 0
	s_add_i32 s55, s55, s40
	s_mov_b32 m0, s55
	ds_read_b128 v[182:185], v157 offset:49152
	ds_read_b128 v[186:189], v157 offset:50176
	ds_read_b128 v[190:193], v157 offset:51200
	ds_read_b128 v[194:197], v157 offset:52224
	ds_read_b128 v[198:201], v157 offset:53248
	ds_read_b128 v[210:213], v157 offset:54272
	ds_read_b128 v[214:217], v157 offset:55296
	ds_read_b128 v[218:221], v157 offset:56320
	global_load_lds_dwordx4 v134, s[30:31]
	s_add_i32 m0, s55, 0x2000
	s_add_u32 s28, s28, 0xc000
	v_lshl_add_u64 v[226:227], s[30:31], 0, v[138:139]
	s_addc_u32 s29, s29, 0
	s_add_i32 s30, s56, s40
	global_load_lds_dwordx4 v[226:227], off
	s_mov_b32 m0, s30
	v_lshl_add_u64 v[222:223], v[222:223], 0, s[8:9]
	global_load_lds_dwordx4 v134, s[28:29]
	s_add_i32 m0, s30, 0x2000
	s_nop 0
	global_load_lds_dwordx4 v138, s[28:29]
	s_mov_b32 m0, s44
	s_nop 0
	global_load_lds_dwordx4 v[222:223], off
	v_lshl_add_u64 v[222:223], v[224:225], 0, s[8:9]
	s_mov_b32 m0, s45
	s_nop 0
	global_load_lds_dwordx4 v[222:223], off
	s_waitcnt vmcnt(8)
	s_waitcnt lgkmcnt(0)
	s_barrier
	s_setprio 1
	s_waitcnt lgkmcnt(0)
	v_mfma_f32_16x16x32_bf16 v[60:63], v[144:147], v[182:185], v[60:63]
	v_mfma_f32_16x16x32_bf16 v[56:59], v[158:161], v[182:185], v[56:59]
	v_mfma_f32_16x16x32_bf16 v[48:51], v[144:147], v[190:193], v[48:51]
	v_mfma_f32_16x16x32_bf16 v[40:43], v[158:161], v[190:193], v[40:43]
	v_mfma_f32_16x16x32_bf16 v[28:31], v[144:147], v[198:201], v[28:31]
	v_mfma_f32_16x16x32_bf16 v[24:27], v[158:161], v[198:201], v[24:27]
	v_mfma_f32_16x16x32_bf16 v[16:19], v[144:147], v[214:217], v[16:19]
	v_mfma_f32_16x16x32_bf16 v[8:11], v[158:161], v[214:217], v[8:11]
	v_mfma_f32_16x16x32_bf16 v[60:63], v[148:151], v[186:189], v[60:63]
	v_mfma_f32_16x16x32_bf16 v[56:59], v[162:165], v[186:189], v[56:59]
	v_mfma_f32_16x16x32_bf16 v[48:51], v[148:151], v[194:197], v[48:51]
	v_mfma_f32_16x16x32_bf16 v[40:43], v[162:165], v[194:197], v[40:43]
	v_mfma_f32_16x16x32_bf16 v[28:31], v[148:151], v[210:213], v[28:31]
	v_mfma_f32_16x16x32_bf16 v[24:27], v[162:165], v[210:213], v[24:27]
	v_mfma_f32_16x16x32_bf16 v[16:19], v[148:151], v[218:221], v[16:19]
	v_mfma_f32_16x16x32_bf16 v[8:11], v[162:165], v[218:221], v[8:11]
	s_setprio 0
	s_setprio 1
	v_mfma_f32_16x16x32_bf16 v[52:55], v[166:169], v[182:185], v[52:55]
	v_mfma_f32_16x16x32_bf16 v[44:47], v[174:177], v[182:185], v[44:47]
	v_mfma_f32_16x16x32_bf16 v[36:39], v[166:169], v[190:193], v[36:39]
	v_mfma_f32_16x16x32_bf16 v[32:35], v[174:177], v[190:193], v[32:35]
	v_mfma_f32_16x16x32_bf16 v[20:23], v[166:169], v[198:201], v[20:23]
	v_mfma_f32_16x16x32_bf16 v[12:15], v[174:177], v[198:201], v[12:15]
	v_mfma_f32_16x16x32_bf16 v[4:7], v[166:169], v[214:217], v[4:7]
	v_mfma_f32_16x16x32_bf16 v[0:3], v[174:177], v[214:217], v[0:3]
	v_mfma_f32_16x16x32_bf16 v[52:55], v[170:173], v[186:189], v[52:55]
	v_mfma_f32_16x16x32_bf16 v[44:47], v[178:181], v[186:189], v[44:47]
	v_mfma_f32_16x16x32_bf16 v[36:39], v[170:173], v[194:197], v[36:39]
	v_mfma_f32_16x16x32_bf16 v[32:35], v[178:181], v[194:197], v[32:35]
	v_mfma_f32_16x16x32_bf16 v[20:23], v[170:173], v[210:213], v[20:23]
	v_mfma_f32_16x16x32_bf16 v[12:15], v[178:181], v[210:213], v[12:15]
	v_mfma_f32_16x16x32_bf16 v[4:7], v[170:173], v[218:221], v[4:7]
	v_mfma_f32_16x16x32_bf16 v[0:3], v[178:181], v[218:221], v[0:3]
	s_setprio 0
	s_barrier
	s_add_i32 s54, s54, 2
	s_add_u32 s52, s52, 0x10000
	s_addc_u32 s53, s53, 0
	s_add_u32 s26, s26, 0x100
	s_addc_u32 s27, s27, 0
	s_cmp_gt_u32 s54, 5
	s_cbranch_scc0 .LBB0_1095
	s_and_b64 vcc, exec, s[10:11]
	s_cbranch_vccz .LBB0_1098
	s_barrier

.LBB0_1171:
	v_add_u32_e32 v168, s77, v182
	v_add_u32_e32 v204, s78, v182
	ds_read_b128 v[156:159], v168
	ds_read_b128 v[160:163], v168 offset:1024
	ds_read_b128 v[164:167], v168 offset:2048
	ds_read_b128 v[168:171], v168 offset:3072
	ds_read_b128 v[172:175], v204
	ds_read_b128 v[176:179], v204 offset:1024
	ds_read_b128 v[212:215], v204 offset:2048
	ds_read_b128 v[216:219], v204 offset:3072
	s_add_u32 s48, s46, 0xfffc0080
	s_addc_u32 s49, s47, -1
	s_cmp_eq_u32 s54, 12
	s_cselect_b32 s51, s35, s49
	s_cselect_b32 s50, s43, s48
	s_cselect_b32 s49, s37, s53
	s_cselect_b32 s48, s45, s52
	s_add_i32 m0, s65, 0xc000
	ds_read_b128 v[220:223], v199
	ds_read_b128 v[224:227], v199 offset:1024
	ds_read_b128 v[228:231], v199 offset:2048
	ds_read_b128 v[232:235], v199 offset:3072
	ds_read_b128 v[236:239], v199 offset:4096
	ds_read_b128 v[240:243], v199 offset:5120
	ds_read_b128 v[244:247], v199 offset:6144
	ds_read_b128 v[248:251], v199 offset:7168
	global_load_lds_dwordx4 v154, s[46:47]
	s_add_i32 m0, s65, 0xe000
	s_nop 0
	global_load_lds_dwordx4 v152, s[46:47]
	s_waitcnt vmcnt(8)
	s_waitcnt lgkmcnt(0)
	s_barrier
	s_setprio 1
	s_waitcnt lgkmcnt(0)
	v_mfma_f32_16x16x32_bf16 v[124:127], v[156:159], v[220:223], v[124:127]
	v_mfma_f32_16x16x32_bf16 v[120:123], v[164:167], v[220:223], v[120:123]
	v_mfma_f32_16x16x32_bf16 v[116:119], v[156:159], v[228:231], v[116:119]
	v_mfma_f32_16x16x32_bf16 v[112:115], v[164:167], v[228:231], v[112:115]
	v_mfma_f32_16x16x32_bf16 v[92:95], v[156:159], v[236:239], v[92:95]
	v_mfma_f32_16x16x32_bf16 v[88:91], v[164:167], v[236:239], v[88:91]
	v_mfma_f32_16x16x32_bf16 v[84:87], v[156:159], v[244:247], v[84:87]
	v_mfma_f32_16x16x32_bf16 v[80:83], v[164:167], v[244:247], v[80:83]
	v_mfma_f32_16x16x32_bf16 v[124:127], v[160:163], v[224:227], v[124:127]
	v_mfma_f32_16x16x32_bf16 v[120:123], v[168:171], v[224:227], v[120:123]
	v_mfma_f32_16x16x32_bf16 v[116:119], v[160:163], v[232:235], v[116:119]
	v_mfma_f32_16x16x32_bf16 v[112:115], v[168:171], v[232:235], v[112:115]
	v_mfma_f32_16x16x32_bf16 v[92:95], v[160:163], v[240:243], v[92:95]
	v_mfma_f32_16x16x32_bf16 v[88:91], v[168:171], v[240:243], v[88:91]
	v_mfma_f32_16x16x32_bf16 v[84:87], v[160:163], v[248:251], v[84:87]
	v_mfma_f32_16x16x32_bf16 v[80:83], v[168:171], v[248:251], v[80:83]
	s_setprio 0
	s_setprio 1
	v_mfma_f32_16x16x32_bf16 v[108:111], v[172:175], v[220:223], v[108:111]
	v_mfma_f32_16x16x32_bf16 v[104:107], v[212:215], v[220:223], v[104:107]
	v_mfma_f32_16x16x32_bf16 v[100:103], v[172:175], v[228:231], v[100:103]
	v_mfma_f32_16x16x32_bf16 v[96:99], v[212:215], v[228:231], v[96:99]
	v_mfma_f32_16x16x32_bf16 v[76:79], v[172:175], v[236:239], v[76:79]
	v_mfma_f32_16x16x32_bf16 v[72:75], v[212:215], v[236:239], v[72:75]
	v_mfma_f32_16x16x32_bf16 v[68:71], v[172:175], v[244:247], v[68:71]
	v_mfma_f32_16x16x32_bf16 v[64:67], v[212:215], v[244:247], v[64:67]
	v_mfma_f32_16x16x32_bf16 v[108:111], v[176:179], v[224:227], v[108:111]
	v_mfma_f32_16x16x32_bf16 v[104:107], v[216:219], v[224:227], v[104:107]
	v_mfma_f32_16x16x32_bf16 v[100:103], v[176:179], v[232:235], v[100:103]
	v_mfma_f32_16x16x32_bf16 v[96:99], v[216:219], v[232:235], v[96:99]
	v_mfma_f32_16x16x32_bf16 v[76:79], v[176:179], v[240:243], v[76:79]
	v_mfma_f32_16x16x32_bf16 v[72:75], v[216:219], v[240:243], v[72:75]
	v_mfma_f32_16x16x32_bf16 v[68:71], v[176:179], v[248:251], v[68:71]
	v_mfma_f32_16x16x32_bf16 v[64:67], v[216:219], v[248:251], v[64:67]
	s_setprio 0
	s_barrier
	s_add_i32 s55, s77, s64
	s_mov_b32 m0, s55
	ds_read_b128 v[220:223], v199 offset:16384
	ds_read_b128 v[224:227], v199 offset:17408
	ds_read_b128 v[228:231], v199 offset:18432
	ds_read_b128 v[232:235], v199 offset:19456
	ds_read_b128 v[236:239], v199 offset:20480
	ds_read_b128 v[240:243], v199 offset:21504
	ds_read_b128 v[244:247], v199 offset:22528
	ds_read_b128 v[248:251], v199 offset:23552
	global_load_lds_dwordx4 v130, s[48:49]
	s_add_i32 m0, s55, 0x2000
	s_add_u32 s56, s48, 0x4000
	s_addc_u32 s57, s49, 0
	s_add_i32 s55, s78, s64
	global_load_lds_dwordx4 v134, s[48:49]
	s_mov_b32 m0, s55
	v_lshl_add_u64 v[204:205], s[50:51], 0, v[132:133]
	global_load_lds_dwordx4 v130, s[56:57]
	s_add_i32 m0, s55, 0x2000
	s_nop 0
	global_load_lds_dwordx4 v134, s[56:57]
	v_lshl_add_u64 v[252:253], s[50:51], 0, v[128:129]
	s_mov_b32 m0, s65
	s_nop 0
	global_load_lds_dwordx4 v[252:253], off
	s_mov_b32 m0, s66
	s_nop 0
	global_load_lds_dwordx4 v[204:205], off
	s_waitcnt vmcnt(8)
	s_waitcnt lgkmcnt(0)
	s_barrier
	s_setprio 1
	s_waitcnt lgkmcnt(0)
	v_mfma_f32_16x16x32_bf16 v[60:63], v[156:159], v[220:223], v[60:63]
	v_mfma_f32_16x16x32_bf16 v[56:59], v[164:167], v[220:223], v[56:59]
	v_mfma_f32_16x16x32_bf16 v[52:55], v[156:159], v[228:231], v[52:55]
	v_mfma_f32_16x16x32_bf16 v[48:51], v[164:167], v[228:231], v[48:51]
	v_mfma_f32_16x16x32_bf16 v[28:31], v[156:159], v[236:239], v[28:31]
	v_mfma_f32_16x16x32_bf16 v[24:27], v[164:167], v[236:239], v[24:27]
	v_mfma_f32_16x16x32_bf16 v[20:23], v[156:159], v[244:247], v[20:23]
	v_mfma_f32_16x16x32_bf16 v[12:15], v[164:167], v[244:247], v[12:15]
	v_mfma_f32_16x16x32_bf16 v[60:63], v[160:163], v[224:227], v[60:63]
	v_mfma_f32_16x16x32_bf16 v[56:59], v[168:171], v[224:227], v[56:59]
	v_mfma_f32_16x16x32_bf16 v[52:55], v[160:163], v[232:235], v[52:55]
	v_mfma_f32_16x16x32_bf16 v[48:51], v[168:171], v[232:235], v[48:51]
	v_mfma_f32_16x16x32_bf16 v[28:31], v[160:163], v[240:243], v[28:31]
	v_mfma_f32_16x16x32_bf16 v[24:27], v[168:171], v[240:243], v[24:27]
	v_mfma_f32_16x16x32_bf16 v[20:23], v[160:163], v[248:251], v[20:23]
	v_mfma_f32_16x16x32_bf16 v[12:15], v[168:171], v[248:251], v[12:15]
	s_setprio 0
	s_setprio 1
	v_mfma_f32_16x16x32_bf16 v[44:47], v[172:175], v[220:223], v[44:47]
	v_mfma_f32_16x16x32_bf16 v[40:43], v[212:215], v[220:223], v[40:43]
	v_mfma_f32_16x16x32_bf16 v[36:39], v[172:175], v[228:231], v[36:39]
	v_mfma_f32_16x16x32_bf16 v[32:35], v[212:215], v[228:231], v[32:35]
	v_mfma_f32_16x16x32_bf16 v[16:19], v[172:175], v[236:239], v[16:19]
	v_mfma_f32_16x16x32_bf16 v[8:11], v[212:215], v[236:239], v[8:11]
	v_mfma_f32_16x16x32_bf16 v[4:7], v[172:175], v[244:247], v[4:7]
	v_mfma_f32_16x16x32_bf16 v[0:3], v[212:215], v[244:247], v[0:3]
	v_mfma_f32_16x16x32_bf16 v[44:47], v[176:179], v[224:227], v[44:47]
	v_mfma_f32_16x16x32_bf16 v[40:43], v[216:219], v[224:227], v[40:43]
	v_mfma_f32_16x16x32_bf16 v[36:39], v[176:179], v[232:235], v[36:39]
	v_mfma_f32_16x16x32_bf16 v[32:35], v[216:219], v[232:235], v[32:35]
	v_mfma_f32_16x16x32_bf16 v[16:19], v[176:179], v[240:243], v[16:19]
	v_mfma_f32_16x16x32_bf16 v[8:11], v[216:219], v[240:243], v[8:11]
	v_mfma_f32_16x16x32_bf16 v[4:7], v[176:179], v[248:251], v[4:7]
	v_mfma_f32_16x16x32_bf16 v[0:3], v[216:219], v[248:251], v[0:3]
	s_setprio 0
	s_barrier
	s_add_i32 s55, 0, 0x18000
	s_add_i32 s56, 0, 0x1c000
	v_add_u32_e32 v168, s55, v182
	v_add_u32_e32 v206, s56, v182
	ds_read_b128 v[156:159], v168
	ds_read_b128 v[160:163], v168 offset:1024
	ds_read_b128 v[164:167], v168 offset:2048
	ds_read_b128 v[168:171], v168 offset:3072
	ds_read_b128 v[172:175], v206
	ds_read_b128 v[176:179], v206 offset:1024
	ds_read_b128 v[212:215], v206 offset:2048
	ds_read_b128 v[216:219], v206 offset:3072
	s_add_u32 s50, s50, 0x40000
	s_addc_u32 s51, s51, 0
	s_mov_b32 m0, s67
	ds_read_b128 v[220:223], v199 offset:32768
	ds_read_b128 v[224:227], v199 offset:33792
	ds_read_b128 v[228:231], v199 offset:34816
	ds_read_b128 v[232:235], v199 offset:35840
	ds_read_b128 v[236:239], v199 offset:36864
	ds_read_b128 v[240:243], v199 offset:37888
	ds_read_b128 v[244:247], v199 offset:38912
	ds_read_b128 v[248:251], v199 offset:39936
	global_load_lds_dwordx4 v128, s[50:51]
	s_mov_b32 m0, s68
	s_nop 0
	global_load_lds_dwordx4 v132, s[50:51]
	s_waitcnt vmcnt(8)
	s_waitcnt lgkmcnt(0)
	s_barrier
	s_setprio 1
	s_waitcnt lgkmcnt(0)
	v_mfma_f32_16x16x32_bf16 v[124:127], v[156:159], v[220:223], v[124:127]
	v_mfma_f32_16x16x32_bf16 v[120:123], v[164:167], v[220:223], v[120:123]
	v_mfma_f32_16x16x32_bf16 v[116:119], v[156:159], v[228:231], v[116:119]
	v_mfma_f32_16x16x32_bf16 v[112:115], v[164:167], v[228:231], v[112:115]
	v_mfma_f32_16x16x32_bf16 v[92:95], v[156:159], v[236:239], v[92:95]
	v_mfma_f32_16x16x32_bf16 v[88:91], v[164:167], v[236:239], v[88:91]
	v_mfma_f32_16x16x32_bf16 v[84:87], v[156:159], v[244:247], v[84:87]
	v_mfma_f32_16x16x32_bf16 v[80:83], v[164:167], v[244:247], v[80:83]
	v_mfma_f32_16x16x32_bf16 v[124:127], v[160:163], v[224:227], v[124:127]
	v_mfma_f32_16x16x32_bf16 v[120:123], v[168:171], v[224:227], v[120:123]
	v_mfma_f32_16x16x32_bf16 v[116:119], v[160:163], v[232:235], v[116:119]
	v_mfma_f32_16x16x32_bf16 v[112:115], v[168:171], v[232:235], v[112:115]
	v_mfma_f32_16x16x32_bf16 v[92:95], v[160:163], v[240:243], v[92:95]
	v_mfma_f32_16x16x32_bf16 v[88:91], v[168:171], v[240:243], v[88:91]
	v_mfma_f32_16x16x32_bf16 v[84:87], v[160:163], v[248:251], v[84:87]
	v_mfma_f32_16x16x32_bf16 v[80:83], v[168:171], v[248:251], v[80:83]
	s_setprio 0
	s_setprio 1
	v_mfma_f32_16x16x32_bf16 v[108:111], v[172:175], v[220:223], v[108:111]
	v_mfma_f32_16x16x32_bf16 v[104:107], v[212:215], v[220:223], v[104:107]
	v_mfma_f32_16x16x32_bf16 v[100:103], v[172:175], v[228:231], v[100:103]
	v_mfma_f32_16x16x32_bf16 v[96:99], v[212:215], v[228:231], v[96:99]
	v_mfma_f32_16x16x32_bf16 v[76:79], v[172:175], v[236:239], v[76:79]
	v_mfma_f32_16x16x32_bf16 v[72:75], v[212:215], v[236:239], v[72:75]
	v_mfma_f32_16x16x32_bf16 v[68:71], v[172:175], v[244:247], v[68:71]
	v_mfma_f32_16x16x32_bf16 v[64:67], v[212:215], v[244:247], v[64:67]
	v_mfma_f32_16x16x32_bf16 v[108:111], v[176:179], v[224:227], v[108:111]
	v_mfma_f32_16x16x32_bf16 v[104:107], v[216:219], v[224:227], v[104:107]
	v_mfma_f32_16x16x32_bf16 v[100:103], v[176:179], v[232:235], v[100:103]
	v_mfma_f32_16x16x32_bf16 v[96:99], v[216:219], v[232:235], v[96:99]
	v_mfma_f32_16x16x32_bf16 v[76:79], v[176:179], v[240:243], v[76:79]
	v_mfma_f32_16x16x32_bf16 v[72:75], v[216:219], v[240:243], v[72:75]
	v_mfma_f32_16x16x32_bf16 v[68:71], v[176:179], v[248:251], v[68:71]
	v_mfma_f32_16x16x32_bf16 v[64:67], v[216:219], v[248:251], v[64:67]
	s_setprio 0
	s_barrier
	s_add_u32 s50, s48, 0x8000
	s_addc_u32 s51, s49, 0
	s_add_i32 s55, s55, s64
	s_mov_b32 m0, s55
	ds_read_b128 v[220:223], v199 offset:49152
	ds_read_b128 v[224:227], v199 offset:50176
	ds_read_b128 v[228:231], v199 offset:51200
	ds_read_b128 v[232:235], v199 offset:52224
	ds_read_b128 v[236:239], v199 offset:53248
	ds_read_b128 v[240:243], v199 offset:54272
	ds_read_b128 v[244:247], v199 offset:55296
	ds_read_b128 v[248:251], v199 offset:56320
	global_load_lds_dwordx4 v130, s[50:51]
	s_add_i32 m0, s55, 0x2000
	s_add_u32 s48, s48, 0xc000
	v_lshl_add_u64 v[206:207], s[50:51], 0, v[134:135]
	s_addc_u32 s49, s49, 0
	s_add_i32 s50, s56, s64
	global_load_lds_dwordx4 v[206:207], off
	s_mov_b32 m0, s50
	v_lshl_add_u64 v[204:205], v[204:205], 0, s[14:15]
	global_load_lds_dwordx4 v130, s[48:49]
	s_add_i32 m0, s50, 0x2000
	s_nop 0
	global_load_lds_dwordx4 v134, s[48:49]
	v_lshl_add_u64 v[206:207], v[252:253], 0, s[14:15]
	s_mov_b32 m0, s74
	s_nop 0
	global_load_lds_dwordx4 v[206:207], off
	s_mov_b32 m0, s75
	s_nop 0
	global_load_lds_dwordx4 v[204:205], off
	s_waitcnt vmcnt(8)
	s_waitcnt lgkmcnt(0)
	s_barrier
	s_setprio 1
	s_waitcnt lgkmcnt(0)
	v_mfma_f32_16x16x32_bf16 v[60:63], v[156:159], v[220:223], v[60:63]
	v_mfma_f32_16x16x32_bf16 v[56:59], v[164:167], v[220:223], v[56:59]
	v_mfma_f32_16x16x32_bf16 v[52:55], v[156:159], v[228:231], v[52:55]
	v_mfma_f32_16x16x32_bf16 v[48:51], v[164:167], v[228:231], v[48:51]
	v_mfma_f32_16x16x32_bf16 v[28:31], v[156:159], v[236:239], v[28:31]
	v_mfma_f32_16x16x32_bf16 v[24:27], v[164:167], v[236:239], v[24:27]
	v_mfma_f32_16x16x32_bf16 v[20:23], v[156:159], v[244:247], v[20:23]
	v_mfma_f32_16x16x32_bf16 v[12:15], v[164:167], v[244:247], v[12:15]
	v_mfma_f32_16x16x32_bf16 v[60:63], v[160:163], v[224:227], v[60:63]
	v_mfma_f32_16x16x32_bf16 v[56:59], v[168:171], v[224:227], v[56:59]
	v_mfma_f32_16x16x32_bf16 v[52:55], v[160:163], v[232:235], v[52:55]
	v_mfma_f32_16x16x32_bf16 v[48:51], v[168:171], v[232:235], v[48:51]
	v_mfma_f32_16x16x32_bf16 v[28:31], v[160:163], v[240:243], v[28:31]
	v_mfma_f32_16x16x32_bf16 v[24:27], v[168:171], v[240:243], v[24:27]
	v_mfma_f32_16x16x32_bf16 v[20:23], v[160:163], v[248:251], v[20:23]
	v_mfma_f32_16x16x32_bf16 v[12:15], v[168:171], v[248:251], v[12:15]
	s_setprio 0
	s_setprio 1
	v_mfma_f32_16x16x32_bf16 v[44:47], v[172:175], v[220:223], v[44:47]
	v_mfma_f32_16x16x32_bf16 v[40:43], v[212:215], v[220:223], v[40:43]
	v_mfma_f32_16x16x32_bf16 v[36:39], v[172:175], v[228:231], v[36:39]
	v_mfma_f32_16x16x32_bf16 v[32:35], v[212:215], v[228:231], v[32:35]
	v_mfma_f32_16x16x32_bf16 v[16:19], v[172:175], v[236:239], v[16:19]
	v_mfma_f32_16x16x32_bf16 v[8:11], v[212:215], v[236:239], v[8:11]
	v_mfma_f32_16x16x32_bf16 v[4:7], v[172:175], v[244:247], v[4:7]
	v_mfma_f32_16x16x32_bf16 v[0:3], v[212:215], v[244:247], v[0:3]
	v_mfma_f32_16x16x32_bf16 v[44:47], v[176:179], v[224:227], v[44:47]
	v_mfma_f32_16x16x32_bf16 v[40:43], v[216:219], v[224:227], v[40:43]
	v_mfma_f32_16x16x32_bf16 v[36:39], v[176:179], v[232:235], v[36:39]
	v_mfma_f32_16x16x32_bf16 v[32:35], v[216:219], v[232:235], v[32:35]
	v_mfma_f32_16x16x32_bf16 v[16:19], v[176:179], v[240:243], v[16:19]
	v_mfma_f32_16x16x32_bf16 v[8:11], v[216:219], v[240:243], v[8:11]
	v_mfma_f32_16x16x32_bf16 v[4:7], v[176:179], v[248:251], v[4:7]
	v_mfma_f32_16x16x32_bf16 v[0:3], v[216:219], v[248:251], v[0:3]
	s_setprio 0
	s_barrier
	s_add_i32 s54, s54, 2
	s_add_u32 s52, s52, 0x10000
	s_addc_u32 s53, s53, 0
	s_add_u32 s46, s46, 0x100
	s_addc_u32 s47, s47, 0
	s_cmp_gt_u32 s54, 13
	s_cbranch_scc0 .LBB0_1171
	s_and_b64 vcc, exec, s[18:19]
	s_cbranch_vccz .LBB0_1174
	s_barrier

.LBB0_1253:
	ds_read_b128 v[170:173], v167
	ds_read_b128 v[174:177], v167 offset:1024
	ds_read_b128 v[178:181], v167 offset:2048
	ds_read_b128 v[182:185], v167 offset:3072
	ds_read_b128 v[186:189], v168
	ds_read_b128 v[190:193], v168 offset:1024
	ds_read_b128 v[194:197], v168 offset:2048
	ds_read_b128 v[198:201], v168 offset:3072
	s_add_u32 s26, s24, 0xfffc0080
	s_addc_u32 s27, s25, -1
	s_cmp_eq_u32 s54, 12
	s_cselect_b32 s29, s11, s27
	s_cselect_b32 s28, s50, s26
	s_cselect_b32 s27, s13, s53
	s_cselect_b32 s26, s51, s52
	s_add_i32 m0, s21, 0xc000
	ds_read_b128 v[210:213], v169
	ds_read_b128 v[214:217], v169 offset:1024
	ds_read_b128 v[218:221], v169 offset:2048
	ds_read_b128 v[222:225], v169 offset:3072
	ds_read_b128 v[226:229], v169 offset:4096
	ds_read_b128 v[230:233], v169 offset:5120
	ds_read_b128 v[234:237], v169 offset:6144
	ds_read_b128 v[238:241], v169 offset:7168
	global_load_lds_dwordx4 v158, s[24:25]
	s_add_i32 m0, s21, 0xe000
	s_nop 0
	global_load_lds_dwordx4 v156, s[24:25]
	s_waitcnt vmcnt(8)
	s_waitcnt lgkmcnt(0)
	s_barrier
	s_setprio 1
	s_waitcnt lgkmcnt(0)
	v_mfma_f32_16x16x32_bf16 v[124:127], v[170:173], v[210:213], v[124:127]
	v_mfma_f32_16x16x32_bf16 v[116:119], v[178:181], v[210:213], v[116:119]
	v_mfma_f32_16x16x32_bf16 v[108:111], v[170:173], v[218:221], v[108:111]
	v_mfma_f32_16x16x32_bf16 v[100:103], v[178:181], v[218:221], v[100:103]
	v_mfma_f32_16x16x32_bf16 v[92:95], v[170:173], v[226:229], v[92:95]
	v_mfma_f32_16x16x32_bf16 v[84:87], v[178:181], v[226:229], v[84:87]
	v_mfma_f32_16x16x32_bf16 v[76:79], v[170:173], v[234:237], v[76:79]
	v_mfma_f32_16x16x32_bf16 v[68:71], v[178:181], v[234:237], v[68:71]
	v_mfma_f32_16x16x32_bf16 v[124:127], v[174:177], v[214:217], v[124:127]
	v_mfma_f32_16x16x32_bf16 v[116:119], v[182:185], v[214:217], v[116:119]
	v_mfma_f32_16x16x32_bf16 v[108:111], v[174:177], v[222:225], v[108:111]
	v_mfma_f32_16x16x32_bf16 v[100:103], v[182:185], v[222:225], v[100:103]
	v_mfma_f32_16x16x32_bf16 v[92:95], v[174:177], v[230:233], v[92:95]
	v_mfma_f32_16x16x32_bf16 v[84:87], v[182:185], v[230:233], v[84:87]
	v_mfma_f32_16x16x32_bf16 v[76:79], v[174:177], v[238:241], v[76:79]
	v_mfma_f32_16x16x32_bf16 v[68:71], v[182:185], v[238:241], v[68:71]
	s_setprio 0
	s_setprio 1
	v_mfma_f32_16x16x32_bf16 v[120:123], v[186:189], v[210:213], v[120:123]
	v_mfma_f32_16x16x32_bf16 v[112:115], v[194:197], v[210:213], v[112:115]
	v_mfma_f32_16x16x32_bf16 v[104:107], v[186:189], v[218:221], v[104:107]
	v_mfma_f32_16x16x32_bf16 v[96:99], v[194:197], v[218:221], v[96:99]
	v_mfma_f32_16x16x32_bf16 v[88:91], v[186:189], v[226:229], v[88:91]
	v_mfma_f32_16x16x32_bf16 v[80:83], v[194:197], v[226:229], v[80:83]
	v_mfma_f32_16x16x32_bf16 v[72:75], v[186:189], v[234:237], v[72:75]
	v_mfma_f32_16x16x32_bf16 v[64:67], v[194:197], v[234:237], v[64:67]
	v_mfma_f32_16x16x32_bf16 v[120:123], v[190:193], v[214:217], v[120:123]
	v_mfma_f32_16x16x32_bf16 v[112:115], v[198:201], v[214:217], v[112:115]
	v_mfma_f32_16x16x32_bf16 v[104:107], v[190:193], v[222:225], v[104:107]
	v_mfma_f32_16x16x32_bf16 v[96:99], v[198:201], v[222:225], v[96:99]
	v_mfma_f32_16x16x32_bf16 v[88:91], v[190:193], v[230:233], v[88:91]
	v_mfma_f32_16x16x32_bf16 v[80:83], v[198:201], v[230:233], v[80:83]
	v_mfma_f32_16x16x32_bf16 v[72:75], v[190:193], v[238:241], v[72:75]
	v_mfma_f32_16x16x32_bf16 v[64:67], v[198:201], v[238:241], v[64:67]
	s_setprio 0
	s_barrier
	s_add_i32 s55, s48, s35
	s_mov_b32 m0, s55
	ds_read_b128 v[210:213], v169 offset:16384
	ds_read_b128 v[214:217], v169 offset:17408
	ds_read_b128 v[218:221], v169 offset:18432
	ds_read_b128 v[222:225], v169 offset:19456
	ds_read_b128 v[226:229], v169 offset:20480
	ds_read_b128 v[230:233], v169 offset:21504
	ds_read_b128 v[234:237], v169 offset:22528
	ds_read_b128 v[238:241], v169 offset:23552
	global_load_lds_dwordx4 v134, s[26:27]
	s_add_i32 m0, s55, 0x2000
	s_add_u32 s56, s26, 0x4000
	s_addc_u32 s57, s27, 0
	s_add_i32 s55, s49, s35
	global_load_lds_dwordx4 v130, s[26:27]
	s_mov_b32 m0, s55
	v_lshl_add_u64 v[204:205], s[28:29], 0, v[132:133]
	global_load_lds_dwordx4 v134, s[56:57]
	s_add_i32 m0, s55, 0x2000
	s_nop 0
	global_load_lds_dwordx4 v130, s[56:57]
	v_lshl_add_u64 v[164:165], s[28:29], 0, v[136:137]
	s_mov_b32 m0, s21
	s_nop 0
	global_load_lds_dwordx4 v[164:165], off
	s_mov_b32 m0, s23
	s_nop 0
	global_load_lds_dwordx4 v[204:205], off
	s_waitcnt vmcnt(8)
	s_waitcnt lgkmcnt(0)
	s_barrier
	s_setprio 1
	s_waitcnt lgkmcnt(0)
	v_mfma_f32_16x16x32_bf16 v[60:63], v[170:173], v[210:213], v[60:63]
	v_mfma_f32_16x16x32_bf16 v[52:55], v[178:181], v[210:213], v[52:55]
	v_mfma_f32_16x16x32_bf16 v[44:47], v[170:173], v[218:221], v[44:47]
	v_mfma_f32_16x16x32_bf16 v[36:39], v[178:181], v[218:221], v[36:39]
	v_mfma_f32_16x16x32_bf16 v[28:31], v[170:173], v[226:229], v[28:31]
	v_mfma_f32_16x16x32_bf16 v[20:23], v[178:181], v[226:229], v[20:23]
	v_mfma_f32_16x16x32_bf16 v[12:15], v[170:173], v[234:237], v[12:15]
	v_mfma_f32_16x16x32_bf16 v[4:7], v[178:181], v[234:237], v[4:7]
	v_mfma_f32_16x16x32_bf16 v[60:63], v[174:177], v[214:217], v[60:63]
	v_mfma_f32_16x16x32_bf16 v[52:55], v[182:185], v[214:217], v[52:55]
	v_mfma_f32_16x16x32_bf16 v[44:47], v[174:177], v[222:225], v[44:47]
	v_mfma_f32_16x16x32_bf16 v[36:39], v[182:185], v[222:225], v[36:39]
	v_mfma_f32_16x16x32_bf16 v[28:31], v[174:177], v[230:233], v[28:31]
	v_mfma_f32_16x16x32_bf16 v[20:23], v[182:185], v[230:233], v[20:23]
	v_mfma_f32_16x16x32_bf16 v[12:15], v[174:177], v[238:241], v[12:15]
	v_mfma_f32_16x16x32_bf16 v[4:7], v[182:185], v[238:241], v[4:7]
	s_setprio 0
	s_setprio 1
	v_mfma_f32_16x16x32_bf16 v[56:59], v[186:189], v[210:213], v[56:59]
	v_mfma_f32_16x16x32_bf16 v[48:51], v[194:197], v[210:213], v[48:51]
	v_mfma_f32_16x16x32_bf16 v[40:43], v[186:189], v[218:221], v[40:43]
	v_mfma_f32_16x16x32_bf16 v[32:35], v[194:197], v[218:221], v[32:35]
	v_mfma_f32_16x16x32_bf16 v[24:27], v[186:189], v[226:229], v[24:27]
	v_mfma_f32_16x16x32_bf16 v[16:19], v[194:197], v[226:229], v[16:19]
	v_mfma_f32_16x16x32_bf16 v[8:11], v[186:189], v[234:237], v[8:11]
	v_mfma_f32_16x16x32_bf16 v[0:3], v[194:197], v[234:237], v[0:3]
	v_mfma_f32_16x16x32_bf16 v[56:59], v[190:193], v[214:217], v[56:59]
	v_mfma_f32_16x16x32_bf16 v[48:51], v[198:201], v[214:217], v[48:51]
	v_mfma_f32_16x16x32_bf16 v[40:43], v[190:193], v[222:225], v[40:43]
	v_mfma_f32_16x16x32_bf16 v[32:35], v[198:201], v[222:225], v[32:35]
	v_mfma_f32_16x16x32_bf16 v[24:27], v[190:193], v[230:233], v[24:27]
	v_mfma_f32_16x16x32_bf16 v[16:19], v[198:201], v[230:233], v[16:19]
	v_mfma_f32_16x16x32_bf16 v[8:11], v[190:193], v[238:241], v[8:11]
	v_mfma_f32_16x16x32_bf16 v[0:3], v[198:201], v[238:241], v[0:3]
	s_setprio 0
	s_barrier
	s_add_i32 s55, 0, 0x18000
	s_add_i32 s56, 0, 0x1c000
	v_add_u32_e32 v182, s55, v129
	v_add_u32_e32 v198, s56, v129
	ds_read_b128 v[170:173], v182
	ds_read_b128 v[174:177], v182 offset:1024
	ds_read_b128 v[178:181], v182 offset:2048
	ds_read_b128 v[182:185], v182 offset:3072
	ds_read_b128 v[186:189], v198
	ds_read_b128 v[190:193], v198 offset:1024
	ds_read_b128 v[194:197], v198 offset:2048
	ds_read_b128 v[198:201], v198 offset:3072
	s_add_u32 s28, s28, 0x40000
	s_addc_u32 s29, s29, 0
	s_mov_b32 m0, s39
	ds_read_b128 v[210:213], v169 offset:32768
	ds_read_b128 v[214:217], v169 offset:33792
	ds_read_b128 v[218:221], v169 offset:34816
	ds_read_b128 v[222:225], v169 offset:35840
	ds_read_b128 v[226:229], v169 offset:36864
	ds_read_b128 v[230:233], v169 offset:37888
	ds_read_b128 v[234:237], v169 offset:38912
	ds_read_b128 v[238:241], v169 offset:39936
	global_load_lds_dwordx4 v136, s[28:29]
	s_mov_b32 m0, s40
	s_nop 0
	global_load_lds_dwordx4 v132, s[28:29]
	s_waitcnt vmcnt(8)
	s_waitcnt lgkmcnt(0)
	s_barrier
	s_setprio 1
	s_waitcnt lgkmcnt(0)
	v_mfma_f32_16x16x32_bf16 v[124:127], v[170:173], v[210:213], v[124:127]
	v_mfma_f32_16x16x32_bf16 v[116:119], v[178:181], v[210:213], v[116:119]
	v_mfma_f32_16x16x32_bf16 v[108:111], v[170:173], v[218:221], v[108:111]
	v_mfma_f32_16x16x32_bf16 v[100:103], v[178:181], v[218:221], v[100:103]
	v_mfma_f32_16x16x32_bf16 v[92:95], v[170:173], v[226:229], v[92:95]
	v_mfma_f32_16x16x32_bf16 v[84:87], v[178:181], v[226:229], v[84:87]
	v_mfma_f32_16x16x32_bf16 v[76:79], v[170:173], v[234:237], v[76:79]
	v_mfma_f32_16x16x32_bf16 v[68:71], v[178:181], v[234:237], v[68:71]
	v_mfma_f32_16x16x32_bf16 v[124:127], v[174:177], v[214:217], v[124:127]
	v_mfma_f32_16x16x32_bf16 v[116:119], v[182:185], v[214:217], v[116:119]
	v_mfma_f32_16x16x32_bf16 v[108:111], v[174:177], v[222:225], v[108:111]
	v_mfma_f32_16x16x32_bf16 v[100:103], v[182:185], v[222:225], v[100:103]
	v_mfma_f32_16x16x32_bf16 v[92:95], v[174:177], v[230:233], v[92:95]
	v_mfma_f32_16x16x32_bf16 v[84:87], v[182:185], v[230:233], v[84:87]
	v_mfma_f32_16x16x32_bf16 v[76:79], v[174:177], v[238:241], v[76:79]
	v_mfma_f32_16x16x32_bf16 v[68:71], v[182:185], v[238:241], v[68:71]
	s_setprio 0
	s_setprio 1
	v_mfma_f32_16x16x32_bf16 v[120:123], v[186:189], v[210:213], v[120:123]
	v_mfma_f32_16x16x32_bf16 v[112:115], v[194:197], v[210:213], v[112:115]
	v_mfma_f32_16x16x32_bf16 v[104:107], v[186:189], v[218:221], v[104:107]
	v_mfma_f32_16x16x32_bf16 v[96:99], v[194:197], v[218:221], v[96:99]
	v_mfma_f32_16x16x32_bf16 v[88:91], v[186:189], v[226:229], v[88:91]
	v_mfma_f32_16x16x32_bf16 v[80:83], v[194:197], v[226:229], v[80:83]
	v_mfma_f32_16x16x32_bf16 v[72:75], v[186:189], v[234:237], v[72:75]
	v_mfma_f32_16x16x32_bf16 v[64:67], v[194:197], v[234:237], v[64:67]
	v_mfma_f32_16x16x32_bf16 v[120:123], v[190:193], v[214:217], v[120:123]
	v_mfma_f32_16x16x32_bf16 v[112:115], v[198:201], v[214:217], v[112:115]
	v_mfma_f32_16x16x32_bf16 v[104:107], v[190:193], v[222:225], v[104:107]
	v_mfma_f32_16x16x32_bf16 v[96:99], v[198:201], v[222:225], v[96:99]
	v_mfma_f32_16x16x32_bf16 v[88:91], v[190:193], v[230:233], v[88:91]
	v_mfma_f32_16x16x32_bf16 v[80:83], v[198:201], v[230:233], v[80:83]
	v_mfma_f32_16x16x32_bf16 v[72:75], v[190:193], v[238:241], v[72:75]
	v_mfma_f32_16x16x32_bf16 v[64:67], v[198:201], v[238:241], v[64:67]
	s_setprio 0
	s_barrier
	s_add_u32 s28, s26, 0x8000
	s_addc_u32 s29, s27, 0
	s_add_i32 s55, s55, s35
	s_mov_b32 m0, s55
	ds_read_b128 v[210:213], v169 offset:49152
	ds_read_b128 v[214:217], v169 offset:50176
	ds_read_b128 v[218:221], v169 offset:51200
	ds_read_b128 v[222:225], v169 offset:52224
	ds_read_b128 v[226:229], v169 offset:53248
	ds_read_b128 v[230:233], v169 offset:54272
	ds_read_b128 v[234:237], v169 offset:55296
	ds_read_b128 v[238:241], v169 offset:56320
	global_load_lds_dwordx4 v134, s[28:29]
	s_add_i32 m0, s55, 0x2000
	s_add_u32 s26, s26, 0xc000
	v_lshl_add_u64 v[206:207], s[28:29], 0, v[130:131]
	s_addc_u32 s27, s27, 0
	s_add_i32 s28, s56, s35
	global_load_lds_dwordx4 v[206:207], off
	s_mov_b32 m0, s28
	v_lshl_add_u64 v[164:165], v[164:165], 0, s[6:7]
	global_load_lds_dwordx4 v134, s[26:27]
	s_add_i32 m0, s28, 0x2000
	s_nop 0
	global_load_lds_dwordx4 v130, s[26:27]
	s_mov_b32 m0, s45
	s_nop 0
	global_load_lds_dwordx4 v[164:165], off
	v_lshl_add_u64 v[164:165], v[204:205], 0, s[6:7]
	s_mov_b32 m0, s46
	s_nop 0
	global_load_lds_dwordx4 v[164:165], off
	s_waitcnt vmcnt(8)
	s_waitcnt lgkmcnt(0)
	s_barrier
	s_setprio 1
	s_waitcnt lgkmcnt(0)
	v_mfma_f32_16x16x32_bf16 v[60:63], v[170:173], v[210:213], v[60:63]
	v_mfma_f32_16x16x32_bf16 v[52:55], v[178:181], v[210:213], v[52:55]
	v_mfma_f32_16x16x32_bf16 v[44:47], v[170:173], v[218:221], v[44:47]
	v_mfma_f32_16x16x32_bf16 v[36:39], v[178:181], v[218:221], v[36:39]
	v_mfma_f32_16x16x32_bf16 v[28:31], v[170:173], v[226:229], v[28:31]
	v_mfma_f32_16x16x32_bf16 v[20:23], v[178:181], v[226:229], v[20:23]
	v_mfma_f32_16x16x32_bf16 v[12:15], v[170:173], v[234:237], v[12:15]
	v_mfma_f32_16x16x32_bf16 v[4:7], v[178:181], v[234:237], v[4:7]
	v_mfma_f32_16x16x32_bf16 v[60:63], v[174:177], v[214:217], v[60:63]
	v_mfma_f32_16x16x32_bf16 v[52:55], v[182:185], v[214:217], v[52:55]
	v_mfma_f32_16x16x32_bf16 v[44:47], v[174:177], v[222:225], v[44:47]
	v_mfma_f32_16x16x32_bf16 v[36:39], v[182:185], v[222:225], v[36:39]
	v_mfma_f32_16x16x32_bf16 v[28:31], v[174:177], v[230:233], v[28:31]
	v_mfma_f32_16x16x32_bf16 v[20:23], v[182:185], v[230:233], v[20:23]
	v_mfma_f32_16x16x32_bf16 v[12:15], v[174:177], v[238:241], v[12:15]
	v_mfma_f32_16x16x32_bf16 v[4:7], v[182:185], v[238:241], v[4:7]
	s_setprio 0
	s_setprio 1
	v_mfma_f32_16x16x32_bf16 v[56:59], v[186:189], v[210:213], v[56:59]
	v_mfma_f32_16x16x32_bf16 v[48:51], v[194:197], v[210:213], v[48:51]
	v_mfma_f32_16x16x32_bf16 v[40:43], v[186:189], v[218:221], v[40:43]
	v_mfma_f32_16x16x32_bf16 v[32:35], v[194:197], v[218:221], v[32:35]
	v_mfma_f32_16x16x32_bf16 v[24:27], v[186:189], v[226:229], v[24:27]
	v_mfma_f32_16x16x32_bf16 v[16:19], v[194:197], v[226:229], v[16:19]
	v_mfma_f32_16x16x32_bf16 v[8:11], v[186:189], v[234:237], v[8:11]
	v_mfma_f32_16x16x32_bf16 v[0:3], v[194:197], v[234:237], v[0:3]
	v_mfma_f32_16x16x32_bf16 v[56:59], v[190:193], v[214:217], v[56:59]
	v_mfma_f32_16x16x32_bf16 v[48:51], v[198:201], v[214:217], v[48:51]
	v_mfma_f32_16x16x32_bf16 v[40:43], v[190:193], v[222:225], v[40:43]
	v_mfma_f32_16x16x32_bf16 v[32:35], v[198:201], v[222:225], v[32:35]
	v_mfma_f32_16x16x32_bf16 v[24:27], v[190:193], v[230:233], v[24:27]
	v_mfma_f32_16x16x32_bf16 v[16:19], v[198:201], v[230:233], v[16:19]
	v_mfma_f32_16x16x32_bf16 v[8:11], v[190:193], v[238:241], v[8:11]
	v_mfma_f32_16x16x32_bf16 v[0:3], v[198:201], v[238:241], v[0:3]
	s_setprio 0
	s_barrier
	s_add_i32 s54, s54, 2
	s_add_u32 s52, s52, 0x10000
	s_addc_u32 s53, s53, 0
	s_add_u32 s24, s24, 0x100
	s_addc_u32 s25, s25, 0
	s_cmp_gt_u32 s54, 13
	s_cbranch_scc0 .LBB0_1253
	s_and_b64 vcc, exec, s[8:9]
	s_cbranch_vccz .LBB0_1256
	s_barrier

.LBB0_1481:
	v_add_u32_e32 v168, s61, v182
	v_add_u32_e32 v204, s62, v182
	ds_read_b128 v[156:159], v168
	ds_read_b128 v[160:163], v168 offset:1024
	ds_read_b128 v[164:167], v168 offset:2048
	ds_read_b128 v[168:171], v168 offset:3072
	ds_read_b128 v[172:175], v204
	ds_read_b128 v[176:179], v204 offset:1024
	ds_read_b128 v[212:215], v204 offset:2048
	ds_read_b128 v[216:219], v204 offset:3072
	s_add_u32 s38, s36, 0x4000
	s_addc_u32 s39, s37, 0
	s_cmp_eq_u32 s70, 40
	s_cselect_b32 s42, s0, s38
	s_cselect_b32 s43, s1, s39
	s_cselect_b32 s40, s34, s68
	s_cselect_b32 s41, s35, s69
	s_add_u32 s38, s42, 0x8000
	s_addc_u32 s39, s43, 0
	s_add_i32 m0, s48, 0xc000
	ds_read_b128 v[220:223], v199
	ds_read_b128 v[224:227], v199 offset:1024
	ds_read_b128 v[228:231], v199 offset:2048
	ds_read_b128 v[232:235], v199 offset:3072
	ds_read_b128 v[236:239], v199 offset:4096
	ds_read_b128 v[240:243], v199 offset:5120
	ds_read_b128 v[244:247], v199 offset:6144
	ds_read_b128 v[248:251], v199 offset:7168
	global_load_lds_dwordx4 v150, s[36:37]
	s_add_i32 m0, s48, 0xe000
	s_nop 0
	global_load_lds_dwordx4 v148, s[36:37]
	s_waitcnt vmcnt(8)
	s_waitcnt lgkmcnt(0)
	s_barrier
	s_setprio 1
	s_waitcnt lgkmcnt(0)
	v_mfma_f32_16x16x32_bf16 v[124:127], v[156:159], v[220:223], v[124:127]
	v_mfma_f32_16x16x32_bf16 v[120:123], v[164:167], v[220:223], v[120:123]
	v_mfma_f32_16x16x32_bf16 v[116:119], v[156:159], v[228:231], v[116:119]
	v_mfma_f32_16x16x32_bf16 v[112:115], v[164:167], v[228:231], v[112:115]
	v_mfma_f32_16x16x32_bf16 v[92:95], v[156:159], v[236:239], v[92:95]
	v_mfma_f32_16x16x32_bf16 v[88:91], v[164:167], v[236:239], v[88:91]
	v_mfma_f32_16x16x32_bf16 v[84:87], v[156:159], v[244:247], v[84:87]
	v_mfma_f32_16x16x32_bf16 v[80:83], v[164:167], v[244:247], v[80:83]
	v_mfma_f32_16x16x32_bf16 v[124:127], v[160:163], v[224:227], v[124:127]
	v_mfma_f32_16x16x32_bf16 v[120:123], v[168:171], v[224:227], v[120:123]
	v_mfma_f32_16x16x32_bf16 v[116:119], v[160:163], v[232:235], v[116:119]
	v_mfma_f32_16x16x32_bf16 v[112:115], v[168:171], v[232:235], v[112:115]
	v_mfma_f32_16x16x32_bf16 v[92:95], v[160:163], v[240:243], v[92:95]
	v_mfma_f32_16x16x32_bf16 v[88:91], v[168:171], v[240:243], v[88:91]
	v_mfma_f32_16x16x32_bf16 v[84:87], v[160:163], v[248:251], v[84:87]
	v_mfma_f32_16x16x32_bf16 v[80:83], v[168:171], v[248:251], v[80:83]
	s_setprio 0
	s_setprio 1
	v_mfma_f32_16x16x32_bf16 v[108:111], v[172:175], v[220:223], v[108:111]
	v_mfma_f32_16x16x32_bf16 v[104:107], v[212:215], v[220:223], v[104:107]
	v_mfma_f32_16x16x32_bf16 v[100:103], v[172:175], v[228:231], v[100:103]
	v_mfma_f32_16x16x32_bf16 v[96:99], v[212:215], v[228:231], v[96:99]
	v_mfma_f32_16x16x32_bf16 v[76:79], v[172:175], v[236:239], v[76:79]
	v_mfma_f32_16x16x32_bf16 v[72:75], v[212:215], v[236:239], v[72:75]
	v_mfma_f32_16x16x32_bf16 v[68:71], v[172:175], v[244:247], v[68:71]
	v_mfma_f32_16x16x32_bf16 v[64:67], v[212:215], v[244:247], v[64:67]
	v_mfma_f32_16x16x32_bf16 v[108:111], v[176:179], v[224:227], v[108:111]
	v_mfma_f32_16x16x32_bf16 v[104:107], v[216:219], v[224:227], v[104:107]
	v_mfma_f32_16x16x32_bf16 v[100:103], v[176:179], v[232:235], v[100:103]
	v_mfma_f32_16x16x32_bf16 v[96:99], v[216:219], v[232:235], v[96:99]
	v_mfma_f32_16x16x32_bf16 v[76:79], v[176:179], v[240:243], v[76:79]
	v_mfma_f32_16x16x32_bf16 v[72:75], v[216:219], v[240:243], v[72:75]
	v_mfma_f32_16x16x32_bf16 v[68:71], v[176:179], v[248:251], v[68:71]
	v_mfma_f32_16x16x32_bf16 v[64:67], v[216:219], v[248:251], v[64:67]
	s_setprio 0
	s_barrier
	s_add_i32 s71, s61, s47
	s_mov_b32 m0, s71
	ds_read_b128 v[220:223], v199 offset:16384
	ds_read_b128 v[224:227], v199 offset:17408
	ds_read_b128 v[228:231], v199 offset:18432
	ds_read_b128 v[232:235], v199 offset:19456
	ds_read_b128 v[236:239], v199 offset:20480
	ds_read_b128 v[240:243], v199 offset:21504
	ds_read_b128 v[244:247], v199 offset:22528
	ds_read_b128 v[248:251], v199 offset:23552
	global_load_lds_dwordx4 v128, s[40:41]
	s_add_i32 m0, s71, 0x2000
	s_add_u32 s72, s40, 0x4000
	s_addc_u32 s73, s41, 0
	s_add_i32 s71, s62, s47
	global_load_lds_dwordx4 v130, s[40:41]
	s_mov_b32 m0, s71
	s_nop 0
	global_load_lds_dwordx4 v128, s[72:73]
	s_add_i32 m0, s71, 0x2000
	s_nop 0
	global_load_lds_dwordx4 v130, s[72:73]
	s_mov_b32 m0, s48
	s_nop 0
	global_load_lds_dwordx4 v128, s[42:43]
	v_lshl_add_u64 v[204:205], s[42:43], 0, v[130:131]
	s_mov_b32 m0, s49
	s_nop 0
	global_load_lds_dwordx4 v[204:205], off
	s_waitcnt vmcnt(8)
	s_waitcnt lgkmcnt(0)
	s_barrier
	s_setprio 1
	s_waitcnt lgkmcnt(0)
	v_mfma_f32_16x16x32_bf16 v[60:63], v[156:159], v[220:223], v[60:63]
	v_mfma_f32_16x16x32_bf16 v[56:59], v[164:167], v[220:223], v[56:59]
	v_mfma_f32_16x16x32_bf16 v[52:55], v[156:159], v[228:231], v[52:55]
	v_mfma_f32_16x16x32_bf16 v[48:51], v[164:167], v[228:231], v[48:51]
	v_mfma_f32_16x16x32_bf16 v[28:31], v[156:159], v[236:239], v[28:31]
	v_mfma_f32_16x16x32_bf16 v[24:27], v[164:167], v[236:239], v[24:27]
	v_mfma_f32_16x16x32_bf16 v[20:23], v[156:159], v[244:247], v[20:23]
	v_mfma_f32_16x16x32_bf16 v[12:15], v[164:167], v[244:247], v[12:15]
	v_mfma_f32_16x16x32_bf16 v[60:63], v[160:163], v[224:227], v[60:63]
	v_mfma_f32_16x16x32_bf16 v[56:59], v[168:171], v[224:227], v[56:59]
	v_mfma_f32_16x16x32_bf16 v[52:55], v[160:163], v[232:235], v[52:55]
	v_mfma_f32_16x16x32_bf16 v[48:51], v[168:171], v[232:235], v[48:51]
	v_mfma_f32_16x16x32_bf16 v[28:31], v[160:163], v[240:243], v[28:31]
	v_mfma_f32_16x16x32_bf16 v[24:27], v[168:171], v[240:243], v[24:27]
	v_mfma_f32_16x16x32_bf16 v[20:23], v[160:163], v[248:251], v[20:23]
	v_mfma_f32_16x16x32_bf16 v[12:15], v[168:171], v[248:251], v[12:15]
	s_setprio 0
	s_setprio 1
	v_mfma_f32_16x16x32_bf16 v[44:47], v[172:175], v[220:223], v[44:47]
	v_mfma_f32_16x16x32_bf16 v[40:43], v[212:215], v[220:223], v[40:43]
	v_mfma_f32_16x16x32_bf16 v[36:39], v[172:175], v[228:231], v[36:39]
	v_mfma_f32_16x16x32_bf16 v[32:35], v[212:215], v[228:231], v[32:35]
	v_mfma_f32_16x16x32_bf16 v[16:19], v[172:175], v[236:239], v[16:19]
	v_mfma_f32_16x16x32_bf16 v[8:11], v[212:215], v[236:239], v[8:11]
	v_mfma_f32_16x16x32_bf16 v[4:7], v[172:175], v[244:247], v[4:7]
	v_mfma_f32_16x16x32_bf16 v[0:3], v[212:215], v[244:247], v[0:3]
	v_mfma_f32_16x16x32_bf16 v[44:47], v[176:179], v[224:227], v[44:47]
	v_mfma_f32_16x16x32_bf16 v[40:43], v[216:219], v[224:227], v[40:43]
	v_mfma_f32_16x16x32_bf16 v[36:39], v[176:179], v[232:235], v[36:39]
	v_mfma_f32_16x16x32_bf16 v[32:35], v[216:219], v[232:235], v[32:35]
	v_mfma_f32_16x16x32_bf16 v[16:19], v[176:179], v[240:243], v[16:19]
	v_mfma_f32_16x16x32_bf16 v[8:11], v[216:219], v[240:243], v[8:11]
	v_mfma_f32_16x16x32_bf16 v[4:7], v[176:179], v[248:251], v[4:7]
	v_mfma_f32_16x16x32_bf16 v[0:3], v[216:219], v[248:251], v[0:3]
	s_setprio 0
	s_barrier
	s_add_i32 s71, 0, 0x18000
	s_add_i32 s72, 0, 0x1c000
	v_add_u32_e32 v168, s71, v182
	v_add_u32_e32 v204, s72, v182
	ds_read_b128 v[156:159], v168
	ds_read_b128 v[160:163], v168 offset:1024
	ds_read_b128 v[164:167], v168 offset:2048
	ds_read_b128 v[168:171], v168 offset:3072
	ds_read_b128 v[172:175], v204
	ds_read_b128 v[176:179], v204 offset:1024
	ds_read_b128 v[212:215], v204 offset:2048
	ds_read_b128 v[216:219], v204 offset:3072
	s_add_u32 s42, s42, 0x4000
	s_addc_u32 s43, s43, 0
	s_mov_b32 m0, s50
	ds_read_b128 v[220:223], v199 offset:32768
	ds_read_b128 v[224:227], v199 offset:33792
	ds_read_b128 v[228:231], v199 offset:34816
	ds_read_b128 v[232:235], v199 offset:35840
	ds_read_b128 v[236:239], v199 offset:36864
	ds_read_b128 v[240:243], v199 offset:37888
	ds_read_b128 v[244:247], v199 offset:38912
	ds_read_b128 v[248:251], v199 offset:39936
	global_load_lds_dwordx4 v128, s[42:43]
	s_mov_b32 m0, s51
	s_nop 0
	global_load_lds_dwordx4 v130, s[42:43]
	s_waitcnt vmcnt(8)
	s_waitcnt lgkmcnt(0)
	s_barrier
	s_setprio 1
	s_waitcnt lgkmcnt(0)
	v_mfma_f32_16x16x32_bf16 v[124:127], v[156:159], v[220:223], v[124:127]
	v_mfma_f32_16x16x32_bf16 v[120:123], v[164:167], v[220:223], v[120:123]
	v_mfma_f32_16x16x32_bf16 v[116:119], v[156:159], v[228:231], v[116:119]
	v_mfma_f32_16x16x32_bf16 v[112:115], v[164:167], v[228:231], v[112:115]
	v_mfma_f32_16x16x32_bf16 v[92:95], v[156:159], v[236:239], v[92:95]
	v_mfma_f32_16x16x32_bf16 v[88:91], v[164:167], v[236:239], v[88:91]
	v_mfma_f32_16x16x32_bf16 v[84:87], v[156:159], v[244:247], v[84:87]
	v_mfma_f32_16x16x32_bf16 v[80:83], v[164:167], v[244:247], v[80:83]
	v_mfma_f32_16x16x32_bf16 v[124:127], v[160:163], v[224:227], v[124:127]
	v_mfma_f32_16x16x32_bf16 v[120:123], v[168:171], v[224:227], v[120:123]
	v_mfma_f32_16x16x32_bf16 v[116:119], v[160:163], v[232:235], v[116:119]
	v_mfma_f32_16x16x32_bf16 v[112:115], v[168:171], v[232:235], v[112:115]
	v_mfma_f32_16x16x32_bf16 v[92:95], v[160:163], v[240:243], v[92:95]
	v_mfma_f32_16x16x32_bf16 v[88:91], v[168:171], v[240:243], v[88:91]
	v_mfma_f32_16x16x32_bf16 v[84:87], v[160:163], v[248:251], v[84:87]
	v_mfma_f32_16x16x32_bf16 v[80:83], v[168:171], v[248:251], v[80:83]
	s_setprio 0
	s_setprio 1
	v_mfma_f32_16x16x32_bf16 v[108:111], v[172:175], v[220:223], v[108:111]
	v_mfma_f32_16x16x32_bf16 v[104:107], v[212:215], v[220:223], v[104:107]
	v_mfma_f32_16x16x32_bf16 v[100:103], v[172:175], v[228:231], v[100:103]
	v_mfma_f32_16x16x32_bf16 v[96:99], v[212:215], v[228:231], v[96:99]
	v_mfma_f32_16x16x32_bf16 v[76:79], v[172:175], v[236:239], v[76:79]
	v_mfma_f32_16x16x32_bf16 v[72:75], v[212:215], v[236:239], v[72:75]
	v_mfma_f32_16x16x32_bf16 v[68:71], v[172:175], v[244:247], v[68:71]
	v_mfma_f32_16x16x32_bf16 v[64:67], v[212:215], v[244:247], v[64:67]
	v_mfma_f32_16x16x32_bf16 v[108:111], v[176:179], v[224:227], v[108:111]
	v_mfma_f32_16x16x32_bf16 v[104:107], v[216:219], v[224:227], v[104:107]
	v_mfma_f32_16x16x32_bf16 v[100:103], v[176:179], v[232:235], v[100:103]
	v_mfma_f32_16x16x32_bf16 v[96:99], v[216:219], v[232:235], v[96:99]
	v_mfma_f32_16x16x32_bf16 v[76:79], v[176:179], v[240:243], v[76:79]
	v_mfma_f32_16x16x32_bf16 v[72:75], v[216:219], v[240:243], v[72:75]
	v_mfma_f32_16x16x32_bf16 v[68:71], v[176:179], v[248:251], v[68:71]
	v_mfma_f32_16x16x32_bf16 v[64:67], v[216:219], v[248:251], v[64:67]
	s_setprio 0
	s_barrier
	s_add_u32 s42, s40, 0x8000
	s_addc_u32 s43, s41, 0
	s_add_i32 s71, s71, s47
	s_mov_b32 m0, s71
	ds_read_b128 v[220:223], v199 offset:49152
	ds_read_b128 v[224:227], v199 offset:50176
	ds_read_b128 v[228:231], v199 offset:51200
	ds_read_b128 v[232:235], v199 offset:52224
	ds_read_b128 v[236:239], v199 offset:53248
	ds_read_b128 v[240:243], v199 offset:54272
	ds_read_b128 v[244:247], v199 offset:55296
	ds_read_b128 v[248:251], v199 offset:56320
	global_load_lds_dwordx4 v128, s[42:43]
	s_add_i32 m0, s71, 0x2000
	s_add_u32 s40, s40, 0xc000
	v_lshl_add_u64 v[204:205], s[42:43], 0, v[130:131]
	s_addc_u32 s41, s41, 0
	s_add_i32 s42, s72, s47
	global_load_lds_dwordx4 v[204:205], off
	s_mov_b32 m0, s42
	s_nop 0
	global_load_lds_dwordx4 v128, s[40:41]
	s_add_i32 m0, s42, 0x2000
	s_nop 0
	global_load_lds_dwordx4 v130, s[40:41]
	s_mov_b32 m0, s57
	s_nop 0
	global_load_lds_dwordx4 v128, s[38:39]
	v_lshl_add_u64 v[204:205], s[38:39], 0, v[130:131]
	s_mov_b32 m0, s58
	s_nop 0
	global_load_lds_dwordx4 v[204:205], off
	s_waitcnt vmcnt(8)
	s_waitcnt lgkmcnt(0)
	s_barrier
	s_setprio 1
	s_waitcnt lgkmcnt(0)
	v_mfma_f32_16x16x32_bf16 v[60:63], v[156:159], v[220:223], v[60:63]
	v_mfma_f32_16x16x32_bf16 v[56:59], v[164:167], v[220:223], v[56:59]
	v_mfma_f32_16x16x32_bf16 v[52:55], v[156:159], v[228:231], v[52:55]
	v_mfma_f32_16x16x32_bf16 v[48:51], v[164:167], v[228:231], v[48:51]
	v_mfma_f32_16x16x32_bf16 v[28:31], v[156:159], v[236:239], v[28:31]
	v_mfma_f32_16x16x32_bf16 v[24:27], v[164:167], v[236:239], v[24:27]
	v_mfma_f32_16x16x32_bf16 v[20:23], v[156:159], v[244:247], v[20:23]
	v_mfma_f32_16x16x32_bf16 v[12:15], v[164:167], v[244:247], v[12:15]
	v_mfma_f32_16x16x32_bf16 v[60:63], v[160:163], v[224:227], v[60:63]
	v_mfma_f32_16x16x32_bf16 v[56:59], v[168:171], v[224:227], v[56:59]
	v_mfma_f32_16x16x32_bf16 v[52:55], v[160:163], v[232:235], v[52:55]
	v_mfma_f32_16x16x32_bf16 v[48:51], v[168:171], v[232:235], v[48:51]
	v_mfma_f32_16x16x32_bf16 v[28:31], v[160:163], v[240:243], v[28:31]
	v_mfma_f32_16x16x32_bf16 v[24:27], v[168:171], v[240:243], v[24:27]
	v_mfma_f32_16x16x32_bf16 v[20:23], v[160:163], v[248:251], v[20:23]
	v_mfma_f32_16x16x32_bf16 v[12:15], v[168:171], v[248:251], v[12:15]
	s_setprio 0
	s_setprio 1
	v_mfma_f32_16x16x32_bf16 v[44:47], v[172:175], v[220:223], v[44:47]
	v_mfma_f32_16x16x32_bf16 v[40:43], v[212:215], v[220:223], v[40:43]
	v_mfma_f32_16x16x32_bf16 v[36:39], v[172:175], v[228:231], v[36:39]
	v_mfma_f32_16x16x32_bf16 v[32:35], v[212:215], v[228:231], v[32:35]
	v_mfma_f32_16x16x32_bf16 v[16:19], v[172:175], v[236:239], v[16:19]
	v_mfma_f32_16x16x32_bf16 v[8:11], v[212:215], v[236:239], v[8:11]
	v_mfma_f32_16x16x32_bf16 v[4:7], v[172:175], v[244:247], v[4:7]
	v_mfma_f32_16x16x32_bf16 v[0:3], v[212:215], v[244:247], v[0:3]
	v_mfma_f32_16x16x32_bf16 v[44:47], v[176:179], v[224:227], v[44:47]
	v_mfma_f32_16x16x32_bf16 v[40:43], v[216:219], v[224:227], v[40:43]
	v_mfma_f32_16x16x32_bf16 v[36:39], v[176:179], v[232:235], v[36:39]
	v_mfma_f32_16x16x32_bf16 v[32:35], v[216:219], v[232:235], v[32:35]
	v_mfma_f32_16x16x32_bf16 v[16:19], v[176:179], v[240:243], v[16:19]
	v_mfma_f32_16x16x32_bf16 v[8:11], v[216:219], v[240:243], v[8:11]
	v_mfma_f32_16x16x32_bf16 v[4:7], v[176:179], v[248:251], v[4:7]
	v_mfma_f32_16x16x32_bf16 v[0:3], v[216:219], v[248:251], v[0:3]
	s_setprio 0
	s_barrier
	s_add_i32 s70, s70, 2
	s_add_u32 s68, s68, 0x10000
	s_addc_u32 s69, s69, 0
	s_add_u32 s36, s36, 0x10000
	s_addc_u32 s37, s37, 0
	s_cmp_gt_u32 s70, 41
	s_cbranch_scc0 .LBB0_1481
	s_and_b64 vcc, exec, s[18:19]
	s_cbranch_vccz .LBB0_1484
	s_barrier

.LBB0_1563:
	ds_read_b128 v[168:171], v165
	ds_read_b128 v[172:175], v165 offset:1024
	ds_read_b128 v[176:179], v165 offset:2048
	ds_read_b128 v[180:183], v165 offset:3072
	ds_read_b128 v[184:187], v166
	ds_read_b128 v[188:191], v166 offset:1024
	ds_read_b128 v[192:195], v166 offset:2048
	ds_read_b128 v[196:199], v166 offset:3072
	s_add_u32 s22, s20, 0xfffc0080
	s_addc_u32 s23, s21, -1
	s_cmp_eq_u32 s49, 12
	s_cselect_b32 s25, s9, s23
	s_cselect_b32 s24, s45, s22
	s_cselect_b32 s23, s11, s48
	s_cselect_b32 s22, s46, s47
	s_add_i32 m0, s17, 0xc000
	ds_read_b128 v[210:213], v167
	ds_read_b128 v[214:217], v167 offset:1024
	ds_read_b128 v[218:221], v167 offset:2048
	ds_read_b128 v[222:225], v167 offset:3072
	ds_read_b128 v[226:229], v167 offset:4096
	ds_read_b128 v[230:233], v167 offset:5120
	ds_read_b128 v[234:237], v167 offset:6144
	ds_read_b128 v[238:241], v167 offset:7168
	global_load_lds_dwordx4 v156, s[20:21]
	s_add_i32 m0, s17, 0xe000
	s_nop 0
	global_load_lds_dwordx4 v154, s[20:21]
	s_waitcnt vmcnt(8)
	s_waitcnt lgkmcnt(0)
	s_barrier
	s_setprio 1
	s_waitcnt lgkmcnt(0)
	v_mfma_f32_16x16x32_bf16 v[124:127], v[168:171], v[210:213], v[124:127]
	v_mfma_f32_16x16x32_bf16 v[116:119], v[176:179], v[210:213], v[116:119]
	v_mfma_f32_16x16x32_bf16 v[108:111], v[168:171], v[218:221], v[108:111]
	v_mfma_f32_16x16x32_bf16 v[100:103], v[176:179], v[218:221], v[100:103]
	v_mfma_f32_16x16x32_bf16 v[92:95], v[168:171], v[226:229], v[92:95]
	v_mfma_f32_16x16x32_bf16 v[84:87], v[176:179], v[226:229], v[84:87]
	v_mfma_f32_16x16x32_bf16 v[76:79], v[168:171], v[234:237], v[76:79]
	v_mfma_f32_16x16x32_bf16 v[68:71], v[176:179], v[234:237], v[68:71]
	v_mfma_f32_16x16x32_bf16 v[124:127], v[172:175], v[214:217], v[124:127]
	v_mfma_f32_16x16x32_bf16 v[116:119], v[180:183], v[214:217], v[116:119]
	v_mfma_f32_16x16x32_bf16 v[108:111], v[172:175], v[222:225], v[108:111]
	v_mfma_f32_16x16x32_bf16 v[100:103], v[180:183], v[222:225], v[100:103]
	v_mfma_f32_16x16x32_bf16 v[92:95], v[172:175], v[230:233], v[92:95]
	v_mfma_f32_16x16x32_bf16 v[84:87], v[180:183], v[230:233], v[84:87]
	v_mfma_f32_16x16x32_bf16 v[76:79], v[172:175], v[238:241], v[76:79]
	v_mfma_f32_16x16x32_bf16 v[68:71], v[180:183], v[238:241], v[68:71]
	s_setprio 0
	s_setprio 1
	v_mfma_f32_16x16x32_bf16 v[120:123], v[184:187], v[210:213], v[120:123]
	v_mfma_f32_16x16x32_bf16 v[112:115], v[192:195], v[210:213], v[112:115]
	v_mfma_f32_16x16x32_bf16 v[104:107], v[184:187], v[218:221], v[104:107]
	v_mfma_f32_16x16x32_bf16 v[96:99], v[192:195], v[218:221], v[96:99]
	v_mfma_f32_16x16x32_bf16 v[88:91], v[184:187], v[226:229], v[88:91]
	v_mfma_f32_16x16x32_bf16 v[80:83], v[192:195], v[226:229], v[80:83]
	v_mfma_f32_16x16x32_bf16 v[72:75], v[184:187], v[234:237], v[72:75]
	v_mfma_f32_16x16x32_bf16 v[64:67], v[192:195], v[234:237], v[64:67]
	v_mfma_f32_16x16x32_bf16 v[120:123], v[188:191], v[214:217], v[120:123]
	v_mfma_f32_16x16x32_bf16 v[112:115], v[196:199], v[214:217], v[112:115]
	v_mfma_f32_16x16x32_bf16 v[104:107], v[188:191], v[222:225], v[104:107]
	v_mfma_f32_16x16x32_bf16 v[96:99], v[196:199], v[222:225], v[96:99]
	v_mfma_f32_16x16x32_bf16 v[88:91], v[188:191], v[230:233], v[88:91]
	v_mfma_f32_16x16x32_bf16 v[80:83], v[196:199], v[230:233], v[80:83]
	v_mfma_f32_16x16x32_bf16 v[72:75], v[188:191], v[238:241], v[72:75]
	v_mfma_f32_16x16x32_bf16 v[64:67], v[196:199], v[238:241], v[64:67]
	s_setprio 0
	s_barrier
	s_add_i32 s50, s43, s33
	s_mov_b32 m0, s50
	ds_read_b128 v[210:213], v167 offset:16384
	ds_read_b128 v[214:217], v167 offset:17408
	ds_read_b128 v[218:221], v167 offset:18432
	ds_read_b128 v[222:225], v167 offset:19456
	ds_read_b128 v[226:229], v167 offset:20480
	ds_read_b128 v[230:233], v167 offset:21504
	ds_read_b128 v[234:237], v167 offset:22528
	ds_read_b128 v[238:241], v167 offset:23552
	global_load_lds_dwordx4 v132, s[22:23]
	s_add_i32 m0, s50, 0x2000
	s_add_u32 s50, s22, 0x4000
	s_addc_u32 s51, s23, 0
	s_add_i32 s52, s44, s33
	global_load_lds_dwordx4 v128, s[22:23]
	s_mov_b32 m0, s52
	v_lshl_add_u64 v[200:201], s[24:25], 0, v[130:131]
	global_load_lds_dwordx4 v132, s[50:51]
	s_add_i32 m0, s52, 0x2000
	s_nop 0
	global_load_lds_dwordx4 v128, s[50:51]
	v_lshl_add_u64 v[162:163], s[24:25], 0, v[134:135]
	s_mov_b32 m0, s17
	s_nop 0
	global_load_lds_dwordx4 v[162:163], off
	s_mov_b32 m0, s19
	s_nop 0
	global_load_lds_dwordx4 v[200:201], off
	s_waitcnt vmcnt(8)
	s_waitcnt lgkmcnt(0)
	s_barrier
	s_setprio 1
	s_waitcnt lgkmcnt(0)
	v_mfma_f32_16x16x32_bf16 v[60:63], v[168:171], v[210:213], v[60:63]
	v_mfma_f32_16x16x32_bf16 v[52:55], v[176:179], v[210:213], v[52:55]
	v_mfma_f32_16x16x32_bf16 v[44:47], v[168:171], v[218:221], v[44:47]
	v_mfma_f32_16x16x32_bf16 v[36:39], v[176:179], v[218:221], v[36:39]
	v_mfma_f32_16x16x32_bf16 v[28:31], v[168:171], v[226:229], v[28:31]
	v_mfma_f32_16x16x32_bf16 v[20:23], v[176:179], v[226:229], v[20:23]
	v_mfma_f32_16x16x32_bf16 v[12:15], v[168:171], v[234:237], v[12:15]
	v_mfma_f32_16x16x32_bf16 v[4:7], v[176:179], v[234:237], v[4:7]
	v_mfma_f32_16x16x32_bf16 v[60:63], v[172:175], v[214:217], v[60:63]
	v_mfma_f32_16x16x32_bf16 v[52:55], v[180:183], v[214:217], v[52:55]
	v_mfma_f32_16x16x32_bf16 v[44:47], v[172:175], v[222:225], v[44:47]
	v_mfma_f32_16x16x32_bf16 v[36:39], v[180:183], v[222:225], v[36:39]
	v_mfma_f32_16x16x32_bf16 v[28:31], v[172:175], v[230:233], v[28:31]
	v_mfma_f32_16x16x32_bf16 v[20:23], v[180:183], v[230:233], v[20:23]
	v_mfma_f32_16x16x32_bf16 v[12:15], v[172:175], v[238:241], v[12:15]
	v_mfma_f32_16x16x32_bf16 v[4:7], v[180:183], v[238:241], v[4:7]
	s_setprio 0
	s_setprio 1
	v_mfma_f32_16x16x32_bf16 v[56:59], v[184:187], v[210:213], v[56:59]
	v_mfma_f32_16x16x32_bf16 v[48:51], v[192:195], v[210:213], v[48:51]
	v_mfma_f32_16x16x32_bf16 v[40:43], v[184:187], v[218:221], v[40:43]
	v_mfma_f32_16x16x32_bf16 v[32:35], v[192:195], v[218:221], v[32:35]
	v_mfma_f32_16x16x32_bf16 v[24:27], v[184:187], v[226:229], v[24:27]
	v_mfma_f32_16x16x32_bf16 v[16:19], v[192:195], v[226:229], v[16:19]
	v_mfma_f32_16x16x32_bf16 v[8:11], v[184:187], v[234:237], v[8:11]
	v_mfma_f32_16x16x32_bf16 v[0:3], v[192:195], v[234:237], v[0:3]
	v_mfma_f32_16x16x32_bf16 v[56:59], v[188:191], v[214:217], v[56:59]
	v_mfma_f32_16x16x32_bf16 v[48:51], v[196:199], v[214:217], v[48:51]
	v_mfma_f32_16x16x32_bf16 v[40:43], v[188:191], v[222:225], v[40:43]
	v_mfma_f32_16x16x32_bf16 v[32:35], v[196:199], v[222:225], v[32:35]
	v_mfma_f32_16x16x32_bf16 v[24:27], v[188:191], v[230:233], v[24:27]
	v_mfma_f32_16x16x32_bf16 v[16:19], v[196:199], v[230:233], v[16:19]
	v_mfma_f32_16x16x32_bf16 v[8:11], v[188:191], v[238:241], v[8:11]
	v_mfma_f32_16x16x32_bf16 v[0:3], v[196:199], v[238:241], v[0:3]
	s_setprio 0
	s_barrier
	s_add_i32 s50, 0, 0x18000
	s_add_i32 s51, 0, 0x1c000
	v_add_u32_e32 v180, s50, v164
	v_add_u32_e32 v196, s51, v164
	ds_read_b128 v[168:171], v180
	ds_read_b128 v[172:175], v180 offset:1024
	ds_read_b128 v[176:179], v180 offset:2048
	ds_read_b128 v[180:183], v180 offset:3072
	ds_read_b128 v[184:187], v196
	ds_read_b128 v[188:191], v196 offset:1024
	ds_read_b128 v[192:195], v196 offset:2048
	ds_read_b128 v[196:199], v196 offset:3072
	s_add_u32 s24, s24, 0x40000
	s_addc_u32 s25, s25, 0
	s_mov_b32 m0, s36
	ds_read_b128 v[210:213], v167 offset:32768
	ds_read_b128 v[214:217], v167 offset:33792
	ds_read_b128 v[218:221], v167 offset:34816
	ds_read_b128 v[222:225], v167 offset:35840
	ds_read_b128 v[226:229], v167 offset:36864
	ds_read_b128 v[230:233], v167 offset:37888
	ds_read_b128 v[234:237], v167 offset:38912
	ds_read_b128 v[238:241], v167 offset:39936
	global_load_lds_dwordx4 v134, s[24:25]
	s_mov_b32 m0, s37
	s_nop 0
	global_load_lds_dwordx4 v130, s[24:25]
	s_waitcnt vmcnt(8)
	s_waitcnt lgkmcnt(0)
	s_barrier
	s_setprio 1
	s_waitcnt lgkmcnt(0)
	v_mfma_f32_16x16x32_bf16 v[124:127], v[168:171], v[210:213], v[124:127]
	v_mfma_f32_16x16x32_bf16 v[116:119], v[176:179], v[210:213], v[116:119]
	v_mfma_f32_16x16x32_bf16 v[108:111], v[168:171], v[218:221], v[108:111]
	v_mfma_f32_16x16x32_bf16 v[100:103], v[176:179], v[218:221], v[100:103]
	v_mfma_f32_16x16x32_bf16 v[92:95], v[168:171], v[226:229], v[92:95]
	v_mfma_f32_16x16x32_bf16 v[84:87], v[176:179], v[226:229], v[84:87]
	v_mfma_f32_16x16x32_bf16 v[76:79], v[168:171], v[234:237], v[76:79]
	v_mfma_f32_16x16x32_bf16 v[68:71], v[176:179], v[234:237], v[68:71]
	v_mfma_f32_16x16x32_bf16 v[124:127], v[172:175], v[214:217], v[124:127]
	v_mfma_f32_16x16x32_bf16 v[116:119], v[180:183], v[214:217], v[116:119]
	v_mfma_f32_16x16x32_bf16 v[108:111], v[172:175], v[222:225], v[108:111]
	v_mfma_f32_16x16x32_bf16 v[100:103], v[180:183], v[222:225], v[100:103]
	v_mfma_f32_16x16x32_bf16 v[92:95], v[172:175], v[230:233], v[92:95]
	v_mfma_f32_16x16x32_bf16 v[84:87], v[180:183], v[230:233], v[84:87]
	v_mfma_f32_16x16x32_bf16 v[76:79], v[172:175], v[238:241], v[76:79]
	v_mfma_f32_16x16x32_bf16 v[68:71], v[180:183], v[238:241], v[68:71]
	s_setprio 0
	s_setprio 1
	v_mfma_f32_16x16x32_bf16 v[120:123], v[184:187], v[210:213], v[120:123]
	v_mfma_f32_16x16x32_bf16 v[112:115], v[192:195], v[210:213], v[112:115]
	v_mfma_f32_16x16x32_bf16 v[104:107], v[184:187], v[218:221], v[104:107]
	v_mfma_f32_16x16x32_bf16 v[96:99], v[192:195], v[218:221], v[96:99]
	v_mfma_f32_16x16x32_bf16 v[88:91], v[184:187], v[226:229], v[88:91]
	v_mfma_f32_16x16x32_bf16 v[80:83], v[192:195], v[226:229], v[80:83]
	v_mfma_f32_16x16x32_bf16 v[72:75], v[184:187], v[234:237], v[72:75]
	v_mfma_f32_16x16x32_bf16 v[64:67], v[192:195], v[234:237], v[64:67]
	v_mfma_f32_16x16x32_bf16 v[120:123], v[188:191], v[214:217], v[120:123]
	v_mfma_f32_16x16x32_bf16 v[112:115], v[196:199], v[214:217], v[112:115]
	v_mfma_f32_16x16x32_bf16 v[104:107], v[188:191], v[222:225], v[104:107]
	v_mfma_f32_16x16x32_bf16 v[96:99], v[196:199], v[222:225], v[96:99]
	v_mfma_f32_16x16x32_bf16 v[88:91], v[188:191], v[230:233], v[88:91]
	v_mfma_f32_16x16x32_bf16 v[80:83], v[196:199], v[230:233], v[80:83]
	v_mfma_f32_16x16x32_bf16 v[72:75], v[188:191], v[238:241], v[72:75]
	v_mfma_f32_16x16x32_bf16 v[64:67], v[196:199], v[238:241], v[64:67]
	s_setprio 0
	s_barrier
	s_add_u32 s24, s22, 0x8000
	s_addc_u32 s25, s23, 0
	s_add_i32 s50, s50, s33
	s_mov_b32 m0, s50
	ds_read_b128 v[210:213], v167 offset:49152
	ds_read_b128 v[214:217], v167 offset:50176
	ds_read_b128 v[218:221], v167 offset:51200
	ds_read_b128 v[222:225], v167 offset:52224
	ds_read_b128 v[226:229], v167 offset:53248
	ds_read_b128 v[230:233], v167 offset:54272
	ds_read_b128 v[234:237], v167 offset:55296
	ds_read_b128 v[238:241], v167 offset:56320
	global_load_lds_dwordx4 v132, s[24:25]
	s_add_i32 m0, s50, 0x2000
	s_add_u32 s22, s22, 0xc000
	v_lshl_add_u64 v[204:205], s[24:25], 0, v[128:129]
	s_addc_u32 s23, s23, 0
	s_add_i32 s24, s51, s33
	global_load_lds_dwordx4 v[204:205], off
	s_mov_b32 m0, s24
	v_lshl_add_u64 v[162:163], v[162:163], 0, s[4:5]
	global_load_lds_dwordx4 v132, s[22:23]
	s_add_i32 m0, s24, 0x2000
	s_nop 0
	global_load_lds_dwordx4 v128, s[22:23]
	s_mov_b32 m0, s40
	s_nop 0
	global_load_lds_dwordx4 v[162:163], off
	v_lshl_add_u64 v[162:163], v[200:201], 0, s[4:5]
	s_mov_b32 m0, s41
	s_nop 0
	global_load_lds_dwordx4 v[162:163], off
	s_waitcnt vmcnt(8)
	s_waitcnt lgkmcnt(0)
	s_barrier
	s_setprio 1
	s_waitcnt lgkmcnt(0)
	v_mfma_f32_16x16x32_bf16 v[60:63], v[168:171], v[210:213], v[60:63]
	v_mfma_f32_16x16x32_bf16 v[52:55], v[176:179], v[210:213], v[52:55]
	v_mfma_f32_16x16x32_bf16 v[44:47], v[168:171], v[218:221], v[44:47]
	v_mfma_f32_16x16x32_bf16 v[36:39], v[176:179], v[218:221], v[36:39]
	v_mfma_f32_16x16x32_bf16 v[28:31], v[168:171], v[226:229], v[28:31]
	v_mfma_f32_16x16x32_bf16 v[20:23], v[176:179], v[226:229], v[20:23]
	v_mfma_f32_16x16x32_bf16 v[12:15], v[168:171], v[234:237], v[12:15]
	v_mfma_f32_16x16x32_bf16 v[4:7], v[176:179], v[234:237], v[4:7]
	v_mfma_f32_16x16x32_bf16 v[60:63], v[172:175], v[214:217], v[60:63]
	v_mfma_f32_16x16x32_bf16 v[52:55], v[180:183], v[214:217], v[52:55]
	v_mfma_f32_16x16x32_bf16 v[44:47], v[172:175], v[222:225], v[44:47]
	v_mfma_f32_16x16x32_bf16 v[36:39], v[180:183], v[222:225], v[36:39]
	v_mfma_f32_16x16x32_bf16 v[28:31], v[172:175], v[230:233], v[28:31]
	v_mfma_f32_16x16x32_bf16 v[20:23], v[180:183], v[230:233], v[20:23]
	v_mfma_f32_16x16x32_bf16 v[12:15], v[172:175], v[238:241], v[12:15]
	v_mfma_f32_16x16x32_bf16 v[4:7], v[180:183], v[238:241], v[4:7]
	s_setprio 0
	s_setprio 1
	v_mfma_f32_16x16x32_bf16 v[56:59], v[184:187], v[210:213], v[56:59]
	v_mfma_f32_16x16x32_bf16 v[48:51], v[192:195], v[210:213], v[48:51]
	v_mfma_f32_16x16x32_bf16 v[40:43], v[184:187], v[218:221], v[40:43]
	v_mfma_f32_16x16x32_bf16 v[32:35], v[192:195], v[218:221], v[32:35]
	v_mfma_f32_16x16x32_bf16 v[24:27], v[184:187], v[226:229], v[24:27]
	v_mfma_f32_16x16x32_bf16 v[16:19], v[192:195], v[226:229], v[16:19]
	v_mfma_f32_16x16x32_bf16 v[8:11], v[184:187], v[234:237], v[8:11]
	v_mfma_f32_16x16x32_bf16 v[0:3], v[192:195], v[234:237], v[0:3]
	v_mfma_f32_16x16x32_bf16 v[56:59], v[188:191], v[214:217], v[56:59]
	v_mfma_f32_16x16x32_bf16 v[48:51], v[196:199], v[214:217], v[48:51]
	v_mfma_f32_16x16x32_bf16 v[40:43], v[188:191], v[222:225], v[40:43]
	v_mfma_f32_16x16x32_bf16 v[32:35], v[196:199], v[222:225], v[32:35]
	v_mfma_f32_16x16x32_bf16 v[24:27], v[188:191], v[230:233], v[24:27]
	v_mfma_f32_16x16x32_bf16 v[16:19], v[196:199], v[230:233], v[16:19]
	v_mfma_f32_16x16x32_bf16 v[8:11], v[188:191], v[238:241], v[8:11]
	v_mfma_f32_16x16x32_bf16 v[0:3], v[196:199], v[238:241], v[0:3]
	s_setprio 0
	s_barrier
	s_add_i32 s49, s49, 2
	s_add_u32 s47, s47, 0x10000
	s_addc_u32 s48, s48, 0
	s_add_u32 s20, s20, 0x100
	s_addc_u32 s21, s21, 0
	s_cmp_gt_u32 s49, 13
	s_cbranch_scc0 .LBB0_1563
	s_and_b64 vcc, exec, s[6:7]
	s_cbranch_vccz .LBB0_1566
	s_barrier

.LBB0_1645:
	v_add_u32_e32 v168, s69, v182
	v_add_u32_e32 v204, s70, v182
	ds_read_b128 v[156:159], v168
	ds_read_b128 v[160:163], v168 offset:1024
	ds_read_b128 v[164:167], v168 offset:2048
	ds_read_b128 v[168:171], v168 offset:3072
	ds_read_b128 v[172:175], v204
	ds_read_b128 v[176:179], v204 offset:1024
	ds_read_b128 v[212:215], v204 offset:2048
	ds_read_b128 v[216:219], v204 offset:3072
	s_add_u32 s38, s36, 0x4000
	s_addc_u32 s39, s37, 0
	s_cmp_eq_u32 s47, 40
	s_cselect_b32 s42, s0, s38
	s_cselect_b32 s43, s1, s39
	s_cselect_b32 s40, s34, s45
	s_cselect_b32 s41, s35, s46
	s_add_u32 s38, s42, 0x8000
	s_addc_u32 s39, s43, 0
	s_add_i32 m0, s56, 0xc000
	ds_read_b128 v[220:223], v199
	ds_read_b128 v[224:227], v199 offset:1024
	ds_read_b128 v[228:231], v199 offset:2048
	ds_read_b128 v[232:235], v199 offset:3072
	ds_read_b128 v[236:239], v199 offset:4096
	ds_read_b128 v[240:243], v199 offset:5120
	ds_read_b128 v[244:247], v199 offset:6144
	ds_read_b128 v[248:251], v199 offset:7168
	global_load_lds_dwordx4 v150, s[36:37]
	s_add_i32 m0, s56, 0xe000
	s_nop 0
	global_load_lds_dwordx4 v148, s[36:37]
	s_waitcnt vmcnt(8)
	s_waitcnt lgkmcnt(0)
	s_barrier
	s_setprio 1
	s_waitcnt lgkmcnt(0)
	v_mfma_f32_16x16x32_bf16 v[124:127], v[156:159], v[220:223], v[124:127]
	v_mfma_f32_16x16x32_bf16 v[120:123], v[164:167], v[220:223], v[120:123]
	v_mfma_f32_16x16x32_bf16 v[116:119], v[156:159], v[228:231], v[116:119]
	v_mfma_f32_16x16x32_bf16 v[112:115], v[164:167], v[228:231], v[112:115]
	v_mfma_f32_16x16x32_bf16 v[92:95], v[156:159], v[236:239], v[92:95]
	v_mfma_f32_16x16x32_bf16 v[88:91], v[164:167], v[236:239], v[88:91]
	v_mfma_f32_16x16x32_bf16 v[84:87], v[156:159], v[244:247], v[84:87]
	v_mfma_f32_16x16x32_bf16 v[80:83], v[164:167], v[244:247], v[80:83]
	v_mfma_f32_16x16x32_bf16 v[124:127], v[160:163], v[224:227], v[124:127]
	v_mfma_f32_16x16x32_bf16 v[120:123], v[168:171], v[224:227], v[120:123]
	v_mfma_f32_16x16x32_bf16 v[116:119], v[160:163], v[232:235], v[116:119]
	v_mfma_f32_16x16x32_bf16 v[112:115], v[168:171], v[232:235], v[112:115]
	v_mfma_f32_16x16x32_bf16 v[92:95], v[160:163], v[240:243], v[92:95]
	v_mfma_f32_16x16x32_bf16 v[88:91], v[168:171], v[240:243], v[88:91]
	v_mfma_f32_16x16x32_bf16 v[84:87], v[160:163], v[248:251], v[84:87]
	v_mfma_f32_16x16x32_bf16 v[80:83], v[168:171], v[248:251], v[80:83]
	s_setprio 0
	s_setprio 1
	v_mfma_f32_16x16x32_bf16 v[108:111], v[172:175], v[220:223], v[108:111]
	v_mfma_f32_16x16x32_bf16 v[104:107], v[212:215], v[220:223], v[104:107]
	v_mfma_f32_16x16x32_bf16 v[100:103], v[172:175], v[228:231], v[100:103]
	v_mfma_f32_16x16x32_bf16 v[96:99], v[212:215], v[228:231], v[96:99]
	v_mfma_f32_16x16x32_bf16 v[76:79], v[172:175], v[236:239], v[76:79]
	v_mfma_f32_16x16x32_bf16 v[72:75], v[212:215], v[236:239], v[72:75]
	v_mfma_f32_16x16x32_bf16 v[68:71], v[172:175], v[244:247], v[68:71]
	v_mfma_f32_16x16x32_bf16 v[64:67], v[212:215], v[244:247], v[64:67]
	v_mfma_f32_16x16x32_bf16 v[108:111], v[176:179], v[224:227], v[108:111]
	v_mfma_f32_16x16x32_bf16 v[104:107], v[216:219], v[224:227], v[104:107]
	v_mfma_f32_16x16x32_bf16 v[100:103], v[176:179], v[232:235], v[100:103]
	v_mfma_f32_16x16x32_bf16 v[96:99], v[216:219], v[232:235], v[96:99]
	v_mfma_f32_16x16x32_bf16 v[76:79], v[176:179], v[240:243], v[76:79]
	v_mfma_f32_16x16x32_bf16 v[72:75], v[216:219], v[240:243], v[72:75]
	v_mfma_f32_16x16x32_bf16 v[68:71], v[176:179], v[248:251], v[68:71]
	v_mfma_f32_16x16x32_bf16 v[64:67], v[216:219], v[248:251], v[64:67]
	s_setprio 0
	s_barrier
	s_add_i32 s48, s69, s55
	s_mov_b32 m0, s48
	ds_read_b128 v[220:223], v199 offset:16384
	ds_read_b128 v[224:227], v199 offset:17408
	ds_read_b128 v[228:231], v199 offset:18432
	ds_read_b128 v[232:235], v199 offset:19456
	ds_read_b128 v[236:239], v199 offset:20480
	ds_read_b128 v[240:243], v199 offset:21504
	ds_read_b128 v[244:247], v199 offset:22528
	ds_read_b128 v[248:251], v199 offset:23552
	global_load_lds_dwordx4 v128, s[40:41]
	s_add_i32 m0, s48, 0x2000
	s_add_u32 s48, s40, 0x4000
	s_addc_u32 s49, s41, 0
	s_add_i32 s50, s70, s55
	global_load_lds_dwordx4 v130, s[40:41]
	s_mov_b32 m0, s50
	s_nop 0
	global_load_lds_dwordx4 v128, s[48:49]
	s_add_i32 m0, s50, 0x2000
	s_nop 0
	global_load_lds_dwordx4 v130, s[48:49]
	s_mov_b32 m0, s56
	s_nop 0
	global_load_lds_dwordx4 v128, s[42:43]
	v_lshl_add_u64 v[204:205], s[42:43], 0, v[130:131]
	s_mov_b32 m0, s57
	s_nop 0
	global_load_lds_dwordx4 v[204:205], off
	s_waitcnt vmcnt(8)
	s_waitcnt lgkmcnt(0)
	s_barrier
	s_setprio 1
	s_waitcnt lgkmcnt(0)
	v_mfma_f32_16x16x32_bf16 v[60:63], v[156:159], v[220:223], v[60:63]
	v_mfma_f32_16x16x32_bf16 v[56:59], v[164:167], v[220:223], v[56:59]
	v_mfma_f32_16x16x32_bf16 v[52:55], v[156:159], v[228:231], v[52:55]
	v_mfma_f32_16x16x32_bf16 v[48:51], v[164:167], v[228:231], v[48:51]
	v_mfma_f32_16x16x32_bf16 v[28:31], v[156:159], v[236:239], v[28:31]
	v_mfma_f32_16x16x32_bf16 v[24:27], v[164:167], v[236:239], v[24:27]
	v_mfma_f32_16x16x32_bf16 v[20:23], v[156:159], v[244:247], v[20:23]
	v_mfma_f32_16x16x32_bf16 v[12:15], v[164:167], v[244:247], v[12:15]
	v_mfma_f32_16x16x32_bf16 v[60:63], v[160:163], v[224:227], v[60:63]
	v_mfma_f32_16x16x32_bf16 v[56:59], v[168:171], v[224:227], v[56:59]
	v_mfma_f32_16x16x32_bf16 v[52:55], v[160:163], v[232:235], v[52:55]
	v_mfma_f32_16x16x32_bf16 v[48:51], v[168:171], v[232:235], v[48:51]
	v_mfma_f32_16x16x32_bf16 v[28:31], v[160:163], v[240:243], v[28:31]
	v_mfma_f32_16x16x32_bf16 v[24:27], v[168:171], v[240:243], v[24:27]
	v_mfma_f32_16x16x32_bf16 v[20:23], v[160:163], v[248:251], v[20:23]
	v_mfma_f32_16x16x32_bf16 v[12:15], v[168:171], v[248:251], v[12:15]
	s_setprio 0
	s_setprio 1
	v_mfma_f32_16x16x32_bf16 v[44:47], v[172:175], v[220:223], v[44:47]
	v_mfma_f32_16x16x32_bf16 v[40:43], v[212:215], v[220:223], v[40:43]
	v_mfma_f32_16x16x32_bf16 v[36:39], v[172:175], v[228:231], v[36:39]
	v_mfma_f32_16x16x32_bf16 v[32:35], v[212:215], v[228:231], v[32:35]
	v_mfma_f32_16x16x32_bf16 v[16:19], v[172:175], v[236:239], v[16:19]
	v_mfma_f32_16x16x32_bf16 v[8:11], v[212:215], v[236:239], v[8:11]
	v_mfma_f32_16x16x32_bf16 v[4:7], v[172:175], v[244:247], v[4:7]
	v_mfma_f32_16x16x32_bf16 v[0:3], v[212:215], v[244:247], v[0:3]
	v_mfma_f32_16x16x32_bf16 v[44:47], v[176:179], v[224:227], v[44:47]
	v_mfma_f32_16x16x32_bf16 v[40:43], v[216:219], v[224:227], v[40:43]
	v_mfma_f32_16x16x32_bf16 v[36:39], v[176:179], v[232:235], v[36:39]
	v_mfma_f32_16x16x32_bf16 v[32:35], v[216:219], v[232:235], v[32:35]
	v_mfma_f32_16x16x32_bf16 v[16:19], v[176:179], v[240:243], v[16:19]
	v_mfma_f32_16x16x32_bf16 v[8:11], v[216:219], v[240:243], v[8:11]
	v_mfma_f32_16x16x32_bf16 v[4:7], v[176:179], v[248:251], v[4:7]
	v_mfma_f32_16x16x32_bf16 v[0:3], v[216:219], v[248:251], v[0:3]
	s_setprio 0
	s_barrier
	s_add_i32 s48, 0, 0x18000
	s_add_i32 s49, 0, 0x1c000
	v_add_u32_e32 v168, s48, v182
	v_add_u32_e32 v204, s49, v182
	ds_read_b128 v[156:159], v168
	ds_read_b128 v[160:163], v168 offset:1024
	ds_read_b128 v[164:167], v168 offset:2048
	ds_read_b128 v[168:171], v168 offset:3072
	ds_read_b128 v[172:175], v204
	ds_read_b128 v[176:179], v204 offset:1024
	ds_read_b128 v[212:215], v204 offset:2048
	ds_read_b128 v[216:219], v204 offset:3072
	s_add_u32 s42, s42, 0x4000
	s_addc_u32 s43, s43, 0
	s_mov_b32 m0, s58
	ds_read_b128 v[220:223], v199 offset:32768
	ds_read_b128 v[224:227], v199 offset:33792
	ds_read_b128 v[228:231], v199 offset:34816
	ds_read_b128 v[232:235], v199 offset:35840
	ds_read_b128 v[236:239], v199 offset:36864
	ds_read_b128 v[240:243], v199 offset:37888
	ds_read_b128 v[244:247], v199 offset:38912
	ds_read_b128 v[248:251], v199 offset:39936
	global_load_lds_dwordx4 v128, s[42:43]
	s_mov_b32 m0, s59
	s_nop 0
	global_load_lds_dwordx4 v130, s[42:43]
	s_waitcnt vmcnt(8)
	s_waitcnt lgkmcnt(0)
	s_barrier
	s_setprio 1
	s_waitcnt lgkmcnt(0)
	v_mfma_f32_16x16x32_bf16 v[124:127], v[156:159], v[220:223], v[124:127]
	v_mfma_f32_16x16x32_bf16 v[120:123], v[164:167], v[220:223], v[120:123]
	v_mfma_f32_16x16x32_bf16 v[116:119], v[156:159], v[228:231], v[116:119]
	v_mfma_f32_16x16x32_bf16 v[112:115], v[164:167], v[228:231], v[112:115]
	v_mfma_f32_16x16x32_bf16 v[92:95], v[156:159], v[236:239], v[92:95]
	v_mfma_f32_16x16x32_bf16 v[88:91], v[164:167], v[236:239], v[88:91]
	v_mfma_f32_16x16x32_bf16 v[84:87], v[156:159], v[244:247], v[84:87]
	v_mfma_f32_16x16x32_bf16 v[80:83], v[164:167], v[244:247], v[80:83]
	v_mfma_f32_16x16x32_bf16 v[124:127], v[160:163], v[224:227], v[124:127]
	v_mfma_f32_16x16x32_bf16 v[120:123], v[168:171], v[224:227], v[120:123]
	v_mfma_f32_16x16x32_bf16 v[116:119], v[160:163], v[232:235], v[116:119]
	v_mfma_f32_16x16x32_bf16 v[112:115], v[168:171], v[232:235], v[112:115]
	v_mfma_f32_16x16x32_bf16 v[92:95], v[160:163], v[240:243], v[92:95]
	v_mfma_f32_16x16x32_bf16 v[88:91], v[168:171], v[240:243], v[88:91]
	v_mfma_f32_16x16x32_bf16 v[84:87], v[160:163], v[248:251], v[84:87]
	v_mfma_f32_16x16x32_bf16 v[80:83], v[168:171], v[248:251], v[80:83]
	s_setprio 0
	s_setprio 1
	v_mfma_f32_16x16x32_bf16 v[108:111], v[172:175], v[220:223], v[108:111]
	v_mfma_f32_16x16x32_bf16 v[104:107], v[212:215], v[220:223], v[104:107]
	v_mfma_f32_16x16x32_bf16 v[100:103], v[172:175], v[228:231], v[100:103]
	v_mfma_f32_16x16x32_bf16 v[96:99], v[212:215], v[228:231], v[96:99]
	v_mfma_f32_16x16x32_bf16 v[76:79], v[172:175], v[236:239], v[76:79]
	v_mfma_f32_16x16x32_bf16 v[72:75], v[212:215], v[236:239], v[72:75]
	v_mfma_f32_16x16x32_bf16 v[68:71], v[172:175], v[244:247], v[68:71]
	v_mfma_f32_16x16x32_bf16 v[64:67], v[212:215], v[244:247], v[64:67]
	v_mfma_f32_16x16x32_bf16 v[108:111], v[176:179], v[224:227], v[108:111]
	v_mfma_f32_16x16x32_bf16 v[104:107], v[216:219], v[224:227], v[104:107]
	v_mfma_f32_16x16x32_bf16 v[100:103], v[176:179], v[232:235], v[100:103]
	v_mfma_f32_16x16x32_bf16 v[96:99], v[216:219], v[232:235], v[96:99]
	v_mfma_f32_16x16x32_bf16 v[76:79], v[176:179], v[240:243], v[76:79]
	v_mfma_f32_16x16x32_bf16 v[72:75], v[216:219], v[240:243], v[72:75]
	v_mfma_f32_16x16x32_bf16 v[68:71], v[176:179], v[248:251], v[68:71]
	v_mfma_f32_16x16x32_bf16 v[64:67], v[216:219], v[248:251], v[64:67]
	s_setprio 0
	s_barrier
	s_add_u32 s42, s40, 0x8000
	s_addc_u32 s43, s41, 0
	s_add_i32 s48, s48, s55
	s_mov_b32 m0, s48
	ds_read_b128 v[220:223], v199 offset:49152
	ds_read_b128 v[224:227], v199 offset:50176
	ds_read_b128 v[228:231], v199 offset:51200
	ds_read_b128 v[232:235], v199 offset:52224
	ds_read_b128 v[236:239], v199 offset:53248
	ds_read_b128 v[240:243], v199 offset:54272
	ds_read_b128 v[244:247], v199 offset:55296
	ds_read_b128 v[248:251], v199 offset:56320
	global_load_lds_dwordx4 v128, s[42:43]
	s_add_i32 m0, s48, 0x2000
	s_add_u32 s40, s40, 0xc000
	v_lshl_add_u64 v[204:205], s[42:43], 0, v[130:131]
	s_addc_u32 s41, s41, 0
	s_add_i32 s42, s49, s55
	global_load_lds_dwordx4 v[204:205], off
	s_mov_b32 m0, s42
	s_nop 0
	global_load_lds_dwordx4 v128, s[40:41]
	s_add_i32 m0, s42, 0x2000
	s_nop 0
	global_load_lds_dwordx4 v130, s[40:41]
	s_mov_b32 m0, s65
	s_nop 0
	global_load_lds_dwordx4 v128, s[38:39]
	v_lshl_add_u64 v[204:205], s[38:39], 0, v[130:131]
	s_mov_b32 m0, s66
	s_nop 0
	global_load_lds_dwordx4 v[204:205], off
	s_waitcnt vmcnt(8)
	s_waitcnt lgkmcnt(0)
	s_barrier
	s_setprio 1
	s_waitcnt lgkmcnt(0)
	v_mfma_f32_16x16x32_bf16 v[60:63], v[156:159], v[220:223], v[60:63]
	v_mfma_f32_16x16x32_bf16 v[56:59], v[164:167], v[220:223], v[56:59]
	v_mfma_f32_16x16x32_bf16 v[52:55], v[156:159], v[228:231], v[52:55]
	v_mfma_f32_16x16x32_bf16 v[48:51], v[164:167], v[228:231], v[48:51]
	v_mfma_f32_16x16x32_bf16 v[28:31], v[156:159], v[236:239], v[28:31]
	v_mfma_f32_16x16x32_bf16 v[24:27], v[164:167], v[236:239], v[24:27]
	v_mfma_f32_16x16x32_bf16 v[20:23], v[156:159], v[244:247], v[20:23]
	v_mfma_f32_16x16x32_bf16 v[12:15], v[164:167], v[244:247], v[12:15]
	v_mfma_f32_16x16x32_bf16 v[60:63], v[160:163], v[224:227], v[60:63]
	v_mfma_f32_16x16x32_bf16 v[56:59], v[168:171], v[224:227], v[56:59]
	v_mfma_f32_16x16x32_bf16 v[52:55], v[160:163], v[232:235], v[52:55]
	v_mfma_f32_16x16x32_bf16 v[48:51], v[168:171], v[232:235], v[48:51]
	v_mfma_f32_16x16x32_bf16 v[28:31], v[160:163], v[240:243], v[28:31]
	v_mfma_f32_16x16x32_bf16 v[24:27], v[168:171], v[240:243], v[24:27]
	v_mfma_f32_16x16x32_bf16 v[20:23], v[160:163], v[248:251], v[20:23]
	v_mfma_f32_16x16x32_bf16 v[12:15], v[168:171], v[248:251], v[12:15]
	s_setprio 0
	s_setprio 1
	v_mfma_f32_16x16x32_bf16 v[44:47], v[172:175], v[220:223], v[44:47]
	v_mfma_f32_16x16x32_bf16 v[40:43], v[212:215], v[220:223], v[40:43]
	v_mfma_f32_16x16x32_bf16 v[36:39], v[172:175], v[228:231], v[36:39]
	v_mfma_f32_16x16x32_bf16 v[32:35], v[212:215], v[228:231], v[32:35]
	v_mfma_f32_16x16x32_bf16 v[16:19], v[172:175], v[236:239], v[16:19]
	v_mfma_f32_16x16x32_bf16 v[8:11], v[212:215], v[236:239], v[8:11]
	v_mfma_f32_16x16x32_bf16 v[4:7], v[172:175], v[244:247], v[4:7]
	v_mfma_f32_16x16x32_bf16 v[0:3], v[212:215], v[244:247], v[0:3]
	v_mfma_f32_16x16x32_bf16 v[44:47], v[176:179], v[224:227], v[44:47]
	v_mfma_f32_16x16x32_bf16 v[40:43], v[216:219], v[224:227], v[40:43]
	v_mfma_f32_16x16x32_bf16 v[36:39], v[176:179], v[232:235], v[36:39]
	v_mfma_f32_16x16x32_bf16 v[32:35], v[216:219], v[232:235], v[32:35]
	v_mfma_f32_16x16x32_bf16 v[16:19], v[176:179], v[240:243], v[16:19]
	v_mfma_f32_16x16x32_bf16 v[8:11], v[216:219], v[240:243], v[8:11]
	v_mfma_f32_16x16x32_bf16 v[4:7], v[176:179], v[248:251], v[4:7]
	v_mfma_f32_16x16x32_bf16 v[0:3], v[216:219], v[248:251], v[0:3]
	s_setprio 0
	s_barrier
	s_add_i32 s47, s47, 2
	s_add_u32 s45, s45, 0x10000
	s_addc_u32 s46, s46, 0
	s_add_u32 s36, s36, 0x10000
	s_addc_u32 s37, s37, 0
	s_cmp_gt_u32 s47, 41
	s_cbranch_scc0 .LBB0_1645
	s_and_b64 vcc, exec, s[2:3]
	s_cbranch_vccz .LBB0_1648
	s_barrier

.LBB0_1729:
	ds_read_b128 v[128:131], v210
	ds_read_b128 v[132:135], v210 offset:1024
	ds_read_b128 v[136:139], v210 offset:2048
	ds_read_b128 v[140:143], v210 offset:3072
	ds_read_b128 v[144:147], v211
	ds_read_b128 v[148:151], v211 offset:1024
	ds_read_b128 v[152:155], v211 offset:2048
	ds_read_b128 v[156:159], v211 offset:3072
	s_add_u32 s26, s6, 0xfffc0080
	s_addc_u32 s27, s7, -1
	s_cmp_eq_u32 s35, 12
	s_cselect_b32 s29, s1, s27
	s_cselect_b32 s28, s19, s26
	s_cselect_b32 s27, s21, s34
	s_cselect_b32 s26, s30, s31
	s_add_i32 m0, s42, 0xc000
	ds_read_b128 v[160:163], v212
	ds_read_b128 v[164:167], v212 offset:1024
	ds_read_b128 v[194:197], v212 offset:2048
	ds_read_b128 v[214:217], v212 offset:3072
	ds_read_b128 v[218:221], v212 offset:4096
	ds_read_b128 v[222:225], v212 offset:5120
	ds_read_b128 v[226:229], v212 offset:6144
	ds_read_b128 v[230:233], v212 offset:7168
	global_load_lds_dwordx4 v188, s[6:7]
	s_add_i32 m0, s42, 0xe000
	s_nop 0
	global_load_lds_dwordx4 v186, s[6:7]
	s_waitcnt vmcnt(8)
	s_waitcnt lgkmcnt(0)
	s_barrier
	s_setprio 1
	s_waitcnt lgkmcnt(0)
	v_mfma_f32_16x16x32_bf16 v[124:127], v[128:131], v[160:163], v[124:127]
	v_mfma_f32_16x16x32_bf16 v[120:123], v[136:139], v[160:163], v[120:123]
	v_mfma_f32_16x16x32_bf16 v[116:119], v[128:131], v[194:197], v[116:119]
	v_mfma_f32_16x16x32_bf16 v[112:115], v[136:139], v[194:197], v[112:115]
	v_mfma_f32_16x16x32_bf16 v[108:111], v[128:131], v[218:221], v[108:111]
	v_mfma_f32_16x16x32_bf16 v[104:107], v[136:139], v[218:221], v[104:107]
	v_mfma_f32_16x16x32_bf16 v[100:103], v[128:131], v[226:229], v[100:103]
	v_mfma_f32_16x16x32_bf16 v[96:99], v[136:139], v[226:229], v[96:99]
	v_mfma_f32_16x16x32_bf16 v[124:127], v[132:135], v[164:167], v[124:127]
	v_mfma_f32_16x16x32_bf16 v[120:123], v[140:143], v[164:167], v[120:123]
	v_mfma_f32_16x16x32_bf16 v[116:119], v[132:135], v[214:217], v[116:119]
	v_mfma_f32_16x16x32_bf16 v[112:115], v[140:143], v[214:217], v[112:115]
	v_mfma_f32_16x16x32_bf16 v[108:111], v[132:135], v[222:225], v[108:111]
	v_mfma_f32_16x16x32_bf16 v[104:107], v[140:143], v[222:225], v[104:107]
	v_mfma_f32_16x16x32_bf16 v[100:103], v[132:135], v[230:233], v[100:103]
	v_mfma_f32_16x16x32_bf16 v[96:99], v[140:143], v[230:233], v[96:99]
	s_setprio 0
	s_setprio 1
	v_mfma_f32_16x16x32_bf16 v[60:63], v[144:147], v[160:163], v[60:63]
	v_mfma_f32_16x16x32_bf16 v[56:59], v[152:155], v[160:163], v[56:59]
	v_mfma_f32_16x16x32_bf16 v[52:55], v[144:147], v[194:197], v[52:55]
	v_mfma_f32_16x16x32_bf16 v[48:51], v[152:155], v[194:197], v[48:51]
	v_mfma_f32_16x16x32_bf16 v[44:47], v[144:147], v[218:221], v[44:47]
	v_mfma_f32_16x16x32_bf16 v[40:43], v[152:155], v[218:221], v[40:43]
	v_mfma_f32_16x16x32_bf16 v[36:39], v[144:147], v[226:229], v[36:39]
	v_mfma_f32_16x16x32_bf16 v[32:35], v[152:155], v[226:229], v[32:35]
	v_mfma_f32_16x16x32_bf16 v[60:63], v[148:151], v[164:167], v[60:63]
	v_mfma_f32_16x16x32_bf16 v[56:59], v[156:159], v[164:167], v[56:59]
	v_mfma_f32_16x16x32_bf16 v[52:55], v[148:151], v[214:217], v[52:55]
	v_mfma_f32_16x16x32_bf16 v[48:51], v[156:159], v[214:217], v[48:51]
	v_mfma_f32_16x16x32_bf16 v[44:47], v[148:151], v[222:225], v[44:47]
	v_mfma_f32_16x16x32_bf16 v[40:43], v[156:159], v[222:225], v[40:43]
	v_mfma_f32_16x16x32_bf16 v[36:39], v[148:151], v[230:233], v[36:39]
	v_mfma_f32_16x16x32_bf16 v[32:35], v[156:159], v[230:233], v[32:35]
	s_setprio 0
	s_barrier
	s_add_i32 s61, s56, s41
	s_mov_b32 m0, s61
	ds_read_b128 v[160:163], v212 offset:16384
	ds_read_b128 v[164:167], v212 offset:17408
	ds_read_b128 v[194:197], v212 offset:18432
	ds_read_b128 v[214:217], v212 offset:19456
	ds_read_b128 v[218:221], v212 offset:20480
	ds_read_b128 v[222:225], v212 offset:21504
	ds_read_b128 v[226:229], v212 offset:22528
	ds_read_b128 v[230:233], v212 offset:23552
	global_load_lds_dwordx4 v170, s[26:27]
	s_add_i32 m0, s61, 0x2000
	s_add_u32 s62, s26, 0x4000
	s_addc_u32 s63, s27, 0
	s_add_i32 s61, s57, s41
	global_load_lds_dwordx4 v174, s[26:27]
	s_mov_b32 m0, s61
	v_lshl_add_u64 v[204:205], s[28:29], 0, v[172:173]
	global_load_lds_dwordx4 v170, s[62:63]
	s_add_i32 m0, s61, 0x2000
	s_nop 0
	global_load_lds_dwordx4 v174, s[62:63]
	v_lshl_add_u64 v[198:199], s[28:29], 0, v[168:169]
	s_mov_b32 m0, s42
	s_nop 0
	global_load_lds_dwordx4 v[198:199], off
	s_mov_b32 m0, s43
	s_nop 0
	global_load_lds_dwordx4 v[204:205], off
	s_waitcnt vmcnt(8)
	s_waitcnt lgkmcnt(0)
	s_barrier
	s_setprio 1
	s_waitcnt lgkmcnt(0)
	v_mfma_f32_16x16x32_bf16 v[92:95], v[128:131], v[160:163], v[92:95]
	v_mfma_f32_16x16x32_bf16 v[88:91], v[136:139], v[160:163], v[88:91]
	v_mfma_f32_16x16x32_bf16 v[84:87], v[128:131], v[194:197], v[84:87]
	v_mfma_f32_16x16x32_bf16 v[80:83], v[136:139], v[194:197], v[80:83]
	v_mfma_f32_16x16x32_bf16 v[76:79], v[128:131], v[218:221], v[76:79]
	v_mfma_f32_16x16x32_bf16 v[72:75], v[136:139], v[218:221], v[72:75]
	v_mfma_f32_16x16x32_bf16 v[68:71], v[128:131], v[226:229], v[68:71]
	v_mfma_f32_16x16x32_bf16 v[64:67], v[136:139], v[226:229], v[64:67]
	v_mfma_f32_16x16x32_bf16 v[92:95], v[132:135], v[164:167], v[92:95]
	v_mfma_f32_16x16x32_bf16 v[88:91], v[140:143], v[164:167], v[88:91]
	v_mfma_f32_16x16x32_bf16 v[84:87], v[132:135], v[214:217], v[84:87]
	v_mfma_f32_16x16x32_bf16 v[80:83], v[140:143], v[214:217], v[80:83]
	v_mfma_f32_16x16x32_bf16 v[76:79], v[132:135], v[222:225], v[76:79]
	v_mfma_f32_16x16x32_bf16 v[72:75], v[140:143], v[222:225], v[72:75]
	v_mfma_f32_16x16x32_bf16 v[68:71], v[132:135], v[230:233], v[68:71]
	v_mfma_f32_16x16x32_bf16 v[64:67], v[140:143], v[230:233], v[64:67]
	s_setprio 0
	s_setprio 1
	v_mfma_f32_16x16x32_bf16 v[28:31], v[144:147], v[160:163], v[28:31]
	v_mfma_f32_16x16x32_bf16 v[24:27], v[152:155], v[160:163], v[24:27]
	v_mfma_f32_16x16x32_bf16 v[20:23], v[144:147], v[194:197], v[20:23]
	v_mfma_f32_16x16x32_bf16 v[16:19], v[152:155], v[194:197], v[16:19]
	v_mfma_f32_16x16x32_bf16 v[12:15], v[144:147], v[218:221], v[12:15]
	v_mfma_f32_16x16x32_bf16 v[8:11], v[152:155], v[218:221], v[8:11]
	v_mfma_f32_16x16x32_bf16 v[4:7], v[144:147], v[226:229], v[4:7]
	v_mfma_f32_16x16x32_bf16 v[0:3], v[152:155], v[226:229], v[0:3]
	v_mfma_f32_16x16x32_bf16 v[28:31], v[148:151], v[164:167], v[28:31]
	v_mfma_f32_16x16x32_bf16 v[24:27], v[156:159], v[164:167], v[24:27]
	v_mfma_f32_16x16x32_bf16 v[20:23], v[148:151], v[214:217], v[20:23]
	v_mfma_f32_16x16x32_bf16 v[16:19], v[156:159], v[214:217], v[16:19]
	v_mfma_f32_16x16x32_bf16 v[12:15], v[148:151], v[222:225], v[12:15]
	v_mfma_f32_16x16x32_bf16 v[8:11], v[156:159], v[222:225], v[8:11]
	v_mfma_f32_16x16x32_bf16 v[4:7], v[148:151], v[230:233], v[4:7]
	v_mfma_f32_16x16x32_bf16 v[0:3], v[156:159], v[230:233], v[0:3]
	s_setprio 0
	s_barrier
	s_add_i32 s61, 0, 0x18000
	s_add_i32 s62, 0, 0x1c000
	v_add_u32_e32 v140, s61, v200
	v_add_u32_e32 v156, s62, v200
	ds_read_b128 v[128:131], v140
	ds_read_b128 v[132:135], v140 offset:1024
	ds_read_b128 v[136:139], v140 offset:2048
	ds_read_b128 v[140:143], v140 offset:3072
	ds_read_b128 v[144:147], v156
	ds_read_b128 v[148:151], v156 offset:1024
	ds_read_b128 v[152:155], v156 offset:2048
	ds_read_b128 v[156:159], v156 offset:3072
	s_add_u32 s28, s28, 0x40000
	s_addc_u32 s29, s29, 0
	s_mov_b32 m0, s44
	ds_read_b128 v[160:163], v212 offset:32768
	ds_read_b128 v[164:167], v212 offset:33792
	ds_read_b128 v[194:197], v212 offset:34816
	ds_read_b128 v[214:217], v212 offset:35840
	ds_read_b128 v[218:221], v212 offset:36864
	ds_read_b128 v[222:225], v212 offset:37888
	ds_read_b128 v[226:229], v212 offset:38912
	ds_read_b128 v[230:233], v212 offset:39936
	global_load_lds_dwordx4 v168, s[28:29]
	s_mov_b32 m0, s45
	s_nop 0
	global_load_lds_dwordx4 v172, s[28:29]
	s_waitcnt vmcnt(8)
	s_waitcnt lgkmcnt(0)
	s_barrier
	s_setprio 1
	s_waitcnt lgkmcnt(0)
	v_mfma_f32_16x16x32_bf16 v[124:127], v[128:131], v[160:163], v[124:127]
	v_mfma_f32_16x16x32_bf16 v[120:123], v[136:139], v[160:163], v[120:123]
	v_mfma_f32_16x16x32_bf16 v[116:119], v[128:131], v[194:197], v[116:119]
	v_mfma_f32_16x16x32_bf16 v[112:115], v[136:139], v[194:197], v[112:115]
	v_mfma_f32_16x16x32_bf16 v[108:111], v[128:131], v[218:221], v[108:111]
	v_mfma_f32_16x16x32_bf16 v[104:107], v[136:139], v[218:221], v[104:107]
	v_mfma_f32_16x16x32_bf16 v[100:103], v[128:131], v[226:229], v[100:103]
	v_mfma_f32_16x16x32_bf16 v[96:99], v[136:139], v[226:229], v[96:99]
	v_mfma_f32_16x16x32_bf16 v[124:127], v[132:135], v[164:167], v[124:127]
	v_mfma_f32_16x16x32_bf16 v[120:123], v[140:143], v[164:167], v[120:123]
	v_mfma_f32_16x16x32_bf16 v[116:119], v[132:135], v[214:217], v[116:119]
	v_mfma_f32_16x16x32_bf16 v[112:115], v[140:143], v[214:217], v[112:115]
	v_mfma_f32_16x16x32_bf16 v[108:111], v[132:135], v[222:225], v[108:111]
	v_mfma_f32_16x16x32_bf16 v[104:107], v[140:143], v[222:225], v[104:107]
	v_mfma_f32_16x16x32_bf16 v[100:103], v[132:135], v[230:233], v[100:103]
	v_mfma_f32_16x16x32_bf16 v[96:99], v[140:143], v[230:233], v[96:99]
	s_setprio 0
	s_setprio 1
	v_mfma_f32_16x16x32_bf16 v[60:63], v[144:147], v[160:163], v[60:63]
	v_mfma_f32_16x16x32_bf16 v[56:59], v[152:155], v[160:163], v[56:59]
	v_mfma_f32_16x16x32_bf16 v[52:55], v[144:147], v[194:197], v[52:55]
	v_mfma_f32_16x16x32_bf16 v[48:51], v[152:155], v[194:197], v[48:51]
	v_mfma_f32_16x16x32_bf16 v[44:47], v[144:147], v[218:221], v[44:47]
	v_mfma_f32_16x16x32_bf16 v[40:43], v[152:155], v[218:221], v[40:43]
	v_mfma_f32_16x16x32_bf16 v[36:39], v[144:147], v[226:229], v[36:39]
	v_mfma_f32_16x16x32_bf16 v[32:35], v[152:155], v[226:229], v[32:35]
	v_mfma_f32_16x16x32_bf16 v[60:63], v[148:151], v[164:167], v[60:63]
	v_mfma_f32_16x16x32_bf16 v[56:59], v[156:159], v[164:167], v[56:59]
	v_mfma_f32_16x16x32_bf16 v[52:55], v[148:151], v[214:217], v[52:55]
	v_mfma_f32_16x16x32_bf16 v[48:51], v[156:159], v[214:217], v[48:51]
	v_mfma_f32_16x16x32_bf16 v[44:47], v[148:151], v[222:225], v[44:47]
	v_mfma_f32_16x16x32_bf16 v[40:43], v[156:159], v[222:225], v[40:43]
	v_mfma_f32_16x16x32_bf16 v[36:39], v[148:151], v[230:233], v[36:39]
	v_mfma_f32_16x16x32_bf16 v[32:35], v[156:159], v[230:233], v[32:35]
	s_setprio 0
	s_barrier
	s_add_u32 s28, s26, 0x8000
	s_addc_u32 s29, s27, 0
	s_add_i32 s61, s61, s41
	s_mov_b32 m0, s61
	ds_read_b128 v[160:163], v212 offset:49152
	ds_read_b128 v[164:167], v212 offset:50176
	ds_read_b128 v[194:197], v212 offset:51200
	ds_read_b128 v[214:217], v212 offset:52224
	ds_read_b128 v[218:221], v212 offset:53248
	ds_read_b128 v[222:225], v212 offset:54272
	ds_read_b128 v[226:229], v212 offset:55296
	ds_read_b128 v[230:233], v212 offset:56320
	global_load_lds_dwordx4 v170, s[28:29]
	s_add_i32 m0, s61, 0x2000
	s_add_u32 s26, s26, 0xc000
	v_lshl_add_u64 v[206:207], s[28:29], 0, v[174:175]
	s_addc_u32 s27, s27, 0
	s_add_i32 s28, s62, s41
	global_load_lds_dwordx4 v[206:207], off
	s_mov_b32 m0, s28
	v_lshl_add_u64 v[198:199], v[198:199], 0, s[12:13]
	global_load_lds_dwordx4 v170, s[26:27]
	s_add_i32 m0, s28, 0x2000
	s_nop 0
	global_load_lds_dwordx4 v174, s[26:27]
	s_mov_b32 m0, s50
	s_nop 0
	global_load_lds_dwordx4 v[198:199], off
	v_lshl_add_u64 v[198:199], v[204:205], 0, s[12:13]
	s_mov_b32 m0, s51
	s_nop 0
	global_load_lds_dwordx4 v[198:199], off
	s_waitcnt vmcnt(8)
	s_waitcnt lgkmcnt(0)
	s_barrier
	s_setprio 1
	s_waitcnt lgkmcnt(0)
	v_mfma_f32_16x16x32_bf16 v[92:95], v[128:131], v[160:163], v[92:95]
	v_mfma_f32_16x16x32_bf16 v[88:91], v[136:139], v[160:163], v[88:91]
	v_mfma_f32_16x16x32_bf16 v[84:87], v[128:131], v[194:197], v[84:87]
	v_mfma_f32_16x16x32_bf16 v[80:83], v[136:139], v[194:197], v[80:83]
	v_mfma_f32_16x16x32_bf16 v[76:79], v[128:131], v[218:221], v[76:79]
	v_mfma_f32_16x16x32_bf16 v[72:75], v[136:139], v[218:221], v[72:75]
	v_mfma_f32_16x16x32_bf16 v[68:71], v[128:131], v[226:229], v[68:71]
	v_mfma_f32_16x16x32_bf16 v[64:67], v[136:139], v[226:229], v[64:67]
	v_mfma_f32_16x16x32_bf16 v[92:95], v[132:135], v[164:167], v[92:95]
	v_mfma_f32_16x16x32_bf16 v[88:91], v[140:143], v[164:167], v[88:91]
	v_mfma_f32_16x16x32_bf16 v[84:87], v[132:135], v[214:217], v[84:87]
	v_mfma_f32_16x16x32_bf16 v[80:83], v[140:143], v[214:217], v[80:83]
	v_mfma_f32_16x16x32_bf16 v[76:79], v[132:135], v[222:225], v[76:79]
	v_mfma_f32_16x16x32_bf16 v[72:75], v[140:143], v[222:225], v[72:75]
	v_mfma_f32_16x16x32_bf16 v[68:71], v[132:135], v[230:233], v[68:71]
	v_mfma_f32_16x16x32_bf16 v[64:67], v[140:143], v[230:233], v[64:67]
	s_setprio 0
	s_setprio 1
	v_mfma_f32_16x16x32_bf16 v[28:31], v[144:147], v[160:163], v[28:31]
	v_mfma_f32_16x16x32_bf16 v[24:27], v[152:155], v[160:163], v[24:27]
	v_mfma_f32_16x16x32_bf16 v[20:23], v[144:147], v[194:197], v[20:23]
	v_mfma_f32_16x16x32_bf16 v[16:19], v[152:155], v[194:197], v[16:19]
	v_mfma_f32_16x16x32_bf16 v[12:15], v[144:147], v[218:221], v[12:15]
	v_mfma_f32_16x16x32_bf16 v[8:11], v[152:155], v[218:221], v[8:11]
	v_mfma_f32_16x16x32_bf16 v[4:7], v[144:147], v[226:229], v[4:7]
	v_mfma_f32_16x16x32_bf16 v[0:3], v[152:155], v[226:229], v[0:3]
	v_mfma_f32_16x16x32_bf16 v[28:31], v[148:151], v[164:167], v[28:31]
	v_mfma_f32_16x16x32_bf16 v[24:27], v[156:159], v[164:167], v[24:27]
	v_mfma_f32_16x16x32_bf16 v[20:23], v[148:151], v[214:217], v[20:23]
	v_mfma_f32_16x16x32_bf16 v[16:19], v[156:159], v[214:217], v[16:19]
	v_mfma_f32_16x16x32_bf16 v[12:15], v[148:151], v[222:225], v[12:15]
	v_mfma_f32_16x16x32_bf16 v[8:11], v[156:159], v[222:225], v[8:11]
	v_mfma_f32_16x16x32_bf16 v[4:7], v[148:151], v[230:233], v[4:7]
	v_mfma_f32_16x16x32_bf16 v[0:3], v[156:159], v[230:233], v[0:3]
	s_setprio 0
	s_barrier
	s_add_i32 s35, s35, 2
	s_add_u32 s31, s31, 0x10000
	s_addc_u32 s34, s34, 0
	s_add_u32 s6, s6, 0x100
	s_addc_u32 s7, s7, 0
	s_cmp_gt_u32 s35, 13
	s_cbranch_scc0 .LBB0_1729
	s_and_b64 vcc, exec, s[14:15]
	s_cbranch_vccz .LBB0_1740
	s_barrier
	v_lshl_add_u32 v214, s0, 8, v179
	s_cmp_gt_i32 s2, 4
	s_mov_b64 s[0:1], -1
	s_cbranch_scc1 .LBB0_1741

.LBB0_2258:
	ds_read_b128 v[128:131], v170
	ds_read_b128 v[148:151], v170 offset:1024
	ds_read_b128 v[152:155], v170 offset:2048
	ds_read_b128 v[174:177], v170 offset:3072
	ds_read_b128 v[178:181], v171
	ds_read_b128 v[182:185], v171 offset:1024
	ds_read_b128 v[186:189], v171 offset:2048
	ds_read_b128 v[190:193], v171 offset:3072
	s_add_u32 s30, s28, 0xfffe0080
	s_addc_u32 s31, s29, -1
	s_cmp_eq_u32 s56, 4
	s_cselect_b32 s35, s17, s31
	s_cselect_b32 s34, s52, s30
	s_cselect_b32 s31, s19, s55
	s_cselect_b32 s30, s53, s54
	s_add_i32 m0, s25, 0xc000
	ds_read_b128 v[194:197], v172
	ds_read_b128 v[198:201], v172 offset:1024
	ds_read_b128 v[210:213], v172 offset:2048
	ds_read_b128 v[214:217], v172 offset:3072
	ds_read_b128 v[218:221], v172 offset:4096
	ds_read_b128 v[222:225], v172 offset:5120
	ds_read_b128 v[226:229], v172 offset:6144
	ds_read_b128 v[230:233], v172 offset:7168
	global_load_lds_dwordx4 v142, s[28:29]
	s_add_i32 m0, s25, 0xe000
	s_nop 0
	global_load_lds_dwordx4 v140, s[28:29]
	s_waitcnt vmcnt(8)
	s_waitcnt lgkmcnt(0)
	s_barrier
	s_setprio 1
	s_waitcnt lgkmcnt(0)
	v_mfma_f32_16x16x32_bf16 v[124:127], v[128:131], v[194:197], v[124:127]
	v_mfma_f32_16x16x32_bf16 v[120:123], v[152:155], v[194:197], v[120:123]
	v_mfma_f32_16x16x32_bf16 v[116:119], v[128:131], v[210:213], v[116:119]
	v_mfma_f32_16x16x32_bf16 v[112:115], v[152:155], v[210:213], v[112:115]
	v_mfma_f32_16x16x32_bf16 v[92:95], v[128:131], v[218:221], v[92:95]
	v_mfma_f32_16x16x32_bf16 v[88:91], v[152:155], v[218:221], v[88:91]
	v_mfma_f32_16x16x32_bf16 v[84:87], v[128:131], v[226:229], v[84:87]
	v_mfma_f32_16x16x32_bf16 v[72:75], v[152:155], v[226:229], v[72:75]
	v_mfma_f32_16x16x32_bf16 v[124:127], v[148:151], v[198:201], v[124:127]
	v_mfma_f32_16x16x32_bf16 v[120:123], v[174:177], v[198:201], v[120:123]
	v_mfma_f32_16x16x32_bf16 v[116:119], v[148:151], v[214:217], v[116:119]
	v_mfma_f32_16x16x32_bf16 v[112:115], v[174:177], v[214:217], v[112:115]
	v_mfma_f32_16x16x32_bf16 v[92:95], v[148:151], v[222:225], v[92:95]
	v_mfma_f32_16x16x32_bf16 v[88:91], v[174:177], v[222:225], v[88:91]
	v_mfma_f32_16x16x32_bf16 v[84:87], v[148:151], v[230:233], v[84:87]
	v_mfma_f32_16x16x32_bf16 v[72:75], v[174:177], v[230:233], v[72:75]
	s_setprio 0
	s_setprio 1
	v_mfma_f32_16x16x32_bf16 v[108:111], v[178:181], v[194:197], v[108:111]
	v_mfma_f32_16x16x32_bf16 v[104:107], v[186:189], v[194:197], v[104:107]
	v_mfma_f32_16x16x32_bf16 v[100:103], v[178:181], v[210:213], v[100:103]
	v_mfma_f32_16x16x32_bf16 v[96:99], v[186:189], v[210:213], v[96:99]
	v_mfma_f32_16x16x32_bf16 v[80:83], v[178:181], v[218:221], v[80:83]
	v_mfma_f32_16x16x32_bf16 v[76:79], v[186:189], v[218:221], v[76:79]
	v_mfma_f32_16x16x32_bf16 v[68:71], v[178:181], v[226:229], v[68:71]
	v_mfma_f32_16x16x32_bf16 v[64:67], v[186:189], v[226:229], v[64:67]
	v_mfma_f32_16x16x32_bf16 v[108:111], v[182:185], v[198:201], v[108:111]
	v_mfma_f32_16x16x32_bf16 v[104:107], v[190:193], v[198:201], v[104:107]
	v_mfma_f32_16x16x32_bf16 v[100:103], v[182:185], v[214:217], v[100:103]
	v_mfma_f32_16x16x32_bf16 v[96:99], v[190:193], v[214:217], v[96:99]
	v_mfma_f32_16x16x32_bf16 v[80:83], v[182:185], v[222:225], v[80:83]
	v_mfma_f32_16x16x32_bf16 v[76:79], v[190:193], v[222:225], v[76:79]
	v_mfma_f32_16x16x32_bf16 v[68:71], v[182:185], v[230:233], v[68:71]
	v_mfma_f32_16x16x32_bf16 v[64:67], v[190:193], v[230:233], v[64:67]
	s_setprio 0
	s_barrier
	s_add_i32 s57, s49, s42
	s_mov_b32 m0, s57
	ds_read_b128 v[194:197], v172 offset:16384
	ds_read_b128 v[198:201], v172 offset:17408
	ds_read_b128 v[210:213], v172 offset:18432
	ds_read_b128 v[214:217], v172 offset:19456
	ds_read_b128 v[218:221], v172 offset:20480
	ds_read_b128 v[222:225], v172 offset:21504
	ds_read_b128 v[226:229], v172 offset:22528
	ds_read_b128 v[230:233], v172 offset:23552
	global_load_lds_dwordx4 v134, s[30:31]
	s_add_i32 m0, s57, 0x2000
	s_add_u32 s58, s30, 0x4000
	s_addc_u32 s59, s31, 0
	s_add_i32 s57, s50, s42
	global_load_lds_dwordx4 v138, s[30:31]
	s_mov_b32 m0, s57
	v_lshl_add_u64 v[206:207], s[34:35], 0, v[136:137]
	global_load_lds_dwordx4 v134, s[58:59]
	s_add_i32 m0, s57, 0x2000
	s_nop 0
	global_load_lds_dwordx4 v138, s[58:59]
	v_lshl_add_u64 v[204:205], s[34:35], 0, v[132:133]
	s_mov_b32 m0, s25
	s_nop 0
	global_load_lds_dwordx4 v[204:205], off
	s_mov_b32 m0, s27
	s_nop 0
	global_load_lds_dwordx4 v[206:207], off
	s_waitcnt vmcnt(8)
	s_waitcnt lgkmcnt(0)
	s_barrier
	s_setprio 1
	s_waitcnt lgkmcnt(0)
	v_mfma_f32_16x16x32_bf16 v[60:63], v[128:131], v[194:197], v[60:63]
	v_mfma_f32_16x16x32_bf16 v[56:59], v[152:155], v[194:197], v[56:59]
	v_mfma_f32_16x16x32_bf16 v[48:51], v[128:131], v[210:213], v[48:51]
	v_mfma_f32_16x16x32_bf16 v[40:43], v[152:155], v[210:213], v[40:43]
	v_mfma_f32_16x16x32_bf16 v[32:35], v[128:131], v[218:221], v[32:35]
	v_mfma_f32_16x16x32_bf16 v[24:27], v[152:155], v[218:221], v[24:27]
	v_mfma_f32_16x16x32_bf16 v[16:19], v[128:131], v[226:229], v[16:19]
	v_mfma_f32_16x16x32_bf16 v[8:11], v[152:155], v[226:229], v[8:11]
	v_mfma_f32_16x16x32_bf16 v[60:63], v[148:151], v[198:201], v[60:63]
	v_mfma_f32_16x16x32_bf16 v[56:59], v[174:177], v[198:201], v[56:59]
	v_mfma_f32_16x16x32_bf16 v[48:51], v[148:151], v[214:217], v[48:51]
	v_mfma_f32_16x16x32_bf16 v[40:43], v[174:177], v[214:217], v[40:43]
	v_mfma_f32_16x16x32_bf16 v[32:35], v[148:151], v[222:225], v[32:35]
	v_mfma_f32_16x16x32_bf16 v[24:27], v[174:177], v[222:225], v[24:27]
	v_mfma_f32_16x16x32_bf16 v[16:19], v[148:151], v[230:233], v[16:19]
	v_mfma_f32_16x16x32_bf16 v[8:11], v[174:177], v[230:233], v[8:11]
	s_setprio 0
	s_setprio 1
	v_mfma_f32_16x16x32_bf16 v[52:55], v[178:181], v[194:197], v[52:55]
	v_mfma_f32_16x16x32_bf16 v[44:47], v[186:189], v[194:197], v[44:47]
	v_mfma_f32_16x16x32_bf16 v[36:39], v[178:181], v[210:213], v[36:39]
	v_mfma_f32_16x16x32_bf16 v[28:31], v[186:189], v[210:213], v[28:31]
	v_mfma_f32_16x16x32_bf16 v[20:23], v[178:181], v[218:221], v[20:23]
	v_mfma_f32_16x16x32_bf16 v[12:15], v[186:189], v[218:221], v[12:15]
	v_mfma_f32_16x16x32_bf16 v[4:7], v[178:181], v[226:229], v[4:7]
	v_mfma_f32_16x16x32_bf16 v[0:3], v[186:189], v[226:229], v[0:3]
	v_mfma_f32_16x16x32_bf16 v[52:55], v[182:185], v[198:201], v[52:55]
	v_mfma_f32_16x16x32_bf16 v[44:47], v[190:193], v[198:201], v[44:47]
	v_mfma_f32_16x16x32_bf16 v[36:39], v[182:185], v[214:217], v[36:39]
	v_mfma_f32_16x16x32_bf16 v[28:31], v[190:193], v[214:217], v[28:31]
	v_mfma_f32_16x16x32_bf16 v[20:23], v[182:185], v[222:225], v[20:23]
	v_mfma_f32_16x16x32_bf16 v[12:15], v[190:193], v[222:225], v[12:15]
	v_mfma_f32_16x16x32_bf16 v[4:7], v[182:185], v[230:233], v[4:7]
	v_mfma_f32_16x16x32_bf16 v[0:3], v[190:193], v[230:233], v[0:3]
	s_setprio 0
	s_barrier
	s_add_i32 s57, 0, 0x18000
	v_add_u32_e32 v173, s57, v168
	s_add_i32 s58, 0, 0x1c000
	ds_read_b128 v[128:131], v173
	ds_read_b128 v[148:151], v173 offset:1024
	ds_read_b128 v[152:155], v173 offset:2048
	ds_read_b128 v[174:177], v173 offset:3072
	v_add_u32_e32 v173, s58, v168
	ds_read_b128 v[178:181], v173
	ds_read_b128 v[182:185], v173 offset:1024
	ds_read_b128 v[186:189], v173 offset:2048
	ds_read_b128 v[190:193], v173 offset:3072
	s_add_u32 s34, s34, 0x20000
	s_addc_u32 s35, s35, 0
	s_mov_b32 m0, s43
	ds_read_b128 v[194:197], v172 offset:32768
	ds_read_b128 v[198:201], v172 offset:33792
	ds_read_b128 v[210:213], v172 offset:34816
	ds_read_b128 v[214:217], v172 offset:35840
	ds_read_b128 v[218:221], v172 offset:36864
	ds_read_b128 v[222:225], v172 offset:37888
	ds_read_b128 v[226:229], v172 offset:38912
	ds_read_b128 v[230:233], v172 offset:39936
	global_load_lds_dwordx4 v132, s[34:35]
	s_mov_b32 m0, s44
	s_nop 0
	global_load_lds_dwordx4 v136, s[34:35]
	s_waitcnt vmcnt(8)
	s_waitcnt lgkmcnt(0)
	s_barrier
	s_setprio 1
	s_waitcnt lgkmcnt(0)
	v_mfma_f32_16x16x32_bf16 v[124:127], v[128:131], v[194:197], v[124:127]
	v_mfma_f32_16x16x32_bf16 v[120:123], v[152:155], v[194:197], v[120:123]
	v_mfma_f32_16x16x32_bf16 v[116:119], v[128:131], v[210:213], v[116:119]
	v_mfma_f32_16x16x32_bf16 v[112:115], v[152:155], v[210:213], v[112:115]
	v_mfma_f32_16x16x32_bf16 v[92:95], v[128:131], v[218:221], v[92:95]
	v_mfma_f32_16x16x32_bf16 v[88:91], v[152:155], v[218:221], v[88:91]
	v_mfma_f32_16x16x32_bf16 v[84:87], v[128:131], v[226:229], v[84:87]
	v_mfma_f32_16x16x32_bf16 v[72:75], v[152:155], v[226:229], v[72:75]
	v_mfma_f32_16x16x32_bf16 v[124:127], v[148:151], v[198:201], v[124:127]
	v_mfma_f32_16x16x32_bf16 v[120:123], v[174:177], v[198:201], v[120:123]
	v_mfma_f32_16x16x32_bf16 v[116:119], v[148:151], v[214:217], v[116:119]
	v_mfma_f32_16x16x32_bf16 v[112:115], v[174:177], v[214:217], v[112:115]
	v_mfma_f32_16x16x32_bf16 v[92:95], v[148:151], v[222:225], v[92:95]
	v_mfma_f32_16x16x32_bf16 v[88:91], v[174:177], v[222:225], v[88:91]
	v_mfma_f32_16x16x32_bf16 v[84:87], v[148:151], v[230:233], v[84:87]
	v_mfma_f32_16x16x32_bf16 v[72:75], v[174:177], v[230:233], v[72:75]
	s_setprio 0
	s_setprio 1
	v_mfma_f32_16x16x32_bf16 v[108:111], v[178:181], v[194:197], v[108:111]
	v_mfma_f32_16x16x32_bf16 v[104:107], v[186:189], v[194:197], v[104:107]
	v_mfma_f32_16x16x32_bf16 v[100:103], v[178:181], v[210:213], v[100:103]
	v_mfma_f32_16x16x32_bf16 v[96:99], v[186:189], v[210:213], v[96:99]
	v_mfma_f32_16x16x32_bf16 v[80:83], v[178:181], v[218:221], v[80:83]
	v_mfma_f32_16x16x32_bf16 v[76:79], v[186:189], v[218:221], v[76:79]
	v_mfma_f32_16x16x32_bf16 v[68:71], v[178:181], v[226:229], v[68:71]
	v_mfma_f32_16x16x32_bf16 v[64:67], v[186:189], v[226:229], v[64:67]
	v_mfma_f32_16x16x32_bf16 v[108:111], v[182:185], v[198:201], v[108:111]
	v_mfma_f32_16x16x32_bf16 v[104:107], v[190:193], v[198:201], v[104:107]
	v_mfma_f32_16x16x32_bf16 v[100:103], v[182:185], v[214:217], v[100:103]
	v_mfma_f32_16x16x32_bf16 v[96:99], v[190:193], v[214:217], v[96:99]
	v_mfma_f32_16x16x32_bf16 v[80:83], v[182:185], v[222:225], v[80:83]
	v_mfma_f32_16x16x32_bf16 v[76:79], v[190:193], v[222:225], v[76:79]
	v_mfma_f32_16x16x32_bf16 v[68:71], v[182:185], v[230:233], v[68:71]
	v_mfma_f32_16x16x32_bf16 v[64:67], v[190:193], v[230:233], v[64:67]
	s_setprio 0
	s_barrier
	s_add_u32 s34, s30, 0x8000
	s_addc_u32 s35, s31, 0
	s_add_i32 s57, s57, s42
	s_mov_b32 m0, s57
	ds_read_b128 v[194:197], v172 offset:49152
	ds_read_b128 v[198:201], v172 offset:50176
	ds_read_b128 v[210:213], v172 offset:51200
	ds_read_b128 v[214:217], v172 offset:52224
	ds_read_b128 v[218:221], v172 offset:53248
	ds_read_b128 v[222:225], v172 offset:54272
	ds_read_b128 v[226:229], v172 offset:55296
	ds_read_b128 v[230:233], v172 offset:56320
	global_load_lds_dwordx4 v134, s[34:35]
	s_add_i32 m0, s57, 0x2000
	s_add_u32 s30, s30, 0xc000
	v_lshl_add_u64 v[234:235], s[34:35], 0, v[138:139]
	s_addc_u32 s31, s31, 0
	s_add_i32 s34, s58, s42
	global_load_lds_dwordx4 v[234:235], off
	s_mov_b32 m0, s34
	v_lshl_add_u64 v[204:205], v[204:205], 0, s[12:13]
	global_load_lds_dwordx4 v134, s[30:31]
	s_add_i32 m0, s34, 0x2000
	s_nop 0
	global_load_lds_dwordx4 v138, s[30:31]
	s_mov_b32 m0, s46
	s_nop 0
	global_load_lds_dwordx4 v[204:205], off
	v_lshl_add_u64 v[204:205], v[206:207], 0, s[12:13]
	s_mov_b32 m0, s47
	s_nop 0
	global_load_lds_dwordx4 v[204:205], off
	s_waitcnt vmcnt(8)
	s_waitcnt lgkmcnt(0)
	s_barrier
	s_setprio 1
	s_waitcnt lgkmcnt(0)
	v_mfma_f32_16x16x32_bf16 v[60:63], v[128:131], v[194:197], v[60:63]
	v_mfma_f32_16x16x32_bf16 v[56:59], v[152:155], v[194:197], v[56:59]
	v_mfma_f32_16x16x32_bf16 v[48:51], v[128:131], v[210:213], v[48:51]
	v_mfma_f32_16x16x32_bf16 v[40:43], v[152:155], v[210:213], v[40:43]
	v_mfma_f32_16x16x32_bf16 v[32:35], v[128:131], v[218:221], v[32:35]
	v_mfma_f32_16x16x32_bf16 v[24:27], v[152:155], v[218:221], v[24:27]
	v_mfma_f32_16x16x32_bf16 v[16:19], v[128:131], v[226:229], v[16:19]
	v_mfma_f32_16x16x32_bf16 v[8:11], v[152:155], v[226:229], v[8:11]
	v_mfma_f32_16x16x32_bf16 v[60:63], v[148:151], v[198:201], v[60:63]
	v_mfma_f32_16x16x32_bf16 v[56:59], v[174:177], v[198:201], v[56:59]
	v_mfma_f32_16x16x32_bf16 v[48:51], v[148:151], v[214:217], v[48:51]
	v_mfma_f32_16x16x32_bf16 v[40:43], v[174:177], v[214:217], v[40:43]
	v_mfma_f32_16x16x32_bf16 v[32:35], v[148:151], v[222:225], v[32:35]
	v_mfma_f32_16x16x32_bf16 v[24:27], v[174:177], v[222:225], v[24:27]
	v_mfma_f32_16x16x32_bf16 v[16:19], v[148:151], v[230:233], v[16:19]
	v_mfma_f32_16x16x32_bf16 v[8:11], v[174:177], v[230:233], v[8:11]
	s_setprio 0
	s_setprio 1
	v_mfma_f32_16x16x32_bf16 v[52:55], v[178:181], v[194:197], v[52:55]
	v_mfma_f32_16x16x32_bf16 v[44:47], v[186:189], v[194:197], v[44:47]
	v_mfma_f32_16x16x32_bf16 v[36:39], v[178:181], v[210:213], v[36:39]
	v_mfma_f32_16x16x32_bf16 v[28:31], v[186:189], v[210:213], v[28:31]
	v_mfma_f32_16x16x32_bf16 v[20:23], v[178:181], v[218:221], v[20:23]
	v_mfma_f32_16x16x32_bf16 v[12:15], v[186:189], v[218:221], v[12:15]
	v_mfma_f32_16x16x32_bf16 v[4:7], v[178:181], v[226:229], v[4:7]
	v_mfma_f32_16x16x32_bf16 v[0:3], v[186:189], v[226:229], v[0:3]
	v_mfma_f32_16x16x32_bf16 v[52:55], v[182:185], v[198:201], v[52:55]
	v_mfma_f32_16x16x32_bf16 v[44:47], v[190:193], v[198:201], v[44:47]
	v_mfma_f32_16x16x32_bf16 v[36:39], v[182:185], v[214:217], v[36:39]
	v_mfma_f32_16x16x32_bf16 v[28:31], v[190:193], v[214:217], v[28:31]
	v_mfma_f32_16x16x32_bf16 v[20:23], v[182:185], v[222:225], v[20:23]
	v_mfma_f32_16x16x32_bf16 v[12:15], v[190:193], v[222:225], v[12:15]
	v_mfma_f32_16x16x32_bf16 v[4:7], v[182:185], v[230:233], v[4:7]
	v_mfma_f32_16x16x32_bf16 v[0:3], v[190:193], v[230:233], v[0:3]
	s_setprio 0
	s_barrier
	s_add_i32 s56, s56, 2
	s_add_u32 s54, s54, 0x10000
	s_addc_u32 s55, s55, 0
	s_add_u32 s28, s28, 0x100
	s_addc_u32 s29, s29, 0
	s_cmp_gt_u32 s56, 5
	s_cbranch_scc0 .LBB0_2258
	s_and_b64 vcc, exec, s[14:15]
	s_cbranch_vccz .LBB0_2261
	s_barrier

.LBB0_2282:
	ds_read_b128 v[144:147], v155
	ds_read_b128 v[148:151], v155 offset:1024
	ds_read_b128 v[158:161], v155 offset:2048
	ds_read_b128 v[162:165], v155 offset:3072
	ds_read_b128 v[166:169], v156
	ds_read_b128 v[170:173], v156 offset:1024
	ds_read_b128 v[174:177], v156 offset:2048
	ds_read_b128 v[178:181], v156 offset:3072
	s_add_u32 s28, s26, 0xfffe0080
	s_addc_u32 s29, s27, -1
	s_cmp_eq_u32 s54, 4
	s_cselect_b32 s31, s15, s29
	s_cselect_b32 s30, s50, s28
	s_cselect_b32 s29, s17, s53
	s_cselect_b32 s28, s51, s52
	s_add_i32 m0, s23, 0xc000
	ds_read_b128 v[182:185], v157
	ds_read_b128 v[186:189], v157 offset:1024
	ds_read_b128 v[190:193], v157 offset:2048
	ds_read_b128 v[194:197], v157 offset:3072
	ds_read_b128 v[198:201], v157 offset:4096
	ds_read_b128 v[210:213], v157 offset:5120
	ds_read_b128 v[214:217], v157 offset:6144
	ds_read_b128 v[218:221], v157 offset:7168
	global_load_lds_dwordx4 v130, s[26:27]
	s_add_i32 m0, s23, 0xe000
	s_nop 0
	global_load_lds_dwordx4 v128, s[26:27]
	s_waitcnt vmcnt(8)
	s_waitcnt lgkmcnt(0)
	s_barrier
	s_setprio 1
	s_waitcnt lgkmcnt(0)
	v_mfma_f32_16x16x32_bf16 v[124:127], v[144:147], v[182:185], v[124:127]
	v_mfma_f32_16x16x32_bf16 v[120:123], v[158:161], v[182:185], v[120:123]
	v_mfma_f32_16x16x32_bf16 v[112:115], v[144:147], v[190:193], v[112:115]
	v_mfma_f32_16x16x32_bf16 v[104:107], v[158:161], v[190:193], v[104:107]
	v_mfma_f32_16x16x32_bf16 v[92:95], v[144:147], v[198:201], v[92:95]
	v_mfma_f32_16x16x32_bf16 v[88:91], v[158:161], v[198:201], v[88:91]
	v_mfma_f32_16x16x32_bf16 v[80:83], v[144:147], v[214:217], v[80:83]
	v_mfma_f32_16x16x32_bf16 v[72:75], v[158:161], v[214:217], v[72:75]
	v_mfma_f32_16x16x32_bf16 v[124:127], v[148:151], v[186:189], v[124:127]
	v_mfma_f32_16x16x32_bf16 v[120:123], v[162:165], v[186:189], v[120:123]
	v_mfma_f32_16x16x32_bf16 v[112:115], v[148:151], v[194:197], v[112:115]
	v_mfma_f32_16x16x32_bf16 v[104:107], v[162:165], v[194:197], v[104:107]
	v_mfma_f32_16x16x32_bf16 v[92:95], v[148:151], v[210:213], v[92:95]
	v_mfma_f32_16x16x32_bf16 v[88:91], v[162:165], v[210:213], v[88:91]
	v_mfma_f32_16x16x32_bf16 v[80:83], v[148:151], v[218:221], v[80:83]
	v_mfma_f32_16x16x32_bf16 v[72:75], v[162:165], v[218:221], v[72:75]
	s_setprio 0
	s_setprio 1
	v_mfma_f32_16x16x32_bf16 v[116:119], v[166:169], v[182:185], v[116:119]
	v_mfma_f32_16x16x32_bf16 v[108:111], v[174:177], v[182:185], v[108:111]
	v_mfma_f32_16x16x32_bf16 v[100:103], v[166:169], v[190:193], v[100:103]
	v_mfma_f32_16x16x32_bf16 v[96:99], v[174:177], v[190:193], v[96:99]
	v_mfma_f32_16x16x32_bf16 v[84:87], v[166:169], v[198:201], v[84:87]
	v_mfma_f32_16x16x32_bf16 v[76:79], v[174:177], v[198:201], v[76:79]
	v_mfma_f32_16x16x32_bf16 v[68:71], v[166:169], v[214:217], v[68:71]
	v_mfma_f32_16x16x32_bf16 v[64:67], v[174:177], v[214:217], v[64:67]
	v_mfma_f32_16x16x32_bf16 v[116:119], v[170:173], v[186:189], v[116:119]
	v_mfma_f32_16x16x32_bf16 v[108:111], v[178:181], v[186:189], v[108:111]
	v_mfma_f32_16x16x32_bf16 v[100:103], v[170:173], v[194:197], v[100:103]
	v_mfma_f32_16x16x32_bf16 v[96:99], v[178:181], v[194:197], v[96:99]
	v_mfma_f32_16x16x32_bf16 v[84:87], v[170:173], v[210:213], v[84:87]
	v_mfma_f32_16x16x32_bf16 v[76:79], v[178:181], v[210:213], v[76:79]
	v_mfma_f32_16x16x32_bf16 v[68:71], v[170:173], v[218:221], v[68:71]
	v_mfma_f32_16x16x32_bf16 v[64:67], v[178:181], v[218:221], v[64:67]
	s_setprio 0
	s_barrier
	s_add_i32 s55, s47, s40
	s_mov_b32 m0, s55
	ds_read_b128 v[182:185], v157 offset:16384
	ds_read_b128 v[186:189], v157 offset:17408
	ds_read_b128 v[190:193], v157 offset:18432
	ds_read_b128 v[194:197], v157 offset:19456
	ds_read_b128 v[198:201], v157 offset:20480
	ds_read_b128 v[210:213], v157 offset:21504
	ds_read_b128 v[214:217], v157 offset:22528
	ds_read_b128 v[218:221], v157 offset:23552
	global_load_lds_dwordx4 v134, s[28:29]
	s_add_i32 m0, s55, 0x2000
	s_add_u32 s56, s28, 0x4000
	s_addc_u32 s57, s29, 0
	s_add_i32 s55, s48, s40
	global_load_lds_dwordx4 v138, s[28:29]
	s_mov_b32 m0, s55
	v_lshl_add_u64 v[206:207], s[30:31], 0, v[136:137]
	global_load_lds_dwordx4 v134, s[56:57]
	s_add_i32 m0, s55, 0x2000
	s_nop 0
	global_load_lds_dwordx4 v138, s[56:57]
	v_lshl_add_u64 v[204:205], s[30:31], 0, v[132:133]
	s_mov_b32 m0, s23
	s_nop 0
	global_load_lds_dwordx4 v[204:205], off
	s_mov_b32 m0, s25
	s_nop 0
	global_load_lds_dwordx4 v[206:207], off
	s_waitcnt vmcnt(8)
	s_waitcnt lgkmcnt(0)
	s_barrier
	s_setprio 1
	s_waitcnt lgkmcnt(0)
	v_mfma_f32_16x16x32_bf16 v[60:63], v[144:147], v[182:185], v[60:63]
	v_mfma_f32_16x16x32_bf16 v[56:59], v[158:161], v[182:185], v[56:59]
	v_mfma_f32_16x16x32_bf16 v[48:51], v[144:147], v[190:193], v[48:51]
	v_mfma_f32_16x16x32_bf16 v[40:43], v[158:161], v[190:193], v[40:43]
	v_mfma_f32_16x16x32_bf16 v[28:31], v[144:147], v[198:201], v[28:31]
	v_mfma_f32_16x16x32_bf16 v[24:27], v[158:161], v[198:201], v[24:27]
	v_mfma_f32_16x16x32_bf16 v[16:19], v[144:147], v[214:217], v[16:19]
	v_mfma_f32_16x16x32_bf16 v[8:11], v[158:161], v[214:217], v[8:11]
	v_mfma_f32_16x16x32_bf16 v[60:63], v[148:151], v[186:189], v[60:63]
	v_mfma_f32_16x16x32_bf16 v[56:59], v[162:165], v[186:189], v[56:59]
	v_mfma_f32_16x16x32_bf16 v[48:51], v[148:151], v[194:197], v[48:51]
	v_mfma_f32_16x16x32_bf16 v[40:43], v[162:165], v[194:197], v[40:43]
	v_mfma_f32_16x16x32_bf16 v[28:31], v[148:151], v[210:213], v[28:31]
	v_mfma_f32_16x16x32_bf16 v[24:27], v[162:165], v[210:213], v[24:27]
	v_mfma_f32_16x16x32_bf16 v[16:19], v[148:151], v[218:221], v[16:19]
	v_mfma_f32_16x16x32_bf16 v[8:11], v[162:165], v[218:221], v[8:11]
	s_setprio 0
	s_setprio 1
	v_mfma_f32_16x16x32_bf16 v[52:55], v[166:169], v[182:185], v[52:55]
	v_mfma_f32_16x16x32_bf16 v[44:47], v[174:177], v[182:185], v[44:47]
	v_mfma_f32_16x16x32_bf16 v[36:39], v[166:169], v[190:193], v[36:39]
	v_mfma_f32_16x16x32_bf16 v[32:35], v[174:177], v[190:193], v[32:35]
	v_mfma_f32_16x16x32_bf16 v[20:23], v[166:169], v[198:201], v[20:23]
	v_mfma_f32_16x16x32_bf16 v[12:15], v[174:177], v[198:201], v[12:15]
	v_mfma_f32_16x16x32_bf16 v[4:7], v[166:169], v[214:217], v[4:7]
	v_mfma_f32_16x16x32_bf16 v[0:3], v[174:177], v[214:217], v[0:3]
	v_mfma_f32_16x16x32_bf16 v[52:55], v[170:173], v[186:189], v[52:55]
	v_mfma_f32_16x16x32_bf16 v[44:47], v[178:181], v[186:189], v[44:47]
	v_mfma_f32_16x16x32_bf16 v[36:39], v[170:173], v[194:197], v[36:39]
	v_mfma_f32_16x16x32_bf16 v[32:35], v[178:181], v[194:197], v[32:35]
	v_mfma_f32_16x16x32_bf16 v[20:23], v[170:173], v[210:213], v[20:23]
	v_mfma_f32_16x16x32_bf16 v[12:15], v[178:181], v[210:213], v[12:15]
	v_mfma_f32_16x16x32_bf16 v[4:7], v[170:173], v[218:221], v[4:7]
	v_mfma_f32_16x16x32_bf16 v[0:3], v[178:181], v[218:221], v[0:3]
	s_setprio 0
	s_barrier
	s_add_i32 s55, 0, 0x18000
	s_add_i32 s56, 0, 0x1c000
	v_add_u32_e32 v162, s55, v153
	v_add_u32_e32 v178, s56, v153
	ds_read_b128 v[144:147], v162
	ds_read_b128 v[148:151], v162 offset:1024
	ds_read_b128 v[158:161], v162 offset:2048
	ds_read_b128 v[162:165], v162 offset:3072
	ds_read_b128 v[166:169], v178
	ds_read_b128 v[170:173], v178 offset:1024
	ds_read_b128 v[174:177], v178 offset:2048
	ds_read_b128 v[178:181], v178 offset:3072
	s_add_u32 s30, s30, 0x20000
	s_addc_u32 s31, s31, 0
	s_mov_b32 m0, s41
	ds_read_b128 v[182:185], v157 offset:32768
	ds_read_b128 v[186:189], v157 offset:33792
	ds_read_b128 v[190:193], v157 offset:34816
	ds_read_b128 v[194:197], v157 offset:35840
	ds_read_b128 v[198:201], v157 offset:36864
	ds_read_b128 v[210:213], v157 offset:37888
	ds_read_b128 v[214:217], v157 offset:38912
	ds_read_b128 v[218:221], v157 offset:39936
	global_load_lds_dwordx4 v132, s[30:31]
	s_mov_b32 m0, s42
	s_nop 0
	global_load_lds_dwordx4 v136, s[30:31]
	s_waitcnt vmcnt(8)
	s_waitcnt lgkmcnt(0)
	s_barrier
	s_setprio 1
	s_waitcnt lgkmcnt(0)
	v_mfma_f32_16x16x32_bf16 v[124:127], v[144:147], v[182:185], v[124:127]
	v_mfma_f32_16x16x32_bf16 v[120:123], v[158:161], v[182:185], v[120:123]
	v_mfma_f32_16x16x32_bf16 v[112:115], v[144:147], v[190:193], v[112:115]
	v_mfma_f32_16x16x32_bf16 v[104:107], v[158:161], v[190:193], v[104:107]
	v_mfma_f32_16x16x32_bf16 v[92:95], v[144:147], v[198:201], v[92:95]
	v_mfma_f32_16x16x32_bf16 v[88:91], v[158:161], v[198:201], v[88:91]
	v_mfma_f32_16x16x32_bf16 v[80:83], v[144:147], v[214:217], v[80:83]
	v_mfma_f32_16x16x32_bf16 v[72:75], v[158:161], v[214:217], v[72:75]
	v_mfma_f32_16x16x32_bf16 v[124:127], v[148:151], v[186:189], v[124:127]
	v_mfma_f32_16x16x32_bf16 v[120:123], v[162:165], v[186:189], v[120:123]
	v_mfma_f32_16x16x32_bf16 v[112:115], v[148:151], v[194:197], v[112:115]
	v_mfma_f32_16x16x32_bf16 v[104:107], v[162:165], v[194:197], v[104:107]
	v_mfma_f32_16x16x32_bf16 v[92:95], v[148:151], v[210:213], v[92:95]
	v_mfma_f32_16x16x32_bf16 v[88:91], v[162:165], v[210:213], v[88:91]
	v_mfma_f32_16x16x32_bf16 v[80:83], v[148:151], v[218:221], v[80:83]
	v_mfma_f32_16x16x32_bf16 v[72:75], v[162:165], v[218:221], v[72:75]
	s_setprio 0
	s_setprio 1
	v_mfma_f32_16x16x32_bf16 v[116:119], v[166:169], v[182:185], v[116:119]
	v_mfma_f32_16x16x32_bf16 v[108:111], v[174:177], v[182:185], v[108:111]
	v_mfma_f32_16x16x32_bf16 v[100:103], v[166:169], v[190:193], v[100:103]
	v_mfma_f32_16x16x32_bf16 v[96:99], v[174:177], v[190:193], v[96:99]
	v_mfma_f32_16x16x32_bf16 v[84:87], v[166:169], v[198:201], v[84:87]
	v_mfma_f32_16x16x32_bf16 v[76:79], v[174:177], v[198:201], v[76:79]
	v_mfma_f32_16x16x32_bf16 v[68:71], v[166:169], v[214:217], v[68:71]
	v_mfma_f32_16x16x32_bf16 v[64:67], v[174:177], v[214:217], v[64:67]
	v_mfma_f32_16x16x32_bf16 v[116:119], v[170:173], v[186:189], v[116:119]
	v_mfma_f32_16x16x32_bf16 v[108:111], v[178:181], v[186:189], v[108:111]
	v_mfma_f32_16x16x32_bf16 v[100:103], v[170:173], v[194:197], v[100:103]
	v_mfma_f32_16x16x32_bf16 v[96:99], v[178:181], v[194:197], v[96:99]
	v_mfma_f32_16x16x32_bf16 v[84:87], v[170:173], v[210:213], v[84:87]
	v_mfma_f32_16x16x32_bf16 v[76:79], v[178:181], v[210:213], v[76:79]
	v_mfma_f32_16x16x32_bf16 v[68:71], v[170:173], v[218:221], v[68:71]
	v_mfma_f32_16x16x32_bf16 v[64:67], v[178:181], v[218:221], v[64:67]
	s_setprio 0
	s_barrier
	s_add_u32 s30, s28, 0x8000
	s_addc_u32 s31, s29, 0
	s_add_i32 s55, s55, s40
	s_mov_b32 m0, s55
	ds_read_b128 v[182:185], v157 offset:49152
	ds_read_b128 v[186:189], v157 offset:50176
	ds_read_b128 v[190:193], v157 offset:51200
	ds_read_b128 v[194:197], v157 offset:52224
	ds_read_b128 v[198:201], v157 offset:53248
	ds_read_b128 v[210:213], v157 offset:54272
	ds_read_b128 v[214:217], v157 offset:55296
	ds_read_b128 v[218:221], v157 offset:56320
	global_load_lds_dwordx4 v134, s[30:31]
	s_add_i32 m0, s55, 0x2000
	s_add_u32 s28, s28, 0xc000
	v_lshl_add_u64 v[222:223], s[30:31], 0, v[138:139]
	s_addc_u32 s29, s29, 0
	s_add_i32 s30, s56, s40
	global_load_lds_dwordx4 v[222:223], off
	s_mov_b32 m0, s30
	v_lshl_add_u64 v[204:205], v[204:205], 0, s[8:9]
	global_load_lds_dwordx4 v134, s[28:29]
	s_add_i32 m0, s30, 0x2000
	s_nop 0
	global_load_lds_dwordx4 v138, s[28:29]
	s_mov_b32 m0, s44
	s_nop 0
	global_load_lds_dwordx4 v[204:205], off
	v_lshl_add_u64 v[204:205], v[206:207], 0, s[8:9]
	s_mov_b32 m0, s45
	s_nop 0
	global_load_lds_dwordx4 v[204:205], off
	s_waitcnt vmcnt(8)
	s_waitcnt lgkmcnt(0)
	s_barrier
	s_setprio 1
	s_waitcnt lgkmcnt(0)
	v_mfma_f32_16x16x32_bf16 v[60:63], v[144:147], v[182:185], v[60:63]
	v_mfma_f32_16x16x32_bf16 v[56:59], v[158:161], v[182:185], v[56:59]
	v_mfma_f32_16x16x32_bf16 v[48:51], v[144:147], v[190:193], v[48:51]
	v_mfma_f32_16x16x32_bf16 v[40:43], v[158:161], v[190:193], v[40:43]
	v_mfma_f32_16x16x32_bf16 v[28:31], v[144:147], v[198:201], v[28:31]
	v_mfma_f32_16x16x32_bf16 v[24:27], v[158:161], v[198:201], v[24:27]
	v_mfma_f32_16x16x32_bf16 v[16:19], v[144:147], v[214:217], v[16:19]
	v_mfma_f32_16x16x32_bf16 v[8:11], v[158:161], v[214:217], v[8:11]
	v_mfma_f32_16x16x32_bf16 v[60:63], v[148:151], v[186:189], v[60:63]
	v_mfma_f32_16x16x32_bf16 v[56:59], v[162:165], v[186:189], v[56:59]
	v_mfma_f32_16x16x32_bf16 v[48:51], v[148:151], v[194:197], v[48:51]
	v_mfma_f32_16x16x32_bf16 v[40:43], v[162:165], v[194:197], v[40:43]
	v_mfma_f32_16x16x32_bf16 v[28:31], v[148:151], v[210:213], v[28:31]
	v_mfma_f32_16x16x32_bf16 v[24:27], v[162:165], v[210:213], v[24:27]
	v_mfma_f32_16x16x32_bf16 v[16:19], v[148:151], v[218:221], v[16:19]
	v_mfma_f32_16x16x32_bf16 v[8:11], v[162:165], v[218:221], v[8:11]
	s_setprio 0
	s_setprio 1
	v_mfma_f32_16x16x32_bf16 v[52:55], v[166:169], v[182:185], v[52:55]
	v_mfma_f32_16x16x32_bf16 v[44:47], v[174:177], v[182:185], v[44:47]
	v_mfma_f32_16x16x32_bf16 v[36:39], v[166:169], v[190:193], v[36:39]
	v_mfma_f32_16x16x32_bf16 v[32:35], v[174:177], v[190:193], v[32:35]
	v_mfma_f32_16x16x32_bf16 v[20:23], v[166:169], v[198:201], v[20:23]
	v_mfma_f32_16x16x32_bf16 v[12:15], v[174:177], v[198:201], v[12:15]
	v_mfma_f32_16x16x32_bf16 v[4:7], v[166:169], v[214:217], v[4:7]
	v_mfma_f32_16x16x32_bf16 v[0:3], v[174:177], v[214:217], v[0:3]
	v_mfma_f32_16x16x32_bf16 v[52:55], v[170:173], v[186:189], v[52:55]
	v_mfma_f32_16x16x32_bf16 v[44:47], v[178:181], v[186:189], v[44:47]
	v_mfma_f32_16x16x32_bf16 v[36:39], v[170:173], v[194:197], v[36:39]
	v_mfma_f32_16x16x32_bf16 v[32:35], v[178:181], v[194:197], v[32:35]
	v_mfma_f32_16x16x32_bf16 v[20:23], v[170:173], v[210:213], v[20:23]
	v_mfma_f32_16x16x32_bf16 v[12:15], v[178:181], v[210:213], v[12:15]
	v_mfma_f32_16x16x32_bf16 v[4:7], v[170:173], v[218:221], v[4:7]
	v_mfma_f32_16x16x32_bf16 v[0:3], v[178:181], v[218:221], v[0:3]
	s_setprio 0
	s_barrier
	s_add_i32 s54, s54, 2
	s_add_u32 s52, s52, 0x10000
	s_addc_u32 s53, s53, 0
	s_add_u32 s26, s26, 0x100
	s_addc_u32 s27, s27, 0
	s_cmp_gt_u32 s54, 5
	s_cbranch_scc0 .LBB0_2282
	s_and_b64 vcc, exec, s[10:11]
	s_cbranch_vccz .LBB0_2285
	s_barrier

.LBB0_2358:
	v_add_u32_e32 v168, s77, v182
	v_add_u32_e32 v204, s78, v182
	ds_read_b128 v[156:159], v168
	ds_read_b128 v[160:163], v168 offset:1024
	ds_read_b128 v[164:167], v168 offset:2048
	ds_read_b128 v[168:171], v168 offset:3072
	ds_read_b128 v[172:175], v204
	ds_read_b128 v[176:179], v204 offset:1024
	ds_read_b128 v[212:215], v204 offset:2048
	ds_read_b128 v[216:219], v204 offset:3072
	s_add_u32 s48, s46, 0xfffc0080
	s_addc_u32 s49, s47, -1
	s_cmp_eq_u32 s54, 12
	s_cselect_b32 s51, s35, s49
	s_cselect_b32 s50, s43, s48
	s_cselect_b32 s49, s37, s53
	s_cselect_b32 s48, s45, s52
	s_add_i32 m0, s65, 0xc000
	ds_read_b128 v[220:223], v199
	ds_read_b128 v[224:227], v199 offset:1024
	ds_read_b128 v[228:231], v199 offset:2048
	ds_read_b128 v[232:235], v199 offset:3072
	ds_read_b128 v[236:239], v199 offset:4096
	ds_read_b128 v[240:243], v199 offset:5120
	ds_read_b128 v[244:247], v199 offset:6144
	ds_read_b128 v[248:251], v199 offset:7168
	global_load_lds_dwordx4 v154, s[46:47]
	s_add_i32 m0, s65, 0xe000
	s_nop 0
	global_load_lds_dwordx4 v152, s[46:47]
	s_waitcnt vmcnt(8)
	s_waitcnt lgkmcnt(0)
	s_barrier
	s_setprio 1
	s_waitcnt lgkmcnt(0)
	v_mfma_f32_16x16x32_bf16 v[124:127], v[156:159], v[220:223], v[124:127]
	v_mfma_f32_16x16x32_bf16 v[120:123], v[164:167], v[220:223], v[120:123]
	v_mfma_f32_16x16x32_bf16 v[116:119], v[156:159], v[228:231], v[116:119]
	v_mfma_f32_16x16x32_bf16 v[112:115], v[164:167], v[228:231], v[112:115]
	v_mfma_f32_16x16x32_bf16 v[92:95], v[156:159], v[236:239], v[92:95]
	v_mfma_f32_16x16x32_bf16 v[88:91], v[164:167], v[236:239], v[88:91]
	v_mfma_f32_16x16x32_bf16 v[84:87], v[156:159], v[244:247], v[84:87]
	v_mfma_f32_16x16x32_bf16 v[80:83], v[164:167], v[244:247], v[80:83]
	v_mfma_f32_16x16x32_bf16 v[124:127], v[160:163], v[224:227], v[124:127]
	v_mfma_f32_16x16x32_bf16 v[120:123], v[168:171], v[224:227], v[120:123]
	v_mfma_f32_16x16x32_bf16 v[116:119], v[160:163], v[232:235], v[116:119]
	v_mfma_f32_16x16x32_bf16 v[112:115], v[168:171], v[232:235], v[112:115]
	v_mfma_f32_16x16x32_bf16 v[92:95], v[160:163], v[240:243], v[92:95]
	v_mfma_f32_16x16x32_bf16 v[88:91], v[168:171], v[240:243], v[88:91]
	v_mfma_f32_16x16x32_bf16 v[84:87], v[160:163], v[248:251], v[84:87]
	v_mfma_f32_16x16x32_bf16 v[80:83], v[168:171], v[248:251], v[80:83]
	s_setprio 0
	s_setprio 1
	v_mfma_f32_16x16x32_bf16 v[108:111], v[172:175], v[220:223], v[108:111]
	v_mfma_f32_16x16x32_bf16 v[104:107], v[212:215], v[220:223], v[104:107]
	v_mfma_f32_16x16x32_bf16 v[100:103], v[172:175], v[228:231], v[100:103]
	v_mfma_f32_16x16x32_bf16 v[96:99], v[212:215], v[228:231], v[96:99]
	v_mfma_f32_16x16x32_bf16 v[76:79], v[172:175], v[236:239], v[76:79]
	v_mfma_f32_16x16x32_bf16 v[72:75], v[212:215], v[236:239], v[72:75]
	v_mfma_f32_16x16x32_bf16 v[68:71], v[172:175], v[244:247], v[68:71]
	v_mfma_f32_16x16x32_bf16 v[64:67], v[212:215], v[244:247], v[64:67]
	v_mfma_f32_16x16x32_bf16 v[108:111], v[176:179], v[224:227], v[108:111]
	v_mfma_f32_16x16x32_bf16 v[104:107], v[216:219], v[224:227], v[104:107]
	v_mfma_f32_16x16x32_bf16 v[100:103], v[176:179], v[232:235], v[100:103]
	v_mfma_f32_16x16x32_bf16 v[96:99], v[216:219], v[232:235], v[96:99]
	v_mfma_f32_16x16x32_bf16 v[76:79], v[176:179], v[240:243], v[76:79]
	v_mfma_f32_16x16x32_bf16 v[72:75], v[216:219], v[240:243], v[72:75]
	v_mfma_f32_16x16x32_bf16 v[68:71], v[176:179], v[248:251], v[68:71]
	v_mfma_f32_16x16x32_bf16 v[64:67], v[216:219], v[248:251], v[64:67]
	s_setprio 0
	s_barrier
	s_add_i32 s55, s77, s64
	s_mov_b32 m0, s55
	ds_read_b128 v[220:223], v199 offset:16384
	ds_read_b128 v[224:227], v199 offset:17408
	ds_read_b128 v[228:231], v199 offset:18432
	ds_read_b128 v[232:235], v199 offset:19456
	ds_read_b128 v[236:239], v199 offset:20480
	ds_read_b128 v[240:243], v199 offset:21504
	ds_read_b128 v[244:247], v199 offset:22528
	ds_read_b128 v[248:251], v199 offset:23552
	global_load_lds_dwordx4 v130, s[48:49]
	s_add_i32 m0, s55, 0x2000
	s_add_u32 s56, s48, 0x4000
	s_addc_u32 s57, s49, 0
	s_add_i32 s55, s78, s64
	global_load_lds_dwordx4 v134, s[48:49]
	s_mov_b32 m0, s55
	v_lshl_add_u64 v[206:207], s[50:51], 0, v[132:133]
	global_load_lds_dwordx4 v130, s[56:57]
	s_add_i32 m0, s55, 0x2000
	s_nop 0
	global_load_lds_dwordx4 v134, s[56:57]
	v_lshl_add_u64 v[204:205], s[50:51], 0, v[128:129]
	s_mov_b32 m0, s65
	s_nop 0
	global_load_lds_dwordx4 v[204:205], off
	s_mov_b32 m0, s66
	s_nop 0
	global_load_lds_dwordx4 v[206:207], off
	s_waitcnt vmcnt(8)
	s_waitcnt lgkmcnt(0)
	s_barrier
	s_setprio 1
	s_waitcnt lgkmcnt(0)
	v_mfma_f32_16x16x32_bf16 v[60:63], v[156:159], v[220:223], v[60:63]
	v_mfma_f32_16x16x32_bf16 v[56:59], v[164:167], v[220:223], v[56:59]
	v_mfma_f32_16x16x32_bf16 v[52:55], v[156:159], v[228:231], v[52:55]
	v_mfma_f32_16x16x32_bf16 v[48:51], v[164:167], v[228:231], v[48:51]
	v_mfma_f32_16x16x32_bf16 v[28:31], v[156:159], v[236:239], v[28:31]
	v_mfma_f32_16x16x32_bf16 v[24:27], v[164:167], v[236:239], v[24:27]
	v_mfma_f32_16x16x32_bf16 v[20:23], v[156:159], v[244:247], v[20:23]
	v_mfma_f32_16x16x32_bf16 v[12:15], v[164:167], v[244:247], v[12:15]
	v_mfma_f32_16x16x32_bf16 v[60:63], v[160:163], v[224:227], v[60:63]
	v_mfma_f32_16x16x32_bf16 v[56:59], v[168:171], v[224:227], v[56:59]
	v_mfma_f32_16x16x32_bf16 v[52:55], v[160:163], v[232:235], v[52:55]
	v_mfma_f32_16x16x32_bf16 v[48:51], v[168:171], v[232:235], v[48:51]
	v_mfma_f32_16x16x32_bf16 v[28:31], v[160:163], v[240:243], v[28:31]
	v_mfma_f32_16x16x32_bf16 v[24:27], v[168:171], v[240:243], v[24:27]
	v_mfma_f32_16x16x32_bf16 v[20:23], v[160:163], v[248:251], v[20:23]
	v_mfma_f32_16x16x32_bf16 v[12:15], v[168:171], v[248:251], v[12:15]
	s_setprio 0
	s_setprio 1
	v_mfma_f32_16x16x32_bf16 v[44:47], v[172:175], v[220:223], v[44:47]
	v_mfma_f32_16x16x32_bf16 v[40:43], v[212:215], v[220:223], v[40:43]
	v_mfma_f32_16x16x32_bf16 v[36:39], v[172:175], v[228:231], v[36:39]
	v_mfma_f32_16x16x32_bf16 v[32:35], v[212:215], v[228:231], v[32:35]
	v_mfma_f32_16x16x32_bf16 v[16:19], v[172:175], v[236:239], v[16:19]
	v_mfma_f32_16x16x32_bf16 v[8:11], v[212:215], v[236:239], v[8:11]
	v_mfma_f32_16x16x32_bf16 v[4:7], v[172:175], v[244:247], v[4:7]
	v_mfma_f32_16x16x32_bf16 v[0:3], v[212:215], v[244:247], v[0:3]
	v_mfma_f32_16x16x32_bf16 v[44:47], v[176:179], v[224:227], v[44:47]
	v_mfma_f32_16x16x32_bf16 v[40:43], v[216:219], v[224:227], v[40:43]
	v_mfma_f32_16x16x32_bf16 v[36:39], v[176:179], v[232:235], v[36:39]
	v_mfma_f32_16x16x32_bf16 v[32:35], v[216:219], v[232:235], v[32:35]
	v_mfma_f32_16x16x32_bf16 v[16:19], v[176:179], v[240:243], v[16:19]
	v_mfma_f32_16x16x32_bf16 v[8:11], v[216:219], v[240:243], v[8:11]
	v_mfma_f32_16x16x32_bf16 v[4:7], v[176:179], v[248:251], v[4:7]
	v_mfma_f32_16x16x32_bf16 v[0:3], v[216:219], v[248:251], v[0:3]
	s_setprio 0
	s_barrier
	s_add_i32 s55, 0, 0x18000
	s_add_i32 s56, 0, 0x1c000
	v_add_u32_e32 v168, s55, v182
	v_add_u32_e32 v216, s56, v182
	ds_read_b128 v[156:159], v168
	ds_read_b128 v[160:163], v168 offset:1024
	ds_read_b128 v[164:167], v168 offset:2048
	ds_read_b128 v[168:171], v168 offset:3072
	ds_read_b128 v[172:175], v216
	ds_read_b128 v[176:179], v216 offset:1024
	ds_read_b128 v[212:215], v216 offset:2048
	ds_read_b128 v[216:219], v216 offset:3072
	s_add_u32 s50, s50, 0x40000
	s_addc_u32 s51, s51, 0
	s_mov_b32 m0, s67
	ds_read_b128 v[220:223], v199 offset:32768
	ds_read_b128 v[224:227], v199 offset:33792
	ds_read_b128 v[228:231], v199 offset:34816
	ds_read_b128 v[232:235], v199 offset:35840
	ds_read_b128 v[236:239], v199 offset:36864
	ds_read_b128 v[240:243], v199 offset:37888
	ds_read_b128 v[244:247], v199 offset:38912
	ds_read_b128 v[248:251], v199 offset:39936
	global_load_lds_dwordx4 v128, s[50:51]
	s_mov_b32 m0, s68
	s_nop 0
	global_load_lds_dwordx4 v132, s[50:51]
	s_waitcnt vmcnt(8)
	s_waitcnt lgkmcnt(0)
	s_barrier
	s_setprio 1
	s_waitcnt lgkmcnt(0)
	v_mfma_f32_16x16x32_bf16 v[124:127], v[156:159], v[220:223], v[124:127]
	v_mfma_f32_16x16x32_bf16 v[120:123], v[164:167], v[220:223], v[120:123]
	v_mfma_f32_16x16x32_bf16 v[116:119], v[156:159], v[228:231], v[116:119]
	v_mfma_f32_16x16x32_bf16 v[112:115], v[164:167], v[228:231], v[112:115]
	v_mfma_f32_16x16x32_bf16 v[92:95], v[156:159], v[236:239], v[92:95]
	v_mfma_f32_16x16x32_bf16 v[88:91], v[164:167], v[236:239], v[88:91]
	v_mfma_f32_16x16x32_bf16 v[84:87], v[156:159], v[244:247], v[84:87]
	v_mfma_f32_16x16x32_bf16 v[80:83], v[164:167], v[244:247], v[80:83]
	v_mfma_f32_16x16x32_bf16 v[124:127], v[160:163], v[224:227], v[124:127]
	v_mfma_f32_16x16x32_bf16 v[120:123], v[168:171], v[224:227], v[120:123]
	v_mfma_f32_16x16x32_bf16 v[116:119], v[160:163], v[232:235], v[116:119]
	v_mfma_f32_16x16x32_bf16 v[112:115], v[168:171], v[232:235], v[112:115]
	v_mfma_f32_16x16x32_bf16 v[92:95], v[160:163], v[240:243], v[92:95]
	v_mfma_f32_16x16x32_bf16 v[88:91], v[168:171], v[240:243], v[88:91]
	v_mfma_f32_16x16x32_bf16 v[84:87], v[160:163], v[248:251], v[84:87]
	v_mfma_f32_16x16x32_bf16 v[80:83], v[168:171], v[248:251], v[80:83]
	s_setprio 0
	s_setprio 1
	v_mfma_f32_16x16x32_bf16 v[108:111], v[172:175], v[220:223], v[108:111]
	v_mfma_f32_16x16x32_bf16 v[104:107], v[212:215], v[220:223], v[104:107]
	v_mfma_f32_16x16x32_bf16 v[100:103], v[172:175], v[228:231], v[100:103]
	v_mfma_f32_16x16x32_bf16 v[96:99], v[212:215], v[228:231], v[96:99]
	v_mfma_f32_16x16x32_bf16 v[76:79], v[172:175], v[236:239], v[76:79]
	v_mfma_f32_16x16x32_bf16 v[72:75], v[212:215], v[236:239], v[72:75]
	v_mfma_f32_16x16x32_bf16 v[68:71], v[172:175], v[244:247], v[68:71]
	v_mfma_f32_16x16x32_bf16 v[64:67], v[212:215], v[244:247], v[64:67]
	v_mfma_f32_16x16x32_bf16 v[108:111], v[176:179], v[224:227], v[108:111]
	v_mfma_f32_16x16x32_bf16 v[104:107], v[216:219], v[224:227], v[104:107]
	v_mfma_f32_16x16x32_bf16 v[100:103], v[176:179], v[232:235], v[100:103]
	v_mfma_f32_16x16x32_bf16 v[96:99], v[216:219], v[232:235], v[96:99]
	v_mfma_f32_16x16x32_bf16 v[76:79], v[176:179], v[240:243], v[76:79]
	v_mfma_f32_16x16x32_bf16 v[72:75], v[216:219], v[240:243], v[72:75]
	v_mfma_f32_16x16x32_bf16 v[68:71], v[176:179], v[248:251], v[68:71]
	v_mfma_f32_16x16x32_bf16 v[64:67], v[216:219], v[248:251], v[64:67]
	s_setprio 0
	s_barrier
	s_add_u32 s50, s48, 0x8000
	s_addc_u32 s51, s49, 0
	s_add_i32 s55, s55, s64
	s_mov_b32 m0, s55
	ds_read_b128 v[220:223], v199 offset:49152
	ds_read_b128 v[224:227], v199 offset:50176
	ds_read_b128 v[228:231], v199 offset:51200
	ds_read_b128 v[232:235], v199 offset:52224
	ds_read_b128 v[236:239], v199 offset:53248
	ds_read_b128 v[240:243], v199 offset:54272
	ds_read_b128 v[244:247], v199 offset:55296
	ds_read_b128 v[248:251], v199 offset:56320
	global_load_lds_dwordx4 v130, s[50:51]
	s_add_i32 m0, s55, 0x2000
	s_add_u32 s48, s48, 0xc000
	v_lshl_add_u64 v[252:253], s[50:51], 0, v[134:135]
	s_addc_u32 s49, s49, 0
	s_add_i32 s50, s56, s64
	global_load_lds_dwordx4 v[252:253], off
	s_mov_b32 m0, s50
	v_lshl_add_u64 v[204:205], v[204:205], 0, s[14:15]
	global_load_lds_dwordx4 v130, s[48:49]
	s_add_i32 m0, s50, 0x2000
	s_nop 0
	global_load_lds_dwordx4 v134, s[48:49]
	s_mov_b32 m0, s74
	s_nop 0
	global_load_lds_dwordx4 v[204:205], off
	v_lshl_add_u64 v[204:205], v[206:207], 0, s[14:15]
	s_mov_b32 m0, s75
	s_nop 0
	global_load_lds_dwordx4 v[204:205], off
	s_waitcnt vmcnt(8)
	s_waitcnt lgkmcnt(0)
	s_barrier
	s_setprio 1
	s_waitcnt lgkmcnt(0)
	v_mfma_f32_16x16x32_bf16 v[60:63], v[156:159], v[220:223], v[60:63]
	v_mfma_f32_16x16x32_bf16 v[56:59], v[164:167], v[220:223], v[56:59]
	v_mfma_f32_16x16x32_bf16 v[52:55], v[156:159], v[228:231], v[52:55]
	v_mfma_f32_16x16x32_bf16 v[48:51], v[164:167], v[228:231], v[48:51]
	v_mfma_f32_16x16x32_bf16 v[28:31], v[156:159], v[236:239], v[28:31]
	v_mfma_f32_16x16x32_bf16 v[24:27], v[164:167], v[236:239], v[24:27]
	v_mfma_f32_16x16x32_bf16 v[20:23], v[156:159], v[244:247], v[20:23]
	v_mfma_f32_16x16x32_bf16 v[12:15], v[164:167], v[244:247], v[12:15]
	v_mfma_f32_16x16x32_bf16 v[60:63], v[160:163], v[224:227], v[60:63]
	v_mfma_f32_16x16x32_bf16 v[56:59], v[168:171], v[224:227], v[56:59]
	v_mfma_f32_16x16x32_bf16 v[52:55], v[160:163], v[232:235], v[52:55]
	v_mfma_f32_16x16x32_bf16 v[48:51], v[168:171], v[232:235], v[48:51]
	v_mfma_f32_16x16x32_bf16 v[28:31], v[160:163], v[240:243], v[28:31]
	v_mfma_f32_16x16x32_bf16 v[24:27], v[168:171], v[240:243], v[24:27]
	v_mfma_f32_16x16x32_bf16 v[20:23], v[160:163], v[248:251], v[20:23]
	v_mfma_f32_16x16x32_bf16 v[12:15], v[168:171], v[248:251], v[12:15]
	s_setprio 0
	s_setprio 1
	v_mfma_f32_16x16x32_bf16 v[44:47], v[172:175], v[220:223], v[44:47]
	v_mfma_f32_16x16x32_bf16 v[40:43], v[212:215], v[220:223], v[40:43]
	v_mfma_f32_16x16x32_bf16 v[36:39], v[172:175], v[228:231], v[36:39]
	v_mfma_f32_16x16x32_bf16 v[32:35], v[212:215], v[228:231], v[32:35]
	v_mfma_f32_16x16x32_bf16 v[16:19], v[172:175], v[236:239], v[16:19]
	v_mfma_f32_16x16x32_bf16 v[8:11], v[212:215], v[236:239], v[8:11]
	v_mfma_f32_16x16x32_bf16 v[4:7], v[172:175], v[244:247], v[4:7]
	v_mfma_f32_16x16x32_bf16 v[0:3], v[212:215], v[244:247], v[0:3]
	v_mfma_f32_16x16x32_bf16 v[44:47], v[176:179], v[224:227], v[44:47]
	v_mfma_f32_16x16x32_bf16 v[40:43], v[216:219], v[224:227], v[40:43]
	v_mfma_f32_16x16x32_bf16 v[36:39], v[176:179], v[232:235], v[36:39]
	v_mfma_f32_16x16x32_bf16 v[32:35], v[216:219], v[232:235], v[32:35]
	v_mfma_f32_16x16x32_bf16 v[16:19], v[176:179], v[240:243], v[16:19]
	v_mfma_f32_16x16x32_bf16 v[8:11], v[216:219], v[240:243], v[8:11]
	v_mfma_f32_16x16x32_bf16 v[4:7], v[176:179], v[248:251], v[4:7]
	v_mfma_f32_16x16x32_bf16 v[0:3], v[216:219], v[248:251], v[0:3]
	s_setprio 0
	s_barrier
	s_add_i32 s54, s54, 2
	s_add_u32 s52, s52, 0x10000
	s_addc_u32 s53, s53, 0
	s_add_u32 s46, s46, 0x100
	s_addc_u32 s47, s47, 0
	s_cmp_gt_u32 s54, 13
	s_cbranch_scc0 .LBB0_2358
	s_and_b64 vcc, exec, s[16:17]
	s_cbranch_vccz .LBB0_2361
	s_barrier

.LBB0_2519:
	ds_read_b128 v[144:147], v178
	ds_read_b128 v[148:151], v178 offset:1024
	ds_read_b128 v[152:155], v178 offset:2048
	ds_read_b128 v[156:159], v178 offset:3072
	ds_read_b128 v[160:163], v179
	ds_read_b128 v[164:167], v179 offset:1024
	ds_read_b128 v[182:185], v179 offset:2048
	ds_read_b128 v[186:189], v179 offset:3072
	s_add_u32 s34, s30, 0x4000
	s_addc_u32 s35, s31, 0
	s_cmp_eq_u32 s64, 40
	s_cselect_b32 s38, s4, s34
	s_cselect_b32 s39, s5, s35
	s_cselect_b32 s36, s28, s62
	s_cselect_b32 s37, s29, s63
	s_add_u32 s34, s38, 0x8000
	s_addc_u32 s35, s39, 0
	s_add_i32 m0, s42, 0xc000
	ds_read_b128 v[190:193], v180
	ds_read_b128 v[194:197], v180 offset:1024
	ds_read_b128 v[198:201], v180 offset:2048
	ds_read_b128 v[202:205], v180 offset:3072
	ds_read_b128 v[206:209], v180 offset:4096
	ds_read_b128 v[210:213], v180 offset:5120
	ds_read_b128 v[214:217], v180 offset:6144
	ds_read_b128 v[218:221], v180 offset:7168
	global_load_lds_dwordx4 v138, s[30:31]
	s_add_i32 m0, s42, 0xe000
	s_nop 0
	global_load_lds_dwordx4 v136, s[30:31]
	s_waitcnt vmcnt(8)
	s_waitcnt lgkmcnt(0)
	s_barrier
	s_setprio 1
	s_waitcnt lgkmcnt(0)
	v_mfma_f32_16x16x32_bf16 v[124:127], v[144:147], v[190:193], v[124:127]
	v_mfma_f32_16x16x32_bf16 v[120:123], v[152:155], v[190:193], v[120:123]
	v_mfma_f32_16x16x32_bf16 v[116:119], v[144:147], v[198:201], v[116:119]
	v_mfma_f32_16x16x32_bf16 v[112:115], v[152:155], v[198:201], v[112:115]
	v_mfma_f32_16x16x32_bf16 v[92:95], v[144:147], v[206:209], v[92:95]
	v_mfma_f32_16x16x32_bf16 v[88:91], v[152:155], v[206:209], v[88:91]
	v_mfma_f32_16x16x32_bf16 v[84:87], v[144:147], v[214:217], v[84:87]
	v_mfma_f32_16x16x32_bf16 v[80:83], v[152:155], v[214:217], v[80:83]
	v_mfma_f32_16x16x32_bf16 v[124:127], v[148:151], v[194:197], v[124:127]
	v_mfma_f32_16x16x32_bf16 v[120:123], v[156:159], v[194:197], v[120:123]
	v_mfma_f32_16x16x32_bf16 v[116:119], v[148:151], v[202:205], v[116:119]
	v_mfma_f32_16x16x32_bf16 v[112:115], v[156:159], v[202:205], v[112:115]
	v_mfma_f32_16x16x32_bf16 v[92:95], v[148:151], v[210:213], v[92:95]
	v_mfma_f32_16x16x32_bf16 v[88:91], v[156:159], v[210:213], v[88:91]
	v_mfma_f32_16x16x32_bf16 v[84:87], v[148:151], v[218:221], v[84:87]
	v_mfma_f32_16x16x32_bf16 v[80:83], v[156:159], v[218:221], v[80:83]
	s_setprio 0
	s_setprio 1
	v_mfma_f32_16x16x32_bf16 v[108:111], v[160:163], v[190:193], v[108:111]
	v_mfma_f32_16x16x32_bf16 v[104:107], v[182:185], v[190:193], v[104:107]
	v_mfma_f32_16x16x32_bf16 v[100:103], v[160:163], v[198:201], v[100:103]
	v_mfma_f32_16x16x32_bf16 v[96:99], v[182:185], v[198:201], v[96:99]
	v_mfma_f32_16x16x32_bf16 v[76:79], v[160:163], v[206:209], v[76:79]
	v_mfma_f32_16x16x32_bf16 v[72:75], v[182:185], v[206:209], v[72:75]
	v_mfma_f32_16x16x32_bf16 v[68:71], v[160:163], v[214:217], v[68:71]
	v_mfma_f32_16x16x32_bf16 v[64:67], v[182:185], v[214:217], v[64:67]
	v_mfma_f32_16x16x32_bf16 v[108:111], v[164:167], v[194:197], v[108:111]
	v_mfma_f32_16x16x32_bf16 v[104:107], v[186:189], v[194:197], v[104:107]
	v_mfma_f32_16x16x32_bf16 v[100:103], v[164:167], v[202:205], v[100:103]
	v_mfma_f32_16x16x32_bf16 v[96:99], v[186:189], v[202:205], v[96:99]
	v_mfma_f32_16x16x32_bf16 v[76:79], v[164:167], v[210:213], v[76:79]
	v_mfma_f32_16x16x32_bf16 v[72:75], v[186:189], v[210:213], v[72:75]
	v_mfma_f32_16x16x32_bf16 v[68:71], v[164:167], v[218:221], v[68:71]
	v_mfma_f32_16x16x32_bf16 v[64:67], v[186:189], v[218:221], v[64:67]
	s_setprio 0
	s_barrier
	s_add_i32 s65, s55, s41
	s_mov_b32 m0, s65
	ds_read_b128 v[190:193], v180 offset:16384
	ds_read_b128 v[194:197], v180 offset:17408
	ds_read_b128 v[198:201], v180 offset:18432
	ds_read_b128 v[202:205], v180 offset:19456
	ds_read_b128 v[206:209], v180 offset:20480
	ds_read_b128 v[210:213], v180 offset:21504
	ds_read_b128 v[214:217], v180 offset:22528
	ds_read_b128 v[218:221], v180 offset:23552
	global_load_lds_dwordx4 v128, s[36:37]
	s_add_i32 m0, s65, 0x2000
	s_add_u32 s66, s36, 0x4000
	s_addc_u32 s67, s37, 0
	s_add_i32 s65, s56, s41
	global_load_lds_dwordx4 v130, s[36:37]
	s_mov_b32 m0, s65
	s_nop 0
	global_load_lds_dwordx4 v128, s[66:67]
	s_add_i32 m0, s65, 0x2000
	s_nop 0
	global_load_lds_dwordx4 v130, s[66:67]
	s_mov_b32 m0, s42
	s_nop 0
	global_load_lds_dwordx4 v128, s[38:39]
	s_mov_b32 m0, s43
	s_nop 0
	global_load_lds_dwordx4 v130, s[38:39]
	s_waitcnt vmcnt(8)
	s_waitcnt lgkmcnt(0)
	s_barrier
	s_setprio 1
	s_waitcnt lgkmcnt(0)
	v_mfma_f32_16x16x32_bf16 v[60:63], v[144:147], v[190:193], v[60:63]
	v_mfma_f32_16x16x32_bf16 v[56:59], v[152:155], v[190:193], v[56:59]
	v_mfma_f32_16x16x32_bf16 v[52:55], v[144:147], v[198:201], v[52:55]
	v_mfma_f32_16x16x32_bf16 v[48:51], v[152:155], v[198:201], v[48:51]
	v_mfma_f32_16x16x32_bf16 v[28:31], v[144:147], v[206:209], v[28:31]
	v_mfma_f32_16x16x32_bf16 v[24:27], v[152:155], v[206:209], v[24:27]
	v_mfma_f32_16x16x32_bf16 v[20:23], v[144:147], v[214:217], v[20:23]
	v_mfma_f32_16x16x32_bf16 v[12:15], v[152:155], v[214:217], v[12:15]
	v_mfma_f32_16x16x32_bf16 v[60:63], v[148:151], v[194:197], v[60:63]
	v_mfma_f32_16x16x32_bf16 v[56:59], v[156:159], v[194:197], v[56:59]
	v_mfma_f32_16x16x32_bf16 v[52:55], v[148:151], v[202:205], v[52:55]
	v_mfma_f32_16x16x32_bf16 v[48:51], v[156:159], v[202:205], v[48:51]
	v_mfma_f32_16x16x32_bf16 v[28:31], v[148:151], v[210:213], v[28:31]
	v_mfma_f32_16x16x32_bf16 v[24:27], v[156:159], v[210:213], v[24:27]
	v_mfma_f32_16x16x32_bf16 v[20:23], v[148:151], v[218:221], v[20:23]
	v_mfma_f32_16x16x32_bf16 v[12:15], v[156:159], v[218:221], v[12:15]
	s_setprio 0
	s_setprio 1
	v_mfma_f32_16x16x32_bf16 v[44:47], v[160:163], v[190:193], v[44:47]
	v_mfma_f32_16x16x32_bf16 v[40:43], v[182:185], v[190:193], v[40:43]
	v_mfma_f32_16x16x32_bf16 v[36:39], v[160:163], v[198:201], v[36:39]
	v_mfma_f32_16x16x32_bf16 v[32:35], v[182:185], v[198:201], v[32:35]
	v_mfma_f32_16x16x32_bf16 v[16:19], v[160:163], v[206:209], v[16:19]
	v_mfma_f32_16x16x32_bf16 v[8:11], v[182:185], v[206:209], v[8:11]
	v_mfma_f32_16x16x32_bf16 v[4:7], v[160:163], v[214:217], v[4:7]
	v_mfma_f32_16x16x32_bf16 v[0:3], v[182:185], v[214:217], v[0:3]
	v_mfma_f32_16x16x32_bf16 v[44:47], v[164:167], v[194:197], v[44:47]
	v_mfma_f32_16x16x32_bf16 v[40:43], v[186:189], v[194:197], v[40:43]
	v_mfma_f32_16x16x32_bf16 v[36:39], v[164:167], v[202:205], v[36:39]
	v_mfma_f32_16x16x32_bf16 v[32:35], v[186:189], v[202:205], v[32:35]
	v_mfma_f32_16x16x32_bf16 v[16:19], v[164:167], v[210:213], v[16:19]
	v_mfma_f32_16x16x32_bf16 v[8:11], v[186:189], v[210:213], v[8:11]
	v_mfma_f32_16x16x32_bf16 v[4:7], v[164:167], v[218:221], v[4:7]
	v_mfma_f32_16x16x32_bf16 v[0:3], v[186:189], v[218:221], v[0:3]
	s_setprio 0
	s_barrier
	s_add_i32 s65, 0, 0x18000
	s_add_i32 s66, 0, 0x1c000
	v_add_u32_e32 v156, s65, v170
	v_add_u32_e32 v186, s66, v170
	ds_read_b128 v[144:147], v156
	ds_read_b128 v[148:151], v156 offset:1024
	ds_read_b128 v[152:155], v156 offset:2048
	ds_read_b128 v[156:159], v156 offset:3072
	ds_read_b128 v[160:163], v186
	ds_read_b128 v[164:167], v186 offset:1024
	ds_read_b128 v[182:185], v186 offset:2048
	ds_read_b128 v[186:189], v186 offset:3072
	s_add_u32 s38, s38, 0x4000
	s_addc_u32 s39, s39, 0
	s_mov_b32 m0, s44
	ds_read_b128 v[190:193], v180 offset:32768
	ds_read_b128 v[194:197], v180 offset:33792
	ds_read_b128 v[198:201], v180 offset:34816
	ds_read_b128 v[202:205], v180 offset:35840
	ds_read_b128 v[206:209], v180 offset:36864
	ds_read_b128 v[210:213], v180 offset:37888
	ds_read_b128 v[214:217], v180 offset:38912
	ds_read_b128 v[218:221], v180 offset:39936
	global_load_lds_dwordx4 v128, s[38:39]
	s_mov_b32 m0, s45
	s_nop 0
	global_load_lds_dwordx4 v130, s[38:39]
	s_waitcnt vmcnt(8)
	s_waitcnt lgkmcnt(0)
	s_barrier
	s_setprio 1
	s_waitcnt lgkmcnt(0)
	v_mfma_f32_16x16x32_bf16 v[124:127], v[144:147], v[190:193], v[124:127]
	v_mfma_f32_16x16x32_bf16 v[120:123], v[152:155], v[190:193], v[120:123]
	v_mfma_f32_16x16x32_bf16 v[116:119], v[144:147], v[198:201], v[116:119]
	v_mfma_f32_16x16x32_bf16 v[112:115], v[152:155], v[198:201], v[112:115]
	v_mfma_f32_16x16x32_bf16 v[92:95], v[144:147], v[206:209], v[92:95]
	v_mfma_f32_16x16x32_bf16 v[88:91], v[152:155], v[206:209], v[88:91]
	v_mfma_f32_16x16x32_bf16 v[84:87], v[144:147], v[214:217], v[84:87]
	v_mfma_f32_16x16x32_bf16 v[80:83], v[152:155], v[214:217], v[80:83]
	v_mfma_f32_16x16x32_bf16 v[124:127], v[148:151], v[194:197], v[124:127]
	v_mfma_f32_16x16x32_bf16 v[120:123], v[156:159], v[194:197], v[120:123]
	v_mfma_f32_16x16x32_bf16 v[116:119], v[148:151], v[202:205], v[116:119]
	v_mfma_f32_16x16x32_bf16 v[112:115], v[156:159], v[202:205], v[112:115]
	v_mfma_f32_16x16x32_bf16 v[92:95], v[148:151], v[210:213], v[92:95]
	v_mfma_f32_16x16x32_bf16 v[88:91], v[156:159], v[210:213], v[88:91]
	v_mfma_f32_16x16x32_bf16 v[84:87], v[148:151], v[218:221], v[84:87]
	v_mfma_f32_16x16x32_bf16 v[80:83], v[156:159], v[218:221], v[80:83]
	s_setprio 0
	s_setprio 1
	v_mfma_f32_16x16x32_bf16 v[108:111], v[160:163], v[190:193], v[108:111]
	v_mfma_f32_16x16x32_bf16 v[104:107], v[182:185], v[190:193], v[104:107]
	v_mfma_f32_16x16x32_bf16 v[100:103], v[160:163], v[198:201], v[100:103]
	v_mfma_f32_16x16x32_bf16 v[96:99], v[182:185], v[198:201], v[96:99]
	v_mfma_f32_16x16x32_bf16 v[76:79], v[160:163], v[206:209], v[76:79]
	v_mfma_f32_16x16x32_bf16 v[72:75], v[182:185], v[206:209], v[72:75]
	v_mfma_f32_16x16x32_bf16 v[68:71], v[160:163], v[214:217], v[68:71]
	v_mfma_f32_16x16x32_bf16 v[64:67], v[182:185], v[214:217], v[64:67]
	v_mfma_f32_16x16x32_bf16 v[108:111], v[164:167], v[194:197], v[108:111]
	v_mfma_f32_16x16x32_bf16 v[104:107], v[186:189], v[194:197], v[104:107]
	v_mfma_f32_16x16x32_bf16 v[100:103], v[164:167], v[202:205], v[100:103]
	v_mfma_f32_16x16x32_bf16 v[96:99], v[186:189], v[202:205], v[96:99]
	v_mfma_f32_16x16x32_bf16 v[76:79], v[164:167], v[210:213], v[76:79]
	v_mfma_f32_16x16x32_bf16 v[72:75], v[186:189], v[210:213], v[72:75]
	v_mfma_f32_16x16x32_bf16 v[68:71], v[164:167], v[218:221], v[68:71]
	v_mfma_f32_16x16x32_bf16 v[64:67], v[186:189], v[218:221], v[64:67]
	s_setprio 0
	s_barrier
	s_add_u32 s38, s36, 0x8000
	s_addc_u32 s39, s37, 0
	s_add_i32 s65, s65, s41
	s_mov_b32 m0, s65
	ds_read_b128 v[190:193], v180 offset:49152
	ds_read_b128 v[194:197], v180 offset:50176
	ds_read_b128 v[198:201], v180 offset:51200
	ds_read_b128 v[202:205], v180 offset:52224
	ds_read_b128 v[206:209], v180 offset:53248
	ds_read_b128 v[210:213], v180 offset:54272
	ds_read_b128 v[214:217], v180 offset:55296
	ds_read_b128 v[218:221], v180 offset:56320
	global_load_lds_dwordx4 v128, s[38:39]
	s_add_i32 m0, s65, 0x2000
	s_add_u32 s36, s36, 0xc000
	v_lshl_add_u64 v[222:223], s[38:39], 0, v[130:131]
	s_addc_u32 s37, s37, 0
	s_add_i32 s38, s66, s41
	global_load_lds_dwordx4 v[222:223], off
	s_mov_b32 m0, s38
	s_nop 0
	global_load_lds_dwordx4 v128, s[36:37]
	s_add_i32 m0, s38, 0x2000
	s_nop 0
	global_load_lds_dwordx4 v130, s[36:37]
	s_mov_b32 m0, s51
	s_nop 0
	global_load_lds_dwordx4 v128, s[34:35]
	s_mov_b32 m0, s52
	s_nop 0
	global_load_lds_dwordx4 v130, s[34:35]
	s_waitcnt vmcnt(8)
	s_waitcnt lgkmcnt(0)
	s_barrier
	s_setprio 1
	s_waitcnt lgkmcnt(0)
	v_mfma_f32_16x16x32_bf16 v[60:63], v[144:147], v[190:193], v[60:63]
	v_mfma_f32_16x16x32_bf16 v[56:59], v[152:155], v[190:193], v[56:59]
	v_mfma_f32_16x16x32_bf16 v[52:55], v[144:147], v[198:201], v[52:55]
	v_mfma_f32_16x16x32_bf16 v[48:51], v[152:155], v[198:201], v[48:51]
	v_mfma_f32_16x16x32_bf16 v[28:31], v[144:147], v[206:209], v[28:31]
	v_mfma_f32_16x16x32_bf16 v[24:27], v[152:155], v[206:209], v[24:27]
	v_mfma_f32_16x16x32_bf16 v[20:23], v[144:147], v[214:217], v[20:23]
	v_mfma_f32_16x16x32_bf16 v[12:15], v[152:155], v[214:217], v[12:15]
	v_mfma_f32_16x16x32_bf16 v[60:63], v[148:151], v[194:197], v[60:63]
	v_mfma_f32_16x16x32_bf16 v[56:59], v[156:159], v[194:197], v[56:59]
	v_mfma_f32_16x16x32_bf16 v[52:55], v[148:151], v[202:205], v[52:55]
	v_mfma_f32_16x16x32_bf16 v[48:51], v[156:159], v[202:205], v[48:51]
	v_mfma_f32_16x16x32_bf16 v[28:31], v[148:151], v[210:213], v[28:31]
	v_mfma_f32_16x16x32_bf16 v[24:27], v[156:159], v[210:213], v[24:27]
	v_mfma_f32_16x16x32_bf16 v[20:23], v[148:151], v[218:221], v[20:23]
	v_mfma_f32_16x16x32_bf16 v[12:15], v[156:159], v[218:221], v[12:15]
	s_setprio 0
	s_setprio 1
	v_mfma_f32_16x16x32_bf16 v[44:47], v[160:163], v[190:193], v[44:47]
	v_mfma_f32_16x16x32_bf16 v[40:43], v[182:185], v[190:193], v[40:43]
	v_mfma_f32_16x16x32_bf16 v[36:39], v[160:163], v[198:201], v[36:39]
	v_mfma_f32_16x16x32_bf16 v[32:35], v[182:185], v[198:201], v[32:35]
	v_mfma_f32_16x16x32_bf16 v[16:19], v[160:163], v[206:209], v[16:19]
	v_mfma_f32_16x16x32_bf16 v[8:11], v[182:185], v[206:209], v[8:11]
	v_mfma_f32_16x16x32_bf16 v[4:7], v[160:163], v[214:217], v[4:7]
	v_mfma_f32_16x16x32_bf16 v[0:3], v[182:185], v[214:217], v[0:3]
	v_mfma_f32_16x16x32_bf16 v[44:47], v[164:167], v[194:197], v[44:47]
	v_mfma_f32_16x16x32_bf16 v[40:43], v[186:189], v[194:197], v[40:43]
	v_mfma_f32_16x16x32_bf16 v[36:39], v[164:167], v[202:205], v[36:39]
	v_mfma_f32_16x16x32_bf16 v[32:35], v[186:189], v[202:205], v[32:35]
	v_mfma_f32_16x16x32_bf16 v[16:19], v[164:167], v[210:213], v[16:19]
	v_mfma_f32_16x16x32_bf16 v[8:11], v[186:189], v[210:213], v[8:11]
	v_mfma_f32_16x16x32_bf16 v[4:7], v[164:167], v[218:221], v[4:7]
	v_mfma_f32_16x16x32_bf16 v[0:3], v[186:189], v[218:221], v[0:3]
	s_setprio 0
	s_barrier
	s_add_i32 s64, s64, 2
	s_add_u32 s62, s62, 0x10000
	s_addc_u32 s63, s63, 0
	s_add_u32 s30, s30, 0x10000
	s_addc_u32 s31, s31, 0
	s_cmp_gt_u32 s64, 41
	s_cbranch_scc0 .LBB0_2519
	s_and_b64 vcc, exec, s[14:15]
	s_cbranch_vccz .LBB0_2522
	s_barrier
